# speedup vs baseline: 1.0098x; 1.0098x over previous
; #define STAGE_A(POFF, h, kt) STAGE_AX(POFF, h, kt, brow)
; #define STAGE_B(POFF, h, kt) STAGE_BX(POFF, h, kt, bcol)
; #define LDA(dst, b, h) _Pragma("unroll") for (int m = 0; m < 4; ++m) _Pragma("unroll") for (int k = 0; k < 2; ++k) \
;     dst[m][k] = *reinterpret_cast<const bf16x8*>((char*)SA(b, h) + lds_byte(wr * 64 + m * 16 + fr, k * 32 + fq * 8))
; #define LDB(dst, b, h) _Pragma("unroll") for (int n = 0; n < 2; ++n) _Pragma("unroll") for (int k = 0; k < 2; ++k) \
;     dst[n][k] = *reinterpret_cast<const bf16x8*>((char*)SB(b, h) + lds_byte(wc * 32 + n * 16 + fr, k * 32 + fq * 8))
; #define MMA(ai, bj, At_, Bt_) do { __builtin_amdgcn_s_setprio(1); \
;     _Pragma("unroll") for (int k = 0; k < 2; ++k) _Pragma("unroll") for (int m = 0; m < 4; ++m) _Pragma("unroll") for (int n = 0; n < 2; ++n) \
;       acc[ai][bj][m][n] = __builtin_amdgcn_mfma_f32_16x16x32_bf16(At_[m][k], Bt_[n][k], acc[ai][bj][m][n], 0, 0, 0); \
;     __builtin_amdgcn_s_setprio(0); } while (0)
; #define WAIT_V(n) asm volatile("s_waitcnt vmcnt(" #n ")" ::: "memory")
; #define BAR __builtin_amdgcn_s_barrier()
; #define SCHED __builtin_amdgcn_sched_barrier(0)
; template <int EPI, int N, int K>
; __device__ __forceinline__ void gemm_phase(const bf16_t* __restrict__ A, const bf16_t* __restrict__ Bt, const EpiArgs ea) {
;     ...
;   float* rstd_l = (float*)(shm + 131072);
;   if ((int)blockIdx.x < nwg) { int brow0, bcol0; TILE_RC((int)blockIdx.x, brow0, bcol0); ISSUE7(brow0, bcol0); }
;   for (int w = blockIdx.x; w < nwg; w += gridDim.x) {
;     int brow, bcol; TILE_RC(w, brow, bcol);
;     f32x4 acc[2][2][4][2];
; #pragma unroll
;     for (int a = 0; a < 2; ++a)
; #pragma unroll
;       for (int b = 0; b < 2; ++b)
; #pragma unroll
;         for (int m = 0; m < 4; ++m)
; #pragma unroll
;           for (int n = 0; n < 2; ++n) acc[a][b][m][n] = (f32x4){0.f, 0.f, 0.f, 0.f};
;     bf16x8 At[4][2], B0[2][2], B1[2][2];
;     if (wr == 1) BAR;
;     if (w == (int)blockIdx.x) { WAIT_V(0); } else { WAIT_V(24); }
;     BAR;
;     BAR;
;     for (int t = 0; t < nt - 2; t += 2) {
;       LDB(B0, 0, 0); SCHED; LDA(At, 0, 0); STAGE_A(SA_OFF(1, 1), 1, t + 1);
;       WAIT_L(8); BAR; WAIT_L(0); MMA(0, 0, At, B0); BAR; SCHED;
;       LDB(B1, 0, 1); STAGE_B(SB_OFF(0, 0), 0, t + 2);
.LBB0_132:
	s_and_b32 s0, s26, 7
	s_mulk_i32 s0, 0xc0
	s_ashr_i32 s1, s26, 3
	s_add_i32 s1, s0, s1
	s_mul_hi_i32 s0, s1, 0x2aaaaaab
	s_lshr_b32 s2, s0, 31
	s_ashr_i32 s0, s0, 5
	s_add_i32 s0, s0, s2
	s_mul_i32 s2, s0, 0xc0
	s_sub_i32 s27, s1, s2
	s_lshl_b32 s1, s27, 8
	s_lshl_b32 s2, s27, 5
	s_lshl_b32 s3, s27, 17
	s_and_b32 s27, s27, 7
	s_lshl_b32 s28, s0, 23
	s_lshl_b32 s27, s27, 20
	v_mov_b32_e32 v0, 0
	s_and_b32 s3, s3, 0xfff00000
	s_or_b32 s27, s28, s27
	s_mov_b32 s28, -2
	s_mov_b32 s29, 0
	v_mov_b32_e32 v1, v0
	v_mov_b32_e32 v2, v0
	v_mov_b32_e32 v3, v0
	v_mov_b32_e32 v4, v0
	v_mov_b32_e32 v5, v0
	v_mov_b32_e32 v6, v0
	v_mov_b32_e32 v7, v0
	v_mov_b32_e32 v8, v0
	v_mov_b32_e32 v9, v0
	v_mov_b32_e32 v10, v0
	v_mov_b32_e32 v11, v0
	v_mov_b32_e32 v12, v0
	v_mov_b32_e32 v13, v0
	v_mov_b32_e32 v14, v0
	v_mov_b32_e32 v15, v0
	v_mov_b32_e32 v16, v0
	v_mov_b32_e32 v17, v0
	v_mov_b32_e32 v18, v0
	v_mov_b32_e32 v19, v0
	v_mov_b32_e32 v20, v0
	v_mov_b32_e32 v21, v0
	v_mov_b32_e32 v22, v0
	v_mov_b32_e32 v23, v0
	v_mov_b32_e32 v24, v0
	v_mov_b32_e32 v25, v0
	v_mov_b32_e32 v26, v0
	v_mov_b32_e32 v27, v0
	v_mov_b32_e32 v28, v0
	v_mov_b32_e32 v29, v0
	v_mov_b32_e32 v30, v0
	v_mov_b32_e32 v31, v0
	v_mov_b32_e32 v32, v0
	v_mov_b32_e32 v33, v0
	v_mov_b32_e32 v34, v0
	v_mov_b32_e32 v35, v0
	v_mov_b32_e32 v36, v0
	v_mov_b32_e32 v37, v0
	v_mov_b32_e32 v38, v0
	v_mov_b32_e32 v39, v0
	v_mov_b32_e32 v40, v0
	v_mov_b32_e32 v41, v0
	v_mov_b32_e32 v42, v0
	v_mov_b32_e32 v43, v0
	v_mov_b32_e32 v44, v0
	v_mov_b32_e32 v45, v0
	v_mov_b32_e32 v46, v0
	v_mov_b32_e32 v47, v0
	v_mov_b32_e32 v48, v0
	v_mov_b32_e32 v49, v0
	v_mov_b32_e32 v50, v0
	v_mov_b32_e32 v51, v0
	v_mov_b32_e32 v52, v0
	v_mov_b32_e32 v53, v0
	v_mov_b32_e32 v54, v0
	v_mov_b32_e32 v55, v0
	v_mov_b32_e32 v56, v0
	v_mov_b32_e32 v57, v0
	v_mov_b32_e32 v58, v0
	v_mov_b32_e32 v59, v0
	v_mov_b32_e32 v60, v0
	v_mov_b32_e32 v61, v0
	v_mov_b32_e32 v62, v0
	v_mov_b32_e32 v63, v0
	v_mov_b32_e32 v64, v0
	v_mov_b32_e32 v65, v0
	v_mov_b32_e32 v66, v0
	v_mov_b32_e32 v67, v0
	v_mov_b32_e32 v68, v0
	v_mov_b32_e32 v69, v0
	v_mov_b32_e32 v70, v0
	v_mov_b32_e32 v71, v0
	v_mov_b32_e32 v72, v0
	v_mov_b32_e32 v73, v0
	v_mov_b32_e32 v74, v0
	v_mov_b32_e32 v75, v0
	v_mov_b32_e32 v76, v0
	v_mov_b32_e32 v77, v0
	v_mov_b32_e32 v78, v0
	v_mov_b32_e32 v79, v0
	v_mov_b32_e32 v80, v0
	v_mov_b32_e32 v81, v0
	v_mov_b32_e32 v82, v0
	v_mov_b32_e32 v83, v0
	v_mov_b32_e32 v84, v0
	v_mov_b32_e32 v85, v0
	v_mov_b32_e32 v86, v0
	v_mov_b32_e32 v87, v0
	v_mov_b32_e32 v88, v0
	v_mov_b32_e32 v89, v0
	v_mov_b32_e32 v90, v0
	v_mov_b32_e32 v91, v0
	v_mov_b32_e32 v92, v0
	v_mov_b32_e32 v93, v0
	v_mov_b32_e32 v94, v0
	v_mov_b32_e32 v95, v0
	v_mov_b32_e32 v96, v0
	v_mov_b32_e32 v97, v0
	v_mov_b32_e32 v98, v0
	v_mov_b32_e32 v99, v0
	v_mov_b32_e32 v100, v0
	v_mov_b32_e32 v101, v0
	v_mov_b32_e32 v102, v0
	v_mov_b32_e32 v103, v0
	v_mov_b32_e32 v104, v0
	v_mov_b32_e32 v105, v0
	v_mov_b32_e32 v106, v0
	v_mov_b32_e32 v107, v0
	v_mov_b32_e32 v108, v0
	v_mov_b32_e32 v109, v0
	v_mov_b32_e32 v110, v0
	v_mov_b32_e32 v111, v0
	v_mov_b32_e32 v112, v0
	v_mov_b32_e32 v113, v0
	v_mov_b32_e32 v114, v0
	v_mov_b32_e32 v115, v0
	v_mov_b32_e32 v116, v0
	v_mov_b32_e32 v117, v0
	v_mov_b32_e32 v118, v0
	v_mov_b32_e32 v119, v0
	v_mov_b32_e32 v120, v0
	v_mov_b32_e32 v121, v0
	v_mov_b32_e32 v122, v0
	v_mov_b32_e32 v123, v0
	v_mov_b32_e32 v124, v0
	v_mov_b32_e32 v125, v0
	v_mov_b32_e32 v126, v0
	v_mov_b32_e32 v127, v0
	s_barrier
	s_barrier
	ds_read_b128 v[154:157], v145
	ds_read_b128 v[158:161], v145 offset:1024
	ds_read_b128 v[162:165], v145 offset:2048
	ds_read_b128 v[166:169], v145 offset:3072
.LBB0_133:
	ds_read_b128 v[170:173], v146
	ds_read_b128 v[174:177], v146 offset:1024
	ds_read_b128 v[178:181], v147
	ds_read_b128 v[182:185], v147 offset:1024
	ds_read_b128 v[186:189], v148
	ds_read_b128 v[190:193], v148 offset:1024
	ds_read_b128 v[194:197], v149
	ds_read_b128 v[198:201], v149 offset:1024
	s_add_i32 s30, s27, s29
	s_or_b32 s31, s30, 0x80080
	s_mov_b32 m0, s24
	s_nop 0
	buffer_load_dwordx4 v131, s[48:51], s31 offen lds
	s_or_b32 s31, s30, 0xc0080
	s_mov_b32 m0, s25
	s_nop 0
	buffer_load_dwordx4 v131, s[48:51], s31 offen lds
	s_waitcnt lgkmcnt(8)
	s_barrier
	s_waitcnt lgkmcnt(0)
	s_setprio 1
	v_mfma_f32_16x16x32_bf16 v[124:127], v[170:173], v[154:157], v[124:127]
	v_mfma_f32_16x16x32_bf16 v[120:123], v[170:173], v[162:165], v[120:123]
	v_mfma_f32_16x16x32_bf16 v[116:119], v[178:181], v[154:157], v[116:119]
	v_mfma_f32_16x16x32_bf16 v[112:115], v[178:181], v[162:165], v[112:115]
	v_mfma_f32_16x16x32_bf16 v[108:111], v[186:189], v[154:157], v[108:111]
	v_mfma_f32_16x16x32_bf16 v[104:107], v[186:189], v[162:165], v[104:107]
	v_mfma_f32_16x16x32_bf16 v[100:103], v[194:197], v[154:157], v[100:103]
	v_mfma_f32_16x16x32_bf16 v[96:99], v[194:197], v[162:165], v[96:99]
	v_mfma_f32_16x16x32_bf16 v[124:127], v[174:177], v[158:161], v[124:127]
	v_mfma_f32_16x16x32_bf16 v[120:123], v[174:177], v[166:169], v[120:123]
	v_mfma_f32_16x16x32_bf16 v[116:119], v[182:185], v[158:161], v[116:119]
	v_mfma_f32_16x16x32_bf16 v[112:115], v[182:185], v[166:169], v[112:115]
	v_mfma_f32_16x16x32_bf16 v[108:111], v[190:193], v[158:161], v[108:111]
	v_mfma_f32_16x16x32_bf16 v[104:107], v[190:193], v[166:169], v[104:107]
	v_mfma_f32_16x16x32_bf16 v[100:103], v[198:201], v[158:161], v[100:103]
	v_mfma_f32_16x16x32_bf16 v[96:99], v[198:201], v[166:169], v[96:99]
	s_setprio 0
	s_barrier
	ds_read_b128 v[202:205], v150
	ds_read_b128 v[206:209], v150 offset:1024
	ds_read_b128 v[210:213], v150 offset:2048
	ds_read_b128 v[214:217], v150 offset:3072
	s_add_i32 s31, s3, s29
	s_add_i32 s34, s31, 0x100
	s_mov_b32 m0, s11
	s_nop 0
	buffer_load_dwordx4 v134, s[72:75], s34 offen lds
	s_add_i32 s34, s31, 0x80100
	s_mov_b32 m0, s12
	s_nop 0
	buffer_load_dwordx4 v134, s[72:75], s34 offen lds
	s_barrier
; #define STAGE_A(POFF, h, kt) STAGE_AX(POFF, h, kt, brow)
; #define STAGE_B(POFF, h, kt) STAGE_BX(POFF, h, kt, bcol)
; #define LDA(dst, b, h) _Pragma("unroll") for (int m = 0; m < 4; ++m) _Pragma("unroll") for (int k = 0; k < 2; ++k) \
;     dst[m][k] = *reinterpret_cast<const bf16x8*>((char*)SA(b, h) + lds_byte(wr * 64 + m * 16 + fr, k * 32 + fq * 8))
; #define LDB(dst, b, h) _Pragma("unroll") for (int n = 0; n < 2; ++n) _Pragma("unroll") for (int k = 0; k < 2; ++k) \
;     dst[n][k] = *reinterpret_cast<const bf16x8*>((char*)SB(b, h) + lds_byte(wc * 32 + n * 16 + fr, k * 32 + fq * 8))
; #define MMA(ai, bj, At_, Bt_) do { __builtin_amdgcn_s_setprio(1); \
;     _Pragma("unroll") for (int k = 0; k < 2; ++k) _Pragma("unroll") for (int m = 0; m < 4; ++m) _Pragma("unroll") for (int n = 0; n < 2; ++n) \
;       acc[ai][bj][m][n] = __builtin_amdgcn_mfma_f32_16x16x32_bf16(At_[m][k], Bt_[n][k], acc[ai][bj][m][n], 0, 0, 0); \
;     __builtin_amdgcn_s_setprio(0); } while (0)
; #define WAIT_V(n) asm volatile("s_waitcnt vmcnt(" #n ")" ::: "memory")
; #define BAR __builtin_amdgcn_s_barrier()
; #define SCHED __builtin_amdgcn_sched_barrier(0)
; template <int EPI, int N, int K>
; __device__ __forceinline__ void gemm_phase(const bf16_t* __restrict__ A, const bf16_t* __restrict__ Bt, const EpiArgs ea) {
;     ...
;       BAR; WAIT_L(0); MMA(0, 1, At, B1); BAR;
;       LDA(At, 0, 1); STAGE_A(SA_OFF(0, 0), 0, t + 2);
;       BAR; WAIT_L(0); MMA(1, 0, At, B0); BAR; SCHED;
;       STAGE_B(SB_OFF(0, 1), 1, t + 2);
;       WAIT_V(6); BAR; MMA(1, 1, At, B1); BAR;
;       LDB(B0, 1, 0); SCHED; LDA(At, 1, 0); STAGE_A(SA_OFF(0, 1), 1, t + 2);
;       WAIT_L(8); BAR; WAIT_L(0); MMA(0, 0, At, B0); BAR; SCHED;
	s_waitcnt lgkmcnt(0)
	s_setprio 1
	v_mfma_f32_16x16x32_bf16 v[92:95], v[170:173], v[202:205], v[92:95]
	v_mfma_f32_16x16x32_bf16 v[88:91], v[170:173], v[210:213], v[88:91]
	v_mfma_f32_16x16x32_bf16 v[84:87], v[178:181], v[202:205], v[84:87]
	v_mfma_f32_16x16x32_bf16 v[80:83], v[178:181], v[210:213], v[80:83]
	v_mfma_f32_16x16x32_bf16 v[76:79], v[186:189], v[202:205], v[76:79]
	v_mfma_f32_16x16x32_bf16 v[72:75], v[186:189], v[210:213], v[72:75]
	v_mfma_f32_16x16x32_bf16 v[68:71], v[194:197], v[202:205], v[68:71]
	v_mfma_f32_16x16x32_bf16 v[64:67], v[194:197], v[210:213], v[64:67]
	v_mfma_f32_16x16x32_bf16 v[92:95], v[174:177], v[206:209], v[92:95]
	v_mfma_f32_16x16x32_bf16 v[88:91], v[174:177], v[214:217], v[88:91]
	v_mfma_f32_16x16x32_bf16 v[84:87], v[182:185], v[206:209], v[84:87]
	v_mfma_f32_16x16x32_bf16 v[80:83], v[182:185], v[214:217], v[80:83]
	v_mfma_f32_16x16x32_bf16 v[76:79], v[190:193], v[206:209], v[76:79]
	v_mfma_f32_16x16x32_bf16 v[72:75], v[190:193], v[214:217], v[72:75]
	v_mfma_f32_16x16x32_bf16 v[68:71], v[198:201], v[206:209], v[68:71]
	v_mfma_f32_16x16x32_bf16 v[64:67], v[198:201], v[214:217], v[64:67]
	s_setprio 0
	s_barrier
	ds_read_b128 v[170:173], v146 offset:16384
	ds_read_b128 v[174:177], v146 offset:17408
	ds_read_b128 v[178:181], v147 offset:16384
	ds_read_b128 v[182:185], v147 offset:17408
	ds_read_b128 v[186:189], v148 offset:16384
	ds_read_b128 v[190:193], v148 offset:17408
	ds_read_b128 v[194:197], v149 offset:16384
	ds_read_b128 v[198:201], v149 offset:17408
	s_add_i32 s34, s30, 0x100
	s_mov_b32 m0, s10
	s_nop 0
	buffer_load_dwordx4 v131, s[48:51], s34 offen lds
	s_add_i32 s35, s30, 0x40100
	s_mov_b32 m0, s13
	s_nop 0
	buffer_load_dwordx4 v131, s[48:51], s35 offen lds
	s_waitcnt vmcnt(10)
	s_barrier
	s_waitcnt lgkmcnt(0)
	s_setprio 1
	v_mfma_f32_16x16x32_bf16 v[60:63], v[170:173], v[154:157], v[60:63]
	v_mfma_f32_16x16x32_bf16 v[56:59], v[170:173], v[162:165], v[56:59]
	v_mfma_f32_16x16x32_bf16 v[52:55], v[178:181], v[154:157], v[52:55]
	v_mfma_f32_16x16x32_bf16 v[48:51], v[178:181], v[162:165], v[48:51]
	v_mfma_f32_16x16x32_bf16 v[44:47], v[186:189], v[154:157], v[44:47]
	v_mfma_f32_16x16x32_bf16 v[40:43], v[186:189], v[162:165], v[40:43]
	v_mfma_f32_16x16x32_bf16 v[36:39], v[194:197], v[154:157], v[36:39]
	v_mfma_f32_16x16x32_bf16 v[32:35], v[194:197], v[162:165], v[32:35]
	v_mfma_f32_16x16x32_bf16 v[60:63], v[174:177], v[158:161], v[60:63]
	v_mfma_f32_16x16x32_bf16 v[56:59], v[174:177], v[166:169], v[56:59]
	v_mfma_f32_16x16x32_bf16 v[52:55], v[182:185], v[158:161], v[52:55]
	v_mfma_f32_16x16x32_bf16 v[48:51], v[182:185], v[166:169], v[48:51]
	v_mfma_f32_16x16x32_bf16 v[44:47], v[190:193], v[158:161], v[44:47]
	v_mfma_f32_16x16x32_bf16 v[40:43], v[190:193], v[166:169], v[40:43]
	v_mfma_f32_16x16x32_bf16 v[36:39], v[198:201], v[158:161], v[36:39]
	v_mfma_f32_16x16x32_bf16 v[32:35], v[198:201], v[166:169], v[32:35]
	s_setprio 0
	s_barrier
	ds_read_b128 v[154:157], v151
	ds_read_b128 v[158:161], v151 offset:1024
	ds_read_b128 v[162:165], v151 offset:2048
	ds_read_b128 v[166:169], v151 offset:3072
	s_add_i32 s35, s31, 0x2100
	s_mov_b32 m0, s14
	s_nop 0
	buffer_load_dwordx4 v134, s[72:75], s35 offen lds
	s_add_i32 s35, s31, 0x82100
	s_mov_b32 m0, s15
	s_nop 0
	buffer_load_dwordx4 v134, s[72:75], s35 offen lds
	s_waitcnt vmcnt(6)
	s_barrier
	s_setprio 1
	v_mfma_f32_16x16x32_bf16 v[28:31], v[170:173], v[202:205], v[28:31]
	v_mfma_f32_16x16x32_bf16 v[24:27], v[170:173], v[210:213], v[24:27]
	v_mfma_f32_16x16x32_bf16 v[20:23], v[178:181], v[202:205], v[20:23]
	v_mfma_f32_16x16x32_bf16 v[16:19], v[178:181], v[210:213], v[16:19]
	v_mfma_f32_16x16x32_bf16 v[12:15], v[186:189], v[202:205], v[12:15]
	v_mfma_f32_16x16x32_bf16 v[8:11], v[186:189], v[210:213], v[8:11]
	v_mfma_f32_16x16x32_bf16 v[4:7], v[194:197], v[202:205], v[4:7]
	v_mfma_f32_16x16x32_bf16 v[0:3], v[194:197], v[210:213], v[0:3]
	v_mfma_f32_16x16x32_bf16 v[28:31], v[174:177], v[206:209], v[28:31]
	v_mfma_f32_16x16x32_bf16 v[24:27], v[174:177], v[214:217], v[24:27]
	v_mfma_f32_16x16x32_bf16 v[20:23], v[182:185], v[206:209], v[20:23]
	v_mfma_f32_16x16x32_bf16 v[16:19], v[182:185], v[214:217], v[16:19]
	v_mfma_f32_16x16x32_bf16 v[12:15], v[190:193], v[206:209], v[12:15]
	v_mfma_f32_16x16x32_bf16 v[8:11], v[190:193], v[214:217], v[8:11]
	v_mfma_f32_16x16x32_bf16 v[4:7], v[198:201], v[206:209], v[4:7]
	v_mfma_f32_16x16x32_bf16 v[0:3], v[198:201], v[214:217], v[0:3]
	s_setprio 0
	s_barrier
	ds_read_b128 v[170:173], v146 offset:32768
	ds_read_b128 v[174:177], v146 offset:33792
	ds_read_b128 v[178:181], v147 offset:32768
	ds_read_b128 v[182:185], v147 offset:33792
	ds_read_b128 v[186:189], v148 offset:32768
	ds_read_b128 v[190:193], v148 offset:33792
	ds_read_b128 v[194:197], v149 offset:32768
	ds_read_b128 v[198:201], v149 offset:33792
	s_or_b32 s35, s34, 0x80000
	s_mov_b32 m0, s16
	s_nop 0
	buffer_load_dwordx4 v131, s[48:51], s35 offen lds
	s_or_b32 s34, s34, 0xc0000
	s_mov_b32 m0, s17
	s_nop 0
	buffer_load_dwordx4 v131, s[48:51], s34 offen lds
	s_waitcnt lgkmcnt(8)
	s_barrier
; #define STAGE_A(POFF, h, kt) STAGE_AX(POFF, h, kt, brow)
; #define STAGE_B(POFF, h, kt) STAGE_BX(POFF, h, kt, bcol)
; #define LDA(dst, b, h) _Pragma("unroll") for (int m = 0; m < 4; ++m) _Pragma("unroll") for (int k = 0; k < 2; ++k) \
;     dst[m][k] = *reinterpret_cast<const bf16x8*>((char*)SA(b, h) + lds_byte(wr * 64 + m * 16 + fr, k * 32 + fq * 8))
; #define LDB(dst, b, h) _Pragma("unroll") for (int n = 0; n < 2; ++n) _Pragma("unroll") for (int k = 0; k < 2; ++k) \
;     dst[n][k] = *reinterpret_cast<const bf16x8*>((char*)SB(b, h) + lds_byte(wc * 32 + n * 16 + fr, k * 32 + fq * 8))
; #define MMA(ai, bj, At_, Bt_) do { __builtin_amdgcn_s_setprio(1); \
;     _Pragma("unroll") for (int k = 0; k < 2; ++k) _Pragma("unroll") for (int m = 0; m < 4; ++m) _Pragma("unroll") for (int n = 0; n < 2; ++n) \
;       acc[ai][bj][m][n] = __builtin_amdgcn_mfma_f32_16x16x32_bf16(At_[m][k], Bt_[n][k], acc[ai][bj][m][n], 0, 0, 0); \
;     __builtin_amdgcn_s_setprio(0); } while (0)
; #define WAIT_V(n) asm volatile("s_waitcnt vmcnt(" #n ")" ::: "memory")
; #define BAR __builtin_amdgcn_s_barrier()
; #define SCHED __builtin_amdgcn_sched_barrier(0)
; template <int EPI, int N, int K>
; __device__ __forceinline__ void gemm_phase(const bf16_t* __restrict__ A, const bf16_t* __restrict__ Bt, const EpiArgs ea) {
;     ...
;       WAIT_L(8); BAR; WAIT_L(0); MMA(0, 0, At, B0); BAR; SCHED;
;       LDB(B1, 1, 1); STAGE_B(SB_OFF(1, 0), 0, t + 3);
;       BAR; WAIT_L(0); MMA(0, 1, At, B1); BAR;
;       LDA(At, 1, 1); STAGE_A(SA_OFF(1, 0), 0, t + 3);
;       BAR; WAIT_L(0); MMA(1, 0, At, B0); BAR; SCHED;
;       STAGE_B(SB_OFF(1, 1), 1, t + 3);
;       WAIT_V(6); BAR; MMA(1, 1, At, B1); BAR;
	s_waitcnt lgkmcnt(0)
	s_setprio 1
	v_mfma_f32_16x16x32_bf16 v[124:127], v[170:173], v[154:157], v[124:127]
	v_mfma_f32_16x16x32_bf16 v[120:123], v[170:173], v[162:165], v[120:123]
	v_mfma_f32_16x16x32_bf16 v[116:119], v[178:181], v[154:157], v[116:119]
	v_mfma_f32_16x16x32_bf16 v[112:115], v[178:181], v[162:165], v[112:115]
	v_mfma_f32_16x16x32_bf16 v[108:111], v[186:189], v[154:157], v[108:111]
	v_mfma_f32_16x16x32_bf16 v[104:107], v[186:189], v[162:165], v[104:107]
	v_mfma_f32_16x16x32_bf16 v[100:103], v[194:197], v[154:157], v[100:103]
	v_mfma_f32_16x16x32_bf16 v[96:99], v[194:197], v[162:165], v[96:99]
	v_mfma_f32_16x16x32_bf16 v[124:127], v[174:177], v[158:161], v[124:127]
	v_mfma_f32_16x16x32_bf16 v[120:123], v[174:177], v[166:169], v[120:123]
	v_mfma_f32_16x16x32_bf16 v[116:119], v[182:185], v[158:161], v[116:119]
	v_mfma_f32_16x16x32_bf16 v[112:115], v[182:185], v[166:169], v[112:115]
	v_mfma_f32_16x16x32_bf16 v[108:111], v[190:193], v[158:161], v[108:111]
	v_mfma_f32_16x16x32_bf16 v[104:107], v[190:193], v[166:169], v[104:107]
	v_mfma_f32_16x16x32_bf16 v[100:103], v[198:201], v[158:161], v[100:103]
	v_mfma_f32_16x16x32_bf16 v[96:99], v[198:201], v[166:169], v[96:99]
	s_setprio 0
	s_barrier
	ds_read_b128 v[202:205], v152
	ds_read_b128 v[206:209], v152 offset:1024
	ds_read_b128 v[210:213], v152 offset:2048
	ds_read_b128 v[214:217], v152 offset:3072
	s_add_i32 s34, s31, 0x180
	s_mov_b32 m0, s18
	s_nop 0
	buffer_load_dwordx4 v134, s[72:75], s34 offen lds
	s_add_i32 s34, s31, 0x80180
	s_mov_b32 m0, s19
	s_nop 0
	buffer_load_dwordx4 v134, s[72:75], s34 offen lds
	s_barrier
	s_waitcnt lgkmcnt(0)
	s_setprio 1
	v_mfma_f32_16x16x32_bf16 v[92:95], v[170:173], v[202:205], v[92:95]
	v_mfma_f32_16x16x32_bf16 v[88:91], v[170:173], v[210:213], v[88:91]
	v_mfma_f32_16x16x32_bf16 v[84:87], v[178:181], v[202:205], v[84:87]
	v_mfma_f32_16x16x32_bf16 v[80:83], v[178:181], v[210:213], v[80:83]
	v_mfma_f32_16x16x32_bf16 v[76:79], v[186:189], v[202:205], v[76:79]
	v_mfma_f32_16x16x32_bf16 v[72:75], v[186:189], v[210:213], v[72:75]
	v_mfma_f32_16x16x32_bf16 v[68:71], v[194:197], v[202:205], v[68:71]
	v_mfma_f32_16x16x32_bf16 v[64:67], v[194:197], v[210:213], v[64:67]
	v_mfma_f32_16x16x32_bf16 v[92:95], v[174:177], v[206:209], v[92:95]
	v_mfma_f32_16x16x32_bf16 v[88:91], v[174:177], v[214:217], v[88:91]
	v_mfma_f32_16x16x32_bf16 v[84:87], v[182:185], v[206:209], v[84:87]
	v_mfma_f32_16x16x32_bf16 v[80:83], v[182:185], v[214:217], v[80:83]
	v_mfma_f32_16x16x32_bf16 v[76:79], v[190:193], v[206:209], v[76:79]
	v_mfma_f32_16x16x32_bf16 v[72:75], v[190:193], v[214:217], v[72:75]
	v_mfma_f32_16x16x32_bf16 v[68:71], v[198:201], v[206:209], v[68:71]
	v_mfma_f32_16x16x32_bf16 v[64:67], v[198:201], v[214:217], v[64:67]
	s_setprio 0
	s_barrier
	ds_read_b128 v[170:173], v146 offset:49152
	ds_read_b128 v[174:177], v146 offset:50176
	ds_read_b128 v[178:181], v147 offset:49152
	ds_read_b128 v[182:185], v147 offset:50176
	ds_read_b128 v[186:189], v148 offset:49152
	ds_read_b128 v[190:193], v148 offset:50176
	ds_read_b128 v[194:197], v149 offset:49152
	ds_read_b128 v[198:201], v149 offset:50176
	s_add_i32 s34, s30, 0x180
	s_mov_b32 m0, s20
	s_nop 0
	buffer_load_dwordx4 v131, s[48:51], s34 offen lds
	s_add_i32 s30, s30, 0x40180
	s_mov_b32 m0, s21
	s_nop 0
	buffer_load_dwordx4 v131, s[48:51], s30 offen lds
	s_waitcnt vmcnt(10)
	s_barrier
	s_waitcnt lgkmcnt(0)
	s_setprio 1
	v_mfma_f32_16x16x32_bf16 v[60:63], v[170:173], v[154:157], v[60:63]
	v_mfma_f32_16x16x32_bf16 v[56:59], v[170:173], v[162:165], v[56:59]
	v_mfma_f32_16x16x32_bf16 v[52:55], v[178:181], v[154:157], v[52:55]
	v_mfma_f32_16x16x32_bf16 v[48:51], v[178:181], v[162:165], v[48:51]
	v_mfma_f32_16x16x32_bf16 v[44:47], v[186:189], v[154:157], v[44:47]
	v_mfma_f32_16x16x32_bf16 v[40:43], v[186:189], v[162:165], v[40:43]
	v_mfma_f32_16x16x32_bf16 v[36:39], v[194:197], v[154:157], v[36:39]
	v_mfma_f32_16x16x32_bf16 v[32:35], v[194:197], v[162:165], v[32:35]
	v_mfma_f32_16x16x32_bf16 v[60:63], v[174:177], v[158:161], v[60:63]
	v_mfma_f32_16x16x32_bf16 v[56:59], v[174:177], v[166:169], v[56:59]
	v_mfma_f32_16x16x32_bf16 v[52:55], v[182:185], v[158:161], v[52:55]
	v_mfma_f32_16x16x32_bf16 v[48:51], v[182:185], v[166:169], v[48:51]
	v_mfma_f32_16x16x32_bf16 v[44:47], v[190:193], v[158:161], v[44:47]
	v_mfma_f32_16x16x32_bf16 v[40:43], v[190:193], v[166:169], v[40:43]
	v_mfma_f32_16x16x32_bf16 v[36:39], v[198:201], v[158:161], v[36:39]
	v_mfma_f32_16x16x32_bf16 v[32:35], v[198:201], v[166:169], v[32:35]
	s_setprio 0
	s_barrier
	ds_read_b128 v[154:157], v145
	ds_read_b128 v[158:161], v145 offset:1024
	ds_read_b128 v[162:165], v145 offset:2048
	ds_read_b128 v[166:169], v145 offset:3072
	s_add_i32 s30, s31, 0x2180
	s_mov_b32 m0, s22
	s_nop 0
	buffer_load_dwordx4 v134, s[72:75], s30 offen lds
	s_add_i32 s31, s31, 0x82180
	s_mov_b32 m0, s23
	s_nop 0
	buffer_load_dwordx4 v134, s[72:75], s31 offen lds
	s_waitcnt vmcnt(6)
	s_barrier
	s_setprio 1
	v_mfma_f32_16x16x32_bf16 v[28:31], v[170:173], v[202:205], v[28:31]
	v_mfma_f32_16x16x32_bf16 v[24:27], v[170:173], v[210:213], v[24:27]
	v_mfma_f32_16x16x32_bf16 v[20:23], v[178:181], v[202:205], v[20:23]
	v_mfma_f32_16x16x32_bf16 v[16:19], v[178:181], v[210:213], v[16:19]
	v_mfma_f32_16x16x32_bf16 v[12:15], v[186:189], v[202:205], v[12:15]
	v_mfma_f32_16x16x32_bf16 v[8:11], v[186:189], v[210:213], v[8:11]
	v_mfma_f32_16x16x32_bf16 v[4:7], v[194:197], v[202:205], v[4:7]
	v_mfma_f32_16x16x32_bf16 v[0:3], v[194:197], v[210:213], v[0:3]
	v_mfma_f32_16x16x32_bf16 v[28:31], v[174:177], v[206:209], v[28:31]
	v_mfma_f32_16x16x32_bf16 v[24:27], v[174:177], v[214:217], v[24:27]
	v_mfma_f32_16x16x32_bf16 v[20:23], v[182:185], v[206:209], v[20:23]
	v_mfma_f32_16x16x32_bf16 v[16:19], v[182:185], v[214:217], v[16:19]
	v_mfma_f32_16x16x32_bf16 v[12:15], v[190:193], v[206:209], v[12:15]
	v_mfma_f32_16x16x32_bf16 v[8:11], v[190:193], v[214:217], v[8:11]
	v_mfma_f32_16x16x32_bf16 v[4:7], v[198:201], v[206:209], v[4:7]
	v_mfma_f32_16x16x32_bf16 v[0:3], v[198:201], v[214:217], v[0:3]
	s_setprio 0
	s_add_i32 s28, s28, 2
	s_addk_i32 s29, 0x100
	s_cmp_lt_u32 s28, 28
	s_barrier
; #define STAGE_A(POFF, h, kt) STAGE_AX(POFF, h, kt, brow)
; #define LDA(dst, b, h) _Pragma("unroll") for (int m = 0; m < 4; ++m) _Pragma("unroll") for (int k = 0; k < 2; ++k) \
;     dst[m][k] = *reinterpret_cast<const bf16x8*>((char*)SA(b, h) + lds_byte(wr * 64 + m * 16 + fr, k * 32 + fq * 8))
; #define LDB(dst, b, h) _Pragma("unroll") for (int n = 0; n < 2; ++n) _Pragma("unroll") for (int k = 0; k < 2; ++k) \
;     dst[n][k] = *reinterpret_cast<const bf16x8*>((char*)SB(b, h) + lds_byte(wc * 32 + n * 16 + fr, k * 32 + fq * 8))
; #define MMA(ai, bj, At_, Bt_) do { __builtin_amdgcn_s_setprio(1); \
;     _Pragma("unroll") for (int k = 0; k < 2; ++k) _Pragma("unroll") for (int m = 0; m < 4; ++m) _Pragma("unroll") for (int n = 0; n < 2; ++n) \
;       acc[ai][bj][m][n] = __builtin_amdgcn_mfma_f32_16x16x32_bf16(At_[m][k], Bt_[n][k], acc[ai][bj][m][n], 0, 0, 0); \
;     __builtin_amdgcn_s_setprio(0); } while (0)
; #define WAIT_V(n) asm volatile("s_waitcnt vmcnt(" #n ")" ::: "memory")
; #define BAR __builtin_amdgcn_s_barrier()
; template <int EPI, int N, int K>
; __device__ __forceinline__ void gemm_phase(const bf16_t* __restrict__ A, const bf16_t* __restrict__ Bt, const EpiArgs ea) {
;     ...
;     { LDB(B0, 0, 0); LDA(At, 0, 0); STAGE_A(SA_OFF(1, 1), 1, nt - 1);
;       BAR; WAIT_L(0); MMA(0, 0, At, B0); BAR;
;       LDB(B1, 0, 1); BAR; WAIT_L(0); MMA(0, 1, At, B1); BAR;
;       LDA(At, 0, 1); WAIT_V(4); BAR; WAIT_L(0); MMA(1, 0, At, B0); MMA(1, 1, At, B1); BAR; }
;     { LDB(B0, 1, 0); LDA(At, 1, 0); WAIT_V(2); BAR; WAIT_L(0); MMA(0, 0, At, B0); BAR;
	s_cbranch_scc1 .LBB0_133
	ds_read_b128 v[170:173], v146
	ds_read_b128 v[174:177], v146 offset:1024
	ds_read_b128 v[178:181], v147
	ds_read_b128 v[182:185], v147 offset:1024
	ds_read_b128 v[186:189], v148
	ds_read_b128 v[190:193], v148 offset:1024
	ds_read_b128 v[194:197], v149
	ds_read_b128 v[198:201], v149 offset:1024
	s_and_b32 s1, s1, 0x700
	s_lshl_b32 s0, s0, 11
	s_or_b32 s27, s1, s0
	s_lshl_b32 s0, s27, 12
	s_or_b32 s1, s0, 0x80f80
	s_mov_b32 m0, s24
	s_nop 0
	buffer_load_dwordx4 v131, s[48:51], s1 offen lds
	s_or_b32 s0, s0, 0xc0f80
	s_mov_b32 m0, s25
	s_nop 0
	buffer_load_dwordx4 v131, s[48:51], s0 offen lds
	s_barrier
	s_waitcnt lgkmcnt(0)
	s_setprio 1
	v_mfma_f32_16x16x32_bf16 v[124:127], v[170:173], v[154:157], v[124:127]
	v_mfma_f32_16x16x32_bf16 v[120:123], v[170:173], v[162:165], v[120:123]
	v_mfma_f32_16x16x32_bf16 v[116:119], v[178:181], v[154:157], v[116:119]
	v_mfma_f32_16x16x32_bf16 v[112:115], v[178:181], v[162:165], v[112:115]
	v_mfma_f32_16x16x32_bf16 v[108:111], v[186:189], v[154:157], v[108:111]
	v_mfma_f32_16x16x32_bf16 v[104:107], v[186:189], v[162:165], v[104:107]
	v_mfma_f32_16x16x32_bf16 v[100:103], v[194:197], v[154:157], v[100:103]
	v_mfma_f32_16x16x32_bf16 v[96:99], v[194:197], v[162:165], v[96:99]
	v_mfma_f32_16x16x32_bf16 v[124:127], v[174:177], v[158:161], v[124:127]
	v_mfma_f32_16x16x32_bf16 v[120:123], v[174:177], v[166:169], v[120:123]
	v_mfma_f32_16x16x32_bf16 v[116:119], v[182:185], v[158:161], v[116:119]
	v_mfma_f32_16x16x32_bf16 v[112:115], v[182:185], v[166:169], v[112:115]
	v_mfma_f32_16x16x32_bf16 v[108:111], v[190:193], v[158:161], v[108:111]
	v_mfma_f32_16x16x32_bf16 v[104:107], v[190:193], v[166:169], v[104:107]
	v_mfma_f32_16x16x32_bf16 v[100:103], v[198:201], v[158:161], v[100:103]
	v_mfma_f32_16x16x32_bf16 v[96:99], v[198:201], v[166:169], v[96:99]
	s_setprio 0
	s_barrier
	ds_read_b128 v[202:205], v150
	ds_read_b128 v[206:209], v150 offset:1024
	ds_read_b128 v[210:213], v150 offset:2048
	ds_read_b128 v[214:217], v150 offset:3072
	s_barrier
	s_waitcnt lgkmcnt(0)
	s_setprio 1
	v_mfma_f32_16x16x32_bf16 v[92:95], v[170:173], v[202:205], v[92:95]
	v_mfma_f32_16x16x32_bf16 v[88:91], v[170:173], v[210:213], v[88:91]
	v_mfma_f32_16x16x32_bf16 v[76:79], v[186:189], v[202:205], v[76:79]
	v_mfma_f32_16x16x32_bf16 v[72:75], v[186:189], v[210:213], v[72:75]
	v_mfma_f32_16x16x32_bf16 v[68:71], v[194:197], v[202:205], v[68:71]
	v_mfma_f32_16x16x32_bf16 v[64:67], v[194:197], v[210:213], v[64:67]
	v_mfma_f32_16x16x32_bf16 v[84:87], v[178:181], v[202:205], v[84:87]
	v_mfma_f32_16x16x32_bf16 v[80:83], v[178:181], v[210:213], v[80:83]
	v_mfma_f32_16x16x32_bf16 v[92:95], v[174:177], v[206:209], v[92:95]
	v_mfma_f32_16x16x32_bf16 v[88:91], v[174:177], v[214:217], v[88:91]
	v_mfma_f32_16x16x32_bf16 v[76:79], v[190:193], v[206:209], v[76:79]
	v_mfma_f32_16x16x32_bf16 v[72:75], v[190:193], v[214:217], v[72:75]
	v_mfma_f32_16x16x32_bf16 v[68:71], v[198:201], v[206:209], v[68:71]
	v_mfma_f32_16x16x32_bf16 v[64:67], v[198:201], v[214:217], v[64:67]
	v_mfma_f32_16x16x32_bf16 v[170:173], v[182:185], v[206:209], v[84:87]
	v_mfma_f32_16x16x32_bf16 v[174:177], v[182:185], v[214:217], v[80:83]
	s_setprio 0
	s_barrier
	s_nop 0
	ds_read_b128 v[80:83], v146 offset:16384
	ds_read_b128 v[84:87], v146 offset:17408
	ds_read_b128 v[178:181], v147 offset:16384
	ds_read_b128 v[182:185], v147 offset:17408
	ds_read_b128 v[186:189], v148 offset:16384
	ds_read_b128 v[190:193], v148 offset:17408
	ds_read_b128 v[194:197], v149 offset:16384
	ds_read_b128 v[198:201], v149 offset:17408
	s_waitcnt vmcnt(4)
	s_barrier
	s_waitcnt lgkmcnt(0)
	s_setprio 1
	v_mfma_f32_16x16x32_bf16 v[52:55], v[178:181], v[154:157], v[52:55]
	v_mfma_f32_16x16x32_bf16 v[48:51], v[178:181], v[162:165], v[48:51]
	v_mfma_f32_16x16x32_bf16 v[44:47], v[186:189], v[154:157], v[44:47]
	v_mfma_f32_16x16x32_bf16 v[40:43], v[186:189], v[162:165], v[40:43]
	v_mfma_f32_16x16x32_bf16 v[36:39], v[194:197], v[154:157], v[36:39]
	v_mfma_f32_16x16x32_bf16 v[32:35], v[194:197], v[162:165], v[32:35]
	v_mfma_f32_16x16x32_bf16 v[60:63], v[80:83], v[154:157], v[60:63]
	v_mfma_f32_16x16x32_bf16 v[56:59], v[80:83], v[162:165], v[56:59]
	v_mfma_f32_16x16x32_bf16 v[52:55], v[182:185], v[158:161], v[52:55]
	v_mfma_f32_16x16x32_bf16 v[48:51], v[182:185], v[166:169], v[48:51]
	v_mfma_f32_16x16x32_bf16 v[44:47], v[190:193], v[158:161], v[44:47]
	v_mfma_f32_16x16x32_bf16 v[40:43], v[190:193], v[166:169], v[40:43]
	v_mfma_f32_16x16x32_bf16 v[36:39], v[198:201], v[158:161], v[36:39]
	v_mfma_f32_16x16x32_bf16 v[32:35], v[198:201], v[166:169], v[32:35]
	v_mfma_f32_16x16x32_bf16 v[154:157], v[84:87], v[158:161], v[60:63]
	v_mfma_f32_16x16x32_bf16 v[162:165], v[84:87], v[166:169], v[56:59]
	s_setprio 0
	s_setprio 1
	v_mfma_f32_16x16x32_bf16 v[28:31], v[80:83], v[202:205], v[28:31]
	v_mfma_f32_16x16x32_bf16 v[24:27], v[80:83], v[210:213], v[24:27]
	v_mfma_f32_16x16x32_bf16 v[12:15], v[186:189], v[202:205], v[12:15]
	v_mfma_f32_16x16x32_bf16 v[8:11], v[186:189], v[210:213], v[8:11]
	v_mfma_f32_16x16x32_bf16 v[20:23], v[178:181], v[202:205], v[20:23]
	v_mfma_f32_16x16x32_bf16 v[16:19], v[178:181], v[210:213], v[16:19]
	v_mfma_f32_16x16x32_bf16 v[4:7], v[194:197], v[202:205], v[4:7]
	v_mfma_f32_16x16x32_bf16 v[0:3], v[194:197], v[210:213], v[0:3]
	v_mfma_f32_16x16x32_bf16 v[28:31], v[84:87], v[206:209], v[28:31]
	v_mfma_f32_16x16x32_bf16 v[24:27], v[84:87], v[214:217], v[24:27]
	v_mfma_f32_16x16x32_bf16 v[12:15], v[190:193], v[206:209], v[12:15]
	v_mfma_f32_16x16x32_bf16 v[8:11], v[190:193], v[214:217], v[8:11]
	v_mfma_f32_16x16x32_bf16 v[158:161], v[182:185], v[206:209], v[20:23]
	v_mfma_f32_16x16x32_bf16 v[166:169], v[182:185], v[214:217], v[16:19]
	v_mfma_f32_16x16x32_bf16 v[178:181], v[198:201], v[206:209], v[4:7]
	v_mfma_f32_16x16x32_bf16 v[182:185], v[198:201], v[214:217], v[0:3]
	s_setprio 0
	s_barrier
; #define LDA(dst, b, h) _Pragma("unroll") for (int m = 0; m < 4; ++m) _Pragma("unroll") for (int k = 0; k < 2; ++k) \
;     dst[m][k] = *reinterpret_cast<const bf16x8*>((char*)SA(b, h) + lds_byte(wr * 64 + m * 16 + fr, k * 32 + fq * 8))
; #define LDB(dst, b, h) _Pragma("unroll") for (int n = 0; n < 2; ++n) _Pragma("unroll") for (int k = 0; k < 2; ++k) \
;     dst[n][k] = *reinterpret_cast<const bf16x8*>((char*)SB(b, h) + lds_byte(wc * 32 + n * 16 + fr, k * 32 + fq * 8))
; #define MMA(ai, bj, At_, Bt_) do { __builtin_amdgcn_s_setprio(1); \
;     _Pragma("unroll") for (int k = 0; k < 2; ++k) _Pragma("unroll") for (int m = 0; m < 4; ++m) _Pragma("unroll") for (int n = 0; n < 2; ++n) \
;       acc[ai][bj][m][n] = __builtin_amdgcn_mfma_f32_16x16x32_bf16(At_[m][k], Bt_[n][k], acc[ai][bj][m][n], 0, 0, 0); \
;     __builtin_amdgcn_s_setprio(0); } while (0)
; #define WAIT_V(n) asm volatile("s_waitcnt vmcnt(" #n ")" ::: "memory")
; #define BAR __builtin_amdgcn_s_barrier()
; template <int EPI, int N, int K>
; __device__ __forceinline__ void gemm_phase(const bf16_t* __restrict__ A, const bf16_t* __restrict__ Bt, const EpiArgs ea) {
;     ...
;     { LDB(B0, 1, 0); LDA(At, 1, 0); WAIT_V(2); BAR; WAIT_L(0); MMA(0, 0, At, B0); BAR;
;       LDB(B1, 1, 1); WAIT_V(0); BAR; WAIT_L(0); MMA(0, 1, At, B1); BAR;
;       LDA(At, 1, 1); BAR; WAIT_L(0); MMA(1, 0, At, B0); MMA(1, 1, At, B1); BAR; }
;     if (wr == 0) BAR;
	s_nop 0
	ds_read_b128 v[0:3], v151
	ds_read_b128 v[4:7], v151 offset:1024
	ds_read_b128 v[16:19], v151 offset:2048
	ds_read_b128 v[186:189], v151 offset:3072
	ds_read_b128 v[20:23], v146 offset:32768
	ds_read_b128 v[190:193], v146 offset:33792
	ds_read_b128 v[194:197], v147 offset:32768
	ds_read_b128 v[198:201], v147 offset:33792
	ds_read_b128 v[202:205], v148 offset:32768
	ds_read_b128 v[206:209], v148 offset:33792
	ds_read_b128 v[210:213], v149 offset:32768
	ds_read_b128 v[214:217], v149 offset:33792
	s_waitcnt vmcnt(2)
	s_barrier
	s_waitcnt lgkmcnt(0)
	s_setprio 1
	v_mfma_f32_16x16x32_bf16 v[56:59], v[20:23], v[0:3], v[124:127]
	v_mfma_f32_16x16x32_bf16 v[60:63], v[20:23], v[16:19], v[120:123]
	v_mfma_f32_16x16x32_bf16 v[80:83], v[194:197], v[0:3], v[116:119]
	v_mfma_f32_16x16x32_bf16 v[84:87], v[194:197], v[16:19], v[112:115]
	v_mfma_f32_16x16x32_bf16 v[108:111], v[202:205], v[0:3], v[108:111]
	v_mfma_f32_16x16x32_bf16 v[104:107], v[202:205], v[16:19], v[104:107]
	v_mfma_f32_16x16x32_bf16 v[120:123], v[210:213], v[0:3], v[100:103]
	v_mfma_f32_16x16x32_bf16 v[124:127], v[210:213], v[16:19], v[96:99]
	v_mfma_f32_16x16x32_bf16 v[116:119], v[190:193], v[4:7], v[56:59]
	v_mfma_f32_16x16x32_bf16 v[112:115], v[190:193], v[186:189], v[60:63]
	v_mfma_f32_16x16x32_bf16 v[100:103], v[198:201], v[4:7], v[80:83]
	v_mfma_f32_16x16x32_bf16 v[96:99], v[198:201], v[186:189], v[84:87]
	v_mfma_f32_16x16x32_bf16 v[84:87], v[206:209], v[4:7], v[108:111]
	v_mfma_f32_16x16x32_bf16 v[80:83], v[206:209], v[186:189], v[104:107]
	v_mfma_f32_16x16x32_bf16 v[60:63], v[214:217], v[4:7], v[120:123]
	v_mfma_f32_16x16x32_bf16 v[56:59], v[214:217], v[186:189], v[124:127]
	s_setprio 0
	s_barrier
	ds_read_b128 v[218:221], v152
	ds_read_b128 v[222:225], v152 offset:1024
	ds_read_b128 v[226:229], v152 offset:2048
	ds_read_b128 v[230:233], v152 offset:3072
	s_waitcnt vmcnt(0)
	s_barrier
	s_waitcnt lgkmcnt(0)
	s_setprio 1
	v_mfma_f32_16x16x32_bf16 v[92:95], v[20:23], v[218:221], v[92:95]
	v_mfma_f32_16x16x32_bf16 v[20:23], v[20:23], v[226:229], v[88:91]
	v_mfma_f32_16x16x32_bf16 v[88:91], v[194:197], v[218:221], v[170:173]
	v_mfma_f32_16x16x32_bf16 v[104:107], v[194:197], v[226:229], v[174:177]
	v_mfma_f32_16x16x32_bf16 v[76:79], v[202:205], v[218:221], v[76:79]
	v_mfma_f32_16x16x32_bf16 v[72:75], v[202:205], v[226:229], v[72:75]
	v_mfma_f32_16x16x32_bf16 v[68:71], v[210:213], v[218:221], v[68:71]
	v_mfma_f32_16x16x32_bf16 v[64:67], v[210:213], v[226:229], v[64:67]
	v_mfma_f32_16x16x32_bf16 v[124:127], v[190:193], v[222:225], v[92:95]
	v_mfma_f32_16x16x32_bf16 v[120:123], v[190:193], v[230:233], v[20:23]
	v_mfma_f32_16x16x32_bf16 v[108:111], v[198:201], v[222:225], v[88:91]
	v_mfma_f32_16x16x32_bf16 v[104:107], v[198:201], v[230:233], v[104:107]
	v_mfma_f32_16x16x32_bf16 v[92:95], v[206:209], v[222:225], v[76:79]
	v_mfma_f32_16x16x32_bf16 v[88:91], v[206:209], v[230:233], v[72:75]
	v_mfma_f32_16x16x32_bf16 v[76:79], v[214:217], v[222:225], v[68:71]
	v_mfma_f32_16x16x32_bf16 v[72:75], v[214:217], v[230:233], v[64:67]
	s_setprio 0
	s_barrier
	s_nop 0
	ds_read_b128 v[64:67], v146 offset:49152
	ds_read_b128 v[170:173], v146 offset:50176
	ds_read_b128 v[68:71], v147 offset:49152
	ds_read_b128 v[174:177], v147 offset:50176
	ds_read_b128 v[190:193], v148 offset:49152
	ds_read_b128 v[194:197], v148 offset:50176
	ds_read_b128 v[198:201], v149 offset:49152
	ds_read_b128 v[202:205], v149 offset:50176
	s_barrier
	s_waitcnt lgkmcnt(0)
	s_setprio 1
	v_mfma_f32_16x16x32_bf16 v[20:23], v[64:67], v[0:3], v[154:157]
	v_mfma_f32_16x16x32_bf16 v[154:157], v[64:67], v[16:19], v[162:165]
	v_mfma_f32_16x16x32_bf16 v[162:165], v[68:71], v[0:3], v[52:55]
	v_mfma_f32_16x16x32_bf16 v[206:209], v[68:71], v[16:19], v[48:51]
	v_mfma_f32_16x16x32_bf16 v[44:47], v[190:193], v[0:3], v[44:47]
	v_mfma_f32_16x16x32_bf16 v[40:43], v[190:193], v[16:19], v[40:43]
	v_mfma_f32_16x16x32_bf16 v[0:3], v[198:201], v[0:3], v[36:39]
	v_mfma_f32_16x16x32_bf16 v[210:213], v[198:201], v[16:19], v[32:35]
	v_mfma_f32_16x16x32_bf16 v[52:55], v[170:173], v[4:7], v[20:23]
	v_mfma_f32_16x16x32_bf16 v[48:51], v[170:173], v[186:189], v[154:157]
	v_mfma_f32_16x16x32_bf16 v[36:39], v[174:177], v[4:7], v[162:165]
	v_mfma_f32_16x16x32_bf16 v[32:35], v[174:177], v[186:189], v[206:209]
	v_mfma_f32_16x16x32_bf16 v[20:23], v[194:197], v[4:7], v[44:47]
	v_mfma_f32_16x16x32_bf16 v[16:19], v[194:197], v[186:189], v[40:43]
	v_mfma_f32_16x16x32_bf16 v[4:7], v[202:205], v[4:7], v[0:3]
	v_mfma_f32_16x16x32_bf16 v[0:3], v[202:205], v[186:189], v[210:213]
	s_setprio 0
	s_setprio 1
	v_mfma_f32_16x16x32_bf16 v[28:31], v[64:67], v[218:221], v[28:31]
	v_mfma_f32_16x16x32_bf16 v[24:27], v[64:67], v[226:229], v[24:27]
	v_mfma_f32_16x16x32_bf16 v[40:43], v[68:71], v[218:221], v[158:161]
	v_mfma_f32_16x16x32_bf16 v[154:157], v[68:71], v[226:229], v[166:169]
	v_mfma_f32_16x16x32_bf16 v[12:15], v[190:193], v[218:221], v[12:15]
	v_mfma_f32_16x16x32_bf16 v[8:11], v[190:193], v[226:229], v[8:11]
	v_mfma_f32_16x16x32_bf16 v[158:161], v[198:201], v[218:221], v[178:181]
	v_mfma_f32_16x16x32_bf16 v[162:165], v[198:201], v[226:229], v[182:185]
	v_mfma_f32_16x16x32_bf16 v[68:71], v[170:173], v[222:225], v[28:31]
	v_mfma_f32_16x16x32_bf16 v[64:67], v[170:173], v[230:233], v[24:27]
	v_mfma_f32_16x16x32_bf16 v[44:47], v[174:177], v[222:225], v[40:43]
	v_mfma_f32_16x16x32_bf16 v[40:43], v[174:177], v[230:233], v[154:157]
	v_mfma_f32_16x16x32_bf16 v[28:31], v[194:197], v[222:225], v[12:15]
	v_mfma_f32_16x16x32_bf16 v[24:27], v[194:197], v[230:233], v[8:11]
	v_mfma_f32_16x16x32_bf16 v[12:15], v[202:205], v[222:225], v[158:161]
	v_mfma_f32_16x16x32_bf16 v[8:11], v[202:205], v[230:233], v[162:165]
	s_setprio 0
	s_barrier
	s_and_saveexec_b64 s[0:1], s[6:7]
	s_cbranch_execz .LBB0_136
	s_barrier

; #define STAGE_A(POFF, h, kt) STAGE_AX(POFF, h, kt, brow)
; #define STAGE_B(POFF, h, kt) STAGE_BX(POFF, h, kt, bcol)
; #define LDA(dst, b, h) _Pragma("unroll") for (int m = 0; m < 4; ++m) _Pragma("unroll") for (int k = 0; k < 2; ++k) \
;     dst[m][k] = *reinterpret_cast<const bf16x8*>((char*)SA(b, h) + lds_byte(wr * 64 + m * 16 + fr, k * 32 + fq * 8))
; #define LDB(dst, b, h) _Pragma("unroll") for (int n = 0; n < 2; ++n) _Pragma("unroll") for (int k = 0; k < 2; ++k) \
;     dst[n][k] = *reinterpret_cast<const bf16x8*>((char*)SB(b, h) + lds_byte(wc * 32 + n * 16 + fr, k * 32 + fq * 8))
; #define MMA(ai, bj, At_, Bt_) do { __builtin_amdgcn_s_setprio(1); \
;     _Pragma("unroll") for (int k = 0; k < 2; ++k) _Pragma("unroll") for (int m = 0; m < 4; ++m) _Pragma("unroll") for (int n = 0; n < 2; ++n) \
;       acc[ai][bj][m][n] = __builtin_amdgcn_mfma_f32_16x16x32_bf16(At_[m][k], Bt_[n][k], acc[ai][bj][m][n], 0, 0, 0); \
;     __builtin_amdgcn_s_setprio(0); } while (0)
; #define WAIT_V(n) asm volatile("s_waitcnt vmcnt(" #n ")" ::: "memory")
; #define BAR __builtin_amdgcn_s_barrier()
; #define SCHED __builtin_amdgcn_sched_barrier(0)
; #define TILE_RC(w_, brow_, bcol_) do { const int wg_ = ((w_) & 7) * qx + ((w_) >> 3); const int gid_ = wg_ / nig; \
;     brow_ = (gid_ * 8 + ((wg_ % nig) & 7)) * 256; bcol_ = ((wg_ % nig) >> 3) * 256; } while (0)
; template <int EPI, int N, int K>
; __device__ __forceinline__ void gemm_phase(const bf16_t* __restrict__ A, const bf16_t* __restrict__ Bt, const EpiArgs ea) {
;     ...
;     int brow, bcol; TILE_RC(w, brow, bcol);
;     f32x4 acc[2][2][4][2];
; #pragma unroll
;     for (int a = 0; a < 2; ++a)
; #pragma unroll
;       for (int b = 0; b < 2; ++b)
; #pragma unroll
;         for (int m = 0; m < 4; ++m)
; #pragma unroll
;           for (int n = 0; n < 2; ++n) acc[a][b][m][n] = (f32x4){0.f, 0.f, 0.f, 0.f};
;     bf16x8 At[4][2], B0[2][2], B1[2][2];
;     if (wr == 1) BAR;
;     if (w == (int)blockIdx.x) { WAIT_V(0); } else { WAIT_V(24); }
;     BAR;
;     BAR;
;     for (int t = 0; t < nt - 2; t += 2) {
;       LDB(B0, 0, 0); SCHED; LDA(At, 0, 0); STAGE_A(SA_OFF(1, 1), 1, t + 1);
;       WAIT_L(8); BAR; WAIT_L(0); MMA(0, 0, At, B0); BAR; SCHED;
;       LDB(B1, 0, 1); STAGE_B(SB_OFF(0, 0), 0, t + 2);
.LBB0_269:
	s_and_b32 s0, s26, 7
	s_mulk_i32 s0, 0x50
	s_ashr_i32 s1, s26, 3
	s_add_i32 s1, s0, s1
	s_mul_hi_i32 s0, s1, 0x66666667
	s_lshr_b32 s2, s0, 31
	s_ashr_i32 s0, s0, 5
	s_add_i32 s0, s0, s2
	s_mul_i32 s2, s0, 0x50
	s_sub_i32 s27, s1, s2
	s_lshl_b32 s1, s27, 8
	s_lshl_b32 s2, s27, 5
	s_lshl_b32 s3, s27, 17
	s_and_b32 s27, s27, 7
	s_lshl_b32 s28, s0, 23
	s_lshl_b32 s27, s27, 20
	v_mov_b32_e32 v0, 0
	s_barrier
	s_barrier
	s_and_b32 s3, s3, 0xfff00000
	s_or_b32 s27, s28, s27
	s_mov_b32 s28, -2
	s_mov_b32 s29, 0
	v_mov_b32_e32 v1, v0
	v_mov_b32_e32 v2, v0
	v_mov_b32_e32 v3, v0
	v_mov_b32_e32 v4, v0
	v_mov_b32_e32 v5, v0
	v_mov_b32_e32 v6, v0
	v_mov_b32_e32 v7, v0
	v_mov_b32_e32 v8, v0
	v_mov_b32_e32 v9, v0
	v_mov_b32_e32 v10, v0
	v_mov_b32_e32 v11, v0
	v_mov_b32_e32 v12, v0
	v_mov_b32_e32 v13, v0
	v_mov_b32_e32 v14, v0
	v_mov_b32_e32 v15, v0
	v_mov_b32_e32 v16, v0
	v_mov_b32_e32 v17, v0
	v_mov_b32_e32 v18, v0
	v_mov_b32_e32 v19, v0
	v_mov_b32_e32 v20, v0
	v_mov_b32_e32 v21, v0
	v_mov_b32_e32 v22, v0
	v_mov_b32_e32 v23, v0
	v_mov_b32_e32 v24, v0
	v_mov_b32_e32 v25, v0
	v_mov_b32_e32 v26, v0
	v_mov_b32_e32 v27, v0
	v_mov_b32_e32 v28, v0
	v_mov_b32_e32 v29, v0
	v_mov_b32_e32 v30, v0
	v_mov_b32_e32 v31, v0
	v_mov_b32_e32 v32, v0
	v_mov_b32_e32 v33, v0
	v_mov_b32_e32 v34, v0
	v_mov_b32_e32 v35, v0
	v_mov_b32_e32 v36, v0
	v_mov_b32_e32 v37, v0
	v_mov_b32_e32 v38, v0
	v_mov_b32_e32 v39, v0
	v_mov_b32_e32 v40, v0
	v_mov_b32_e32 v41, v0
	v_mov_b32_e32 v42, v0
	v_mov_b32_e32 v43, v0
	v_mov_b32_e32 v44, v0
	v_mov_b32_e32 v45, v0
	v_mov_b32_e32 v46, v0
	v_mov_b32_e32 v47, v0
	v_mov_b32_e32 v48, v0
	v_mov_b32_e32 v49, v0
	v_mov_b32_e32 v50, v0
	v_mov_b32_e32 v51, v0
	v_mov_b32_e32 v52, v0
	v_mov_b32_e32 v53, v0
	v_mov_b32_e32 v54, v0
	v_mov_b32_e32 v55, v0
	v_mov_b32_e32 v56, v0
	v_mov_b32_e32 v57, v0
	v_mov_b32_e32 v58, v0
	v_mov_b32_e32 v59, v0
	v_mov_b32_e32 v60, v0
	v_mov_b32_e32 v61, v0
	v_mov_b32_e32 v62, v0
	v_mov_b32_e32 v63, v0
	v_mov_b32_e32 v64, v0
	v_mov_b32_e32 v65, v0
	v_mov_b32_e32 v66, v0
	v_mov_b32_e32 v67, v0
	v_mov_b32_e32 v68, v0
	v_mov_b32_e32 v69, v0
	v_mov_b32_e32 v70, v0
	v_mov_b32_e32 v71, v0
	v_mov_b32_e32 v72, v0
	v_mov_b32_e32 v73, v0
	v_mov_b32_e32 v74, v0
	v_mov_b32_e32 v75, v0
	v_mov_b32_e32 v76, v0
	v_mov_b32_e32 v77, v0
	v_mov_b32_e32 v78, v0
	v_mov_b32_e32 v79, v0
	v_mov_b32_e32 v80, v0
	v_mov_b32_e32 v81, v0
	v_mov_b32_e32 v82, v0
	v_mov_b32_e32 v83, v0
	v_mov_b32_e32 v84, v0
	v_mov_b32_e32 v85, v0
	v_mov_b32_e32 v86, v0
	v_mov_b32_e32 v87, v0
	v_mov_b32_e32 v88, v0
	v_mov_b32_e32 v89, v0
	v_mov_b32_e32 v90, v0
	v_mov_b32_e32 v91, v0
	v_mov_b32_e32 v92, v0
	v_mov_b32_e32 v93, v0
	v_mov_b32_e32 v94, v0
	v_mov_b32_e32 v95, v0
	v_mov_b32_e32 v96, v0
	v_mov_b32_e32 v97, v0
	v_mov_b32_e32 v98, v0
	v_mov_b32_e32 v99, v0
	v_mov_b32_e32 v100, v0
	v_mov_b32_e32 v101, v0
	v_mov_b32_e32 v102, v0
	v_mov_b32_e32 v103, v0
	v_mov_b32_e32 v104, v0
	v_mov_b32_e32 v105, v0
	v_mov_b32_e32 v106, v0
	v_mov_b32_e32 v107, v0
	v_mov_b32_e32 v108, v0
	v_mov_b32_e32 v109, v0
	v_mov_b32_e32 v110, v0
	v_mov_b32_e32 v111, v0
	v_mov_b32_e32 v112, v0
	v_mov_b32_e32 v113, v0
	v_mov_b32_e32 v114, v0
	v_mov_b32_e32 v115, v0
	v_mov_b32_e32 v116, v0
	v_mov_b32_e32 v117, v0
	v_mov_b32_e32 v118, v0
	v_mov_b32_e32 v119, v0
	v_mov_b32_e32 v120, v0
	v_mov_b32_e32 v121, v0
	v_mov_b32_e32 v122, v0
	v_mov_b32_e32 v123, v0
	v_mov_b32_e32 v124, v0
	v_mov_b32_e32 v125, v0
	v_mov_b32_e32 v126, v0
	v_mov_b32_e32 v127, v0
	ds_read_b128 v[154:157], v145
	ds_read_b128 v[158:161], v145 offset:1024
	ds_read_b128 v[162:165], v145 offset:2048
	ds_read_b128 v[166:169], v145 offset:3072
.LBB0_270:
	ds_read_b128 v[170:173], v146
	ds_read_b128 v[174:177], v146 offset:1024
	ds_read_b128 v[178:181], v147
	ds_read_b128 v[182:185], v147 offset:1024
	ds_read_b128 v[186:189], v148
	ds_read_b128 v[190:193], v148 offset:1024
	ds_read_b128 v[194:197], v149
	ds_read_b128 v[198:201], v149 offset:1024
	s_add_i32 s30, s27, s29
	s_or_b32 s31, s30, 0x80080
	s_mov_b32 m0, s24
	s_nop 0
	buffer_load_dwordx4 v131, s[48:51], s31 offen lds
	s_or_b32 s31, s30, 0xc0080
	s_mov_b32 m0, s25
	s_nop 0
	buffer_load_dwordx4 v131, s[48:51], s31 offen lds
	s_waitcnt lgkmcnt(8)
	s_barrier
	s_waitcnt lgkmcnt(0)
	s_setprio 1
	v_mfma_f32_16x16x32_bf16 v[124:127], v[170:173], v[154:157], v[124:127]
	v_mfma_f32_16x16x32_bf16 v[120:123], v[170:173], v[162:165], v[120:123]
	v_mfma_f32_16x16x32_bf16 v[116:119], v[178:181], v[154:157], v[116:119]
	v_mfma_f32_16x16x32_bf16 v[112:115], v[178:181], v[162:165], v[112:115]
	v_mfma_f32_16x16x32_bf16 v[108:111], v[186:189], v[154:157], v[108:111]
	v_mfma_f32_16x16x32_bf16 v[104:107], v[186:189], v[162:165], v[104:107]
	v_mfma_f32_16x16x32_bf16 v[100:103], v[194:197], v[154:157], v[100:103]
	v_mfma_f32_16x16x32_bf16 v[96:99], v[194:197], v[162:165], v[96:99]
	v_mfma_f32_16x16x32_bf16 v[124:127], v[174:177], v[158:161], v[124:127]
	v_mfma_f32_16x16x32_bf16 v[120:123], v[174:177], v[166:169], v[120:123]
	v_mfma_f32_16x16x32_bf16 v[116:119], v[182:185], v[158:161], v[116:119]
	v_mfma_f32_16x16x32_bf16 v[112:115], v[182:185], v[166:169], v[112:115]
	v_mfma_f32_16x16x32_bf16 v[108:111], v[190:193], v[158:161], v[108:111]
	v_mfma_f32_16x16x32_bf16 v[104:107], v[190:193], v[166:169], v[104:107]
	v_mfma_f32_16x16x32_bf16 v[100:103], v[198:201], v[158:161], v[100:103]
	v_mfma_f32_16x16x32_bf16 v[96:99], v[198:201], v[166:169], v[96:99]
	s_setprio 0
	s_barrier
	ds_read_b128 v[202:205], v150
	ds_read_b128 v[206:209], v150 offset:1024
	ds_read_b128 v[210:213], v150 offset:2048
	ds_read_b128 v[214:217], v150 offset:3072
	s_add_i32 s31, s3, s29
	s_add_i32 s34, s31, 0x100
	s_mov_b32 m0, s11
	s_nop 0
	buffer_load_dwordx4 v134, s[56:59], s34 offen lds
	s_add_i32 s34, s31, 0x80100
	s_mov_b32 m0, s12
	s_nop 0
	buffer_load_dwordx4 v134, s[56:59], s34 offen lds
	s_barrier
; #define STAGE_A(POFF, h, kt) STAGE_AX(POFF, h, kt, brow)
; #define STAGE_B(POFF, h, kt) STAGE_BX(POFF, h, kt, bcol)
; #define LDA(dst, b, h) _Pragma("unroll") for (int m = 0; m < 4; ++m) _Pragma("unroll") for (int k = 0; k < 2; ++k) \
;     dst[m][k] = *reinterpret_cast<const bf16x8*>((char*)SA(b, h) + lds_byte(wr * 64 + m * 16 + fr, k * 32 + fq * 8))
; #define LDB(dst, b, h) _Pragma("unroll") for (int n = 0; n < 2; ++n) _Pragma("unroll") for (int k = 0; k < 2; ++k) \
;     dst[n][k] = *reinterpret_cast<const bf16x8*>((char*)SB(b, h) + lds_byte(wc * 32 + n * 16 + fr, k * 32 + fq * 8))
; #define MMA(ai, bj, At_, Bt_) do { __builtin_amdgcn_s_setprio(1); \
;     _Pragma("unroll") for (int k = 0; k < 2; ++k) _Pragma("unroll") for (int m = 0; m < 4; ++m) _Pragma("unroll") for (int n = 0; n < 2; ++n) \
;       acc[ai][bj][m][n] = __builtin_amdgcn_mfma_f32_16x16x32_bf16(At_[m][k], Bt_[n][k], acc[ai][bj][m][n], 0, 0, 0); \
;     __builtin_amdgcn_s_setprio(0); } while (0)
; #define WAIT_V(n) asm volatile("s_waitcnt vmcnt(" #n ")" ::: "memory")
; #define BAR __builtin_amdgcn_s_barrier()
; #define SCHED __builtin_amdgcn_sched_barrier(0)
; template <int EPI, int N, int K>
; __device__ __forceinline__ void gemm_phase(const bf16_t* __restrict__ A, const bf16_t* __restrict__ Bt, const EpiArgs ea) {
;     ...
;       BAR; WAIT_L(0); MMA(0, 1, At, B1); BAR;
;       LDA(At, 0, 1); STAGE_A(SA_OFF(0, 0), 0, t + 2);
;       BAR; WAIT_L(0); MMA(1, 0, At, B0); BAR; SCHED;
;       STAGE_B(SB_OFF(0, 1), 1, t + 2);
;       WAIT_V(6); BAR; MMA(1, 1, At, B1); BAR;
;       LDB(B0, 1, 0); SCHED; LDA(At, 1, 0); STAGE_A(SA_OFF(0, 1), 1, t + 2);
;       WAIT_L(8); BAR; WAIT_L(0); MMA(0, 0, At, B0); BAR; SCHED;
	s_waitcnt lgkmcnt(0)
	s_setprio 1
	v_mfma_f32_16x16x32_bf16 v[92:95], v[170:173], v[202:205], v[92:95]
	v_mfma_f32_16x16x32_bf16 v[88:91], v[170:173], v[210:213], v[88:91]
	v_mfma_f32_16x16x32_bf16 v[84:87], v[178:181], v[202:205], v[84:87]
	v_mfma_f32_16x16x32_bf16 v[80:83], v[178:181], v[210:213], v[80:83]
	v_mfma_f32_16x16x32_bf16 v[76:79], v[186:189], v[202:205], v[76:79]
	v_mfma_f32_16x16x32_bf16 v[72:75], v[186:189], v[210:213], v[72:75]
	v_mfma_f32_16x16x32_bf16 v[68:71], v[194:197], v[202:205], v[68:71]
	v_mfma_f32_16x16x32_bf16 v[64:67], v[194:197], v[210:213], v[64:67]
	v_mfma_f32_16x16x32_bf16 v[92:95], v[174:177], v[206:209], v[92:95]
	v_mfma_f32_16x16x32_bf16 v[88:91], v[174:177], v[214:217], v[88:91]
	v_mfma_f32_16x16x32_bf16 v[84:87], v[182:185], v[206:209], v[84:87]
	v_mfma_f32_16x16x32_bf16 v[80:83], v[182:185], v[214:217], v[80:83]
	v_mfma_f32_16x16x32_bf16 v[76:79], v[190:193], v[206:209], v[76:79]
	v_mfma_f32_16x16x32_bf16 v[72:75], v[190:193], v[214:217], v[72:75]
	v_mfma_f32_16x16x32_bf16 v[68:71], v[198:201], v[206:209], v[68:71]
	v_mfma_f32_16x16x32_bf16 v[64:67], v[198:201], v[214:217], v[64:67]
	s_setprio 0
	s_barrier
	ds_read_b128 v[170:173], v146 offset:16384
	ds_read_b128 v[174:177], v146 offset:17408
	ds_read_b128 v[178:181], v147 offset:16384
	ds_read_b128 v[182:185], v147 offset:17408
	ds_read_b128 v[186:189], v148 offset:16384
	ds_read_b128 v[190:193], v148 offset:17408
	ds_read_b128 v[194:197], v149 offset:16384
	ds_read_b128 v[198:201], v149 offset:17408
	s_add_i32 s34, s30, 0x100
	s_mov_b32 m0, s10
	s_nop 0
	buffer_load_dwordx4 v131, s[48:51], s34 offen lds
	s_add_i32 s35, s30, 0x40100
	s_mov_b32 m0, s13
	s_nop 0
	buffer_load_dwordx4 v131, s[48:51], s35 offen lds
	s_waitcnt vmcnt(10)
	s_barrier
	s_waitcnt lgkmcnt(0)
	s_setprio 1
	v_mfma_f32_16x16x32_bf16 v[60:63], v[170:173], v[154:157], v[60:63]
	v_mfma_f32_16x16x32_bf16 v[56:59], v[170:173], v[162:165], v[56:59]
	v_mfma_f32_16x16x32_bf16 v[52:55], v[178:181], v[154:157], v[52:55]
	v_mfma_f32_16x16x32_bf16 v[48:51], v[178:181], v[162:165], v[48:51]
	v_mfma_f32_16x16x32_bf16 v[44:47], v[186:189], v[154:157], v[44:47]
	v_mfma_f32_16x16x32_bf16 v[40:43], v[186:189], v[162:165], v[40:43]
	v_mfma_f32_16x16x32_bf16 v[36:39], v[194:197], v[154:157], v[36:39]
	v_mfma_f32_16x16x32_bf16 v[32:35], v[194:197], v[162:165], v[32:35]
	v_mfma_f32_16x16x32_bf16 v[60:63], v[174:177], v[158:161], v[60:63]
	v_mfma_f32_16x16x32_bf16 v[56:59], v[174:177], v[166:169], v[56:59]
	v_mfma_f32_16x16x32_bf16 v[52:55], v[182:185], v[158:161], v[52:55]
	v_mfma_f32_16x16x32_bf16 v[48:51], v[182:185], v[166:169], v[48:51]
	v_mfma_f32_16x16x32_bf16 v[44:47], v[190:193], v[158:161], v[44:47]
	v_mfma_f32_16x16x32_bf16 v[40:43], v[190:193], v[166:169], v[40:43]
	v_mfma_f32_16x16x32_bf16 v[36:39], v[198:201], v[158:161], v[36:39]
	v_mfma_f32_16x16x32_bf16 v[32:35], v[198:201], v[166:169], v[32:35]
	s_setprio 0
	s_barrier
	ds_read_b128 v[154:157], v151
	ds_read_b128 v[158:161], v151 offset:1024
	ds_read_b128 v[162:165], v151 offset:2048
	ds_read_b128 v[166:169], v151 offset:3072
	s_add_i32 s35, s31, 0x2100
	s_mov_b32 m0, s14
	s_nop 0
	buffer_load_dwordx4 v134, s[56:59], s35 offen lds
	s_add_i32 s35, s31, 0x82100
	s_mov_b32 m0, s15
	s_nop 0
	buffer_load_dwordx4 v134, s[56:59], s35 offen lds
	s_waitcnt vmcnt(6)
	s_barrier
	s_setprio 1
	v_mfma_f32_16x16x32_bf16 v[28:31], v[170:173], v[202:205], v[28:31]
	v_mfma_f32_16x16x32_bf16 v[24:27], v[170:173], v[210:213], v[24:27]
	v_mfma_f32_16x16x32_bf16 v[20:23], v[178:181], v[202:205], v[20:23]
	v_mfma_f32_16x16x32_bf16 v[16:19], v[178:181], v[210:213], v[16:19]
	v_mfma_f32_16x16x32_bf16 v[12:15], v[186:189], v[202:205], v[12:15]
	v_mfma_f32_16x16x32_bf16 v[8:11], v[186:189], v[210:213], v[8:11]
	v_mfma_f32_16x16x32_bf16 v[4:7], v[194:197], v[202:205], v[4:7]
	v_mfma_f32_16x16x32_bf16 v[0:3], v[194:197], v[210:213], v[0:3]
	v_mfma_f32_16x16x32_bf16 v[28:31], v[174:177], v[206:209], v[28:31]
	v_mfma_f32_16x16x32_bf16 v[24:27], v[174:177], v[214:217], v[24:27]
	v_mfma_f32_16x16x32_bf16 v[20:23], v[182:185], v[206:209], v[20:23]
	v_mfma_f32_16x16x32_bf16 v[16:19], v[182:185], v[214:217], v[16:19]
	v_mfma_f32_16x16x32_bf16 v[12:15], v[190:193], v[206:209], v[12:15]
	v_mfma_f32_16x16x32_bf16 v[8:11], v[190:193], v[214:217], v[8:11]
	v_mfma_f32_16x16x32_bf16 v[4:7], v[198:201], v[206:209], v[4:7]
	v_mfma_f32_16x16x32_bf16 v[0:3], v[198:201], v[214:217], v[0:3]
	s_setprio 0
	s_barrier
	ds_read_b128 v[170:173], v146 offset:32768
	ds_read_b128 v[174:177], v146 offset:33792
	ds_read_b128 v[178:181], v147 offset:32768
	ds_read_b128 v[182:185], v147 offset:33792
	ds_read_b128 v[186:189], v148 offset:32768
	ds_read_b128 v[190:193], v148 offset:33792
	ds_read_b128 v[194:197], v149 offset:32768
	ds_read_b128 v[198:201], v149 offset:33792
	s_or_b32 s35, s34, 0x80000
	s_mov_b32 m0, s16
	s_nop 0
	buffer_load_dwordx4 v131, s[48:51], s35 offen lds
	s_or_b32 s34, s34, 0xc0000
	s_mov_b32 m0, s17
	s_nop 0
	buffer_load_dwordx4 v131, s[48:51], s34 offen lds
	s_waitcnt lgkmcnt(8)
	s_barrier
; #define STAGE_A(POFF, h, kt) STAGE_AX(POFF, h, kt, brow)
; #define STAGE_B(POFF, h, kt) STAGE_BX(POFF, h, kt, bcol)
; #define LDA(dst, b, h) _Pragma("unroll") for (int m = 0; m < 4; ++m) _Pragma("unroll") for (int k = 0; k < 2; ++k) \
;     dst[m][k] = *reinterpret_cast<const bf16x8*>((char*)SA(b, h) + lds_byte(wr * 64 + m * 16 + fr, k * 32 + fq * 8))
; #define LDB(dst, b, h) _Pragma("unroll") for (int n = 0; n < 2; ++n) _Pragma("unroll") for (int k = 0; k < 2; ++k) \
;     dst[n][k] = *reinterpret_cast<const bf16x8*>((char*)SB(b, h) + lds_byte(wc * 32 + n * 16 + fr, k * 32 + fq * 8))
; #define MMA(ai, bj, At_, Bt_) do { __builtin_amdgcn_s_setprio(1); \
;     _Pragma("unroll") for (int k = 0; k < 2; ++k) _Pragma("unroll") for (int m = 0; m < 4; ++m) _Pragma("unroll") for (int n = 0; n < 2; ++n) \
;       acc[ai][bj][m][n] = __builtin_amdgcn_mfma_f32_16x16x32_bf16(At_[m][k], Bt_[n][k], acc[ai][bj][m][n], 0, 0, 0); \
;     __builtin_amdgcn_s_setprio(0); } while (0)
; #define WAIT_V(n) asm volatile("s_waitcnt vmcnt(" #n ")" ::: "memory")
; #define BAR __builtin_amdgcn_s_barrier()
; #define SCHED __builtin_amdgcn_sched_barrier(0)
; template <int EPI, int N, int K>
; __device__ __forceinline__ void gemm_phase(const bf16_t* __restrict__ A, const bf16_t* __restrict__ Bt, const EpiArgs ea) {
;     ...
;       WAIT_L(8); BAR; WAIT_L(0); MMA(0, 0, At, B0); BAR; SCHED;
;       LDB(B1, 1, 1); STAGE_B(SB_OFF(1, 0), 0, t + 3);
;       BAR; WAIT_L(0); MMA(0, 1, At, B1); BAR;
;       LDA(At, 1, 1); STAGE_A(SA_OFF(1, 0), 0, t + 3);
;       BAR; WAIT_L(0); MMA(1, 0, At, B0); BAR; SCHED;
;       STAGE_B(SB_OFF(1, 1), 1, t + 3);
;       WAIT_V(6); BAR; MMA(1, 1, At, B1); BAR;
	s_waitcnt lgkmcnt(0)
	s_setprio 1
	v_mfma_f32_16x16x32_bf16 v[124:127], v[170:173], v[154:157], v[124:127]
	v_mfma_f32_16x16x32_bf16 v[120:123], v[170:173], v[162:165], v[120:123]
	v_mfma_f32_16x16x32_bf16 v[116:119], v[178:181], v[154:157], v[116:119]
	v_mfma_f32_16x16x32_bf16 v[112:115], v[178:181], v[162:165], v[112:115]
	v_mfma_f32_16x16x32_bf16 v[108:111], v[186:189], v[154:157], v[108:111]
	v_mfma_f32_16x16x32_bf16 v[104:107], v[186:189], v[162:165], v[104:107]
	v_mfma_f32_16x16x32_bf16 v[100:103], v[194:197], v[154:157], v[100:103]
	v_mfma_f32_16x16x32_bf16 v[96:99], v[194:197], v[162:165], v[96:99]
	v_mfma_f32_16x16x32_bf16 v[124:127], v[174:177], v[158:161], v[124:127]
	v_mfma_f32_16x16x32_bf16 v[120:123], v[174:177], v[166:169], v[120:123]
	v_mfma_f32_16x16x32_bf16 v[116:119], v[182:185], v[158:161], v[116:119]
	v_mfma_f32_16x16x32_bf16 v[112:115], v[182:185], v[166:169], v[112:115]
	v_mfma_f32_16x16x32_bf16 v[108:111], v[190:193], v[158:161], v[108:111]
	v_mfma_f32_16x16x32_bf16 v[104:107], v[190:193], v[166:169], v[104:107]
	v_mfma_f32_16x16x32_bf16 v[100:103], v[198:201], v[158:161], v[100:103]
	v_mfma_f32_16x16x32_bf16 v[96:99], v[198:201], v[166:169], v[96:99]
	s_setprio 0
	s_barrier
	ds_read_b128 v[202:205], v152
	ds_read_b128 v[206:209], v152 offset:1024
	ds_read_b128 v[210:213], v152 offset:2048
	ds_read_b128 v[214:217], v152 offset:3072
	s_add_i32 s34, s31, 0x180
	s_mov_b32 m0, s18
	s_nop 0
	buffer_load_dwordx4 v134, s[56:59], s34 offen lds
	s_add_i32 s34, s31, 0x80180
	s_mov_b32 m0, s19
	s_nop 0
	buffer_load_dwordx4 v134, s[56:59], s34 offen lds
	s_barrier
	s_waitcnt lgkmcnt(0)
	s_setprio 1
	v_mfma_f32_16x16x32_bf16 v[92:95], v[170:173], v[202:205], v[92:95]
	v_mfma_f32_16x16x32_bf16 v[88:91], v[170:173], v[210:213], v[88:91]
	v_mfma_f32_16x16x32_bf16 v[84:87], v[178:181], v[202:205], v[84:87]
	v_mfma_f32_16x16x32_bf16 v[80:83], v[178:181], v[210:213], v[80:83]
	v_mfma_f32_16x16x32_bf16 v[76:79], v[186:189], v[202:205], v[76:79]
	v_mfma_f32_16x16x32_bf16 v[72:75], v[186:189], v[210:213], v[72:75]
	v_mfma_f32_16x16x32_bf16 v[68:71], v[194:197], v[202:205], v[68:71]
	v_mfma_f32_16x16x32_bf16 v[64:67], v[194:197], v[210:213], v[64:67]
	v_mfma_f32_16x16x32_bf16 v[92:95], v[174:177], v[206:209], v[92:95]
	v_mfma_f32_16x16x32_bf16 v[88:91], v[174:177], v[214:217], v[88:91]
	v_mfma_f32_16x16x32_bf16 v[84:87], v[182:185], v[206:209], v[84:87]
	v_mfma_f32_16x16x32_bf16 v[80:83], v[182:185], v[214:217], v[80:83]
	v_mfma_f32_16x16x32_bf16 v[76:79], v[190:193], v[206:209], v[76:79]
	v_mfma_f32_16x16x32_bf16 v[72:75], v[190:193], v[214:217], v[72:75]
	v_mfma_f32_16x16x32_bf16 v[68:71], v[198:201], v[206:209], v[68:71]
	v_mfma_f32_16x16x32_bf16 v[64:67], v[198:201], v[214:217], v[64:67]
	s_setprio 0
	s_barrier
	ds_read_b128 v[170:173], v146 offset:49152
	ds_read_b128 v[174:177], v146 offset:50176
	ds_read_b128 v[178:181], v147 offset:49152
	ds_read_b128 v[182:185], v147 offset:50176
	ds_read_b128 v[186:189], v148 offset:49152
	ds_read_b128 v[190:193], v148 offset:50176
	ds_read_b128 v[194:197], v149 offset:49152
	ds_read_b128 v[198:201], v149 offset:50176
	s_add_i32 s34, s30, 0x180
	s_mov_b32 m0, s20
	s_nop 0
	buffer_load_dwordx4 v131, s[48:51], s34 offen lds
	s_add_i32 s30, s30, 0x40180
	s_mov_b32 m0, s21
	s_nop 0
	buffer_load_dwordx4 v131, s[48:51], s30 offen lds
	s_waitcnt vmcnt(10)
	s_barrier
	s_waitcnt lgkmcnt(0)
	s_setprio 1
	v_mfma_f32_16x16x32_bf16 v[60:63], v[170:173], v[154:157], v[60:63]
	v_mfma_f32_16x16x32_bf16 v[56:59], v[170:173], v[162:165], v[56:59]
	v_mfma_f32_16x16x32_bf16 v[52:55], v[178:181], v[154:157], v[52:55]
	v_mfma_f32_16x16x32_bf16 v[48:51], v[178:181], v[162:165], v[48:51]
	v_mfma_f32_16x16x32_bf16 v[44:47], v[186:189], v[154:157], v[44:47]
	v_mfma_f32_16x16x32_bf16 v[40:43], v[186:189], v[162:165], v[40:43]
	v_mfma_f32_16x16x32_bf16 v[36:39], v[194:197], v[154:157], v[36:39]
	v_mfma_f32_16x16x32_bf16 v[32:35], v[194:197], v[162:165], v[32:35]
	v_mfma_f32_16x16x32_bf16 v[60:63], v[174:177], v[158:161], v[60:63]
	v_mfma_f32_16x16x32_bf16 v[56:59], v[174:177], v[166:169], v[56:59]
	v_mfma_f32_16x16x32_bf16 v[52:55], v[182:185], v[158:161], v[52:55]
	v_mfma_f32_16x16x32_bf16 v[48:51], v[182:185], v[166:169], v[48:51]
	v_mfma_f32_16x16x32_bf16 v[44:47], v[190:193], v[158:161], v[44:47]
	v_mfma_f32_16x16x32_bf16 v[40:43], v[190:193], v[166:169], v[40:43]
	v_mfma_f32_16x16x32_bf16 v[36:39], v[198:201], v[158:161], v[36:39]
	v_mfma_f32_16x16x32_bf16 v[32:35], v[198:201], v[166:169], v[32:35]
	s_setprio 0
	s_barrier
	ds_read_b128 v[154:157], v145
	ds_read_b128 v[158:161], v145 offset:1024
	ds_read_b128 v[162:165], v145 offset:2048
	ds_read_b128 v[166:169], v145 offset:3072
	s_add_i32 s30, s31, 0x2180
	s_mov_b32 m0, s22
	s_nop 0
	buffer_load_dwordx4 v134, s[56:59], s30 offen lds
	s_add_i32 s31, s31, 0x82180
	s_mov_b32 m0, s23
	s_nop 0
	buffer_load_dwordx4 v134, s[56:59], s31 offen lds
	s_waitcnt vmcnt(6)
	s_barrier
	s_setprio 1
	v_mfma_f32_16x16x32_bf16 v[28:31], v[170:173], v[202:205], v[28:31]
	v_mfma_f32_16x16x32_bf16 v[24:27], v[170:173], v[210:213], v[24:27]
	v_mfma_f32_16x16x32_bf16 v[20:23], v[178:181], v[202:205], v[20:23]
	v_mfma_f32_16x16x32_bf16 v[16:19], v[178:181], v[210:213], v[16:19]
	v_mfma_f32_16x16x32_bf16 v[12:15], v[186:189], v[202:205], v[12:15]
	v_mfma_f32_16x16x32_bf16 v[8:11], v[186:189], v[210:213], v[8:11]
	v_mfma_f32_16x16x32_bf16 v[4:7], v[194:197], v[202:205], v[4:7]
	v_mfma_f32_16x16x32_bf16 v[0:3], v[194:197], v[210:213], v[0:3]
	v_mfma_f32_16x16x32_bf16 v[28:31], v[174:177], v[206:209], v[28:31]
	v_mfma_f32_16x16x32_bf16 v[24:27], v[174:177], v[214:217], v[24:27]
	v_mfma_f32_16x16x32_bf16 v[20:23], v[182:185], v[206:209], v[20:23]
	v_mfma_f32_16x16x32_bf16 v[16:19], v[182:185], v[214:217], v[16:19]
	v_mfma_f32_16x16x32_bf16 v[12:15], v[190:193], v[206:209], v[12:15]
	v_mfma_f32_16x16x32_bf16 v[8:11], v[190:193], v[214:217], v[8:11]
	v_mfma_f32_16x16x32_bf16 v[4:7], v[198:201], v[206:209], v[4:7]
	v_mfma_f32_16x16x32_bf16 v[0:3], v[198:201], v[214:217], v[0:3]
	s_setprio 0
	s_add_i32 s28, s28, 2
	s_addk_i32 s29, 0x100
	s_cmp_lt_u32 s28, 28
	s_barrier
; #define STAGE_A(POFF, h, kt) STAGE_AX(POFF, h, kt, brow)
; #define LDA(dst, b, h) _Pragma("unroll") for (int m = 0; m < 4; ++m) _Pragma("unroll") for (int k = 0; k < 2; ++k) \
;     dst[m][k] = *reinterpret_cast<const bf16x8*>((char*)SA(b, h) + lds_byte(wr * 64 + m * 16 + fr, k * 32 + fq * 8))
; #define LDB(dst, b, h) _Pragma("unroll") for (int n = 0; n < 2; ++n) _Pragma("unroll") for (int k = 0; k < 2; ++k) \
;     dst[n][k] = *reinterpret_cast<const bf16x8*>((char*)SB(b, h) + lds_byte(wc * 32 + n * 16 + fr, k * 32 + fq * 8))
; #define MMA(ai, bj, At_, Bt_) do { __builtin_amdgcn_s_setprio(1); \
;     _Pragma("unroll") for (int k = 0; k < 2; ++k) _Pragma("unroll") for (int m = 0; m < 4; ++m) _Pragma("unroll") for (int n = 0; n < 2; ++n) \
;       acc[ai][bj][m][n] = __builtin_amdgcn_mfma_f32_16x16x32_bf16(At_[m][k], Bt_[n][k], acc[ai][bj][m][n], 0, 0, 0); \
;     __builtin_amdgcn_s_setprio(0); } while (0)
; #define WAIT_V(n) asm volatile("s_waitcnt vmcnt(" #n ")" ::: "memory")
; #define BAR __builtin_amdgcn_s_barrier()
; template <int EPI, int N, int K>
; __device__ __forceinline__ void gemm_phase(const bf16_t* __restrict__ A, const bf16_t* __restrict__ Bt, const EpiArgs ea) {
;     ...
;     { LDB(B0, 0, 0); LDA(At, 0, 0); STAGE_A(SA_OFF(1, 1), 1, nt - 1);
;       BAR; WAIT_L(0); MMA(0, 0, At, B0); BAR;
;       LDB(B1, 0, 1); BAR; WAIT_L(0); MMA(0, 1, At, B1); BAR;
;       LDA(At, 0, 1); WAIT_V(4); BAR; WAIT_L(0); MMA(1, 0, At, B0); MMA(1, 1, At, B1); BAR; }
;     { LDB(B0, 1, 0); LDA(At, 1, 0); WAIT_V(2); BAR; WAIT_L(0); MMA(0, 0, At, B0); BAR;
	s_cbranch_scc1 .LBB0_270
	ds_read_b128 v[170:173], v146
	ds_read_b128 v[174:177], v146 offset:1024
	ds_read_b128 v[178:181], v147
	ds_read_b128 v[182:185], v147 offset:1024
	ds_read_b128 v[186:189], v148
	ds_read_b128 v[190:193], v148 offset:1024
	ds_read_b128 v[194:197], v149
	ds_read_b128 v[198:201], v149 offset:1024
	s_and_b32 s1, s1, 0x700
	s_lshl_b32 s0, s0, 11
	s_or_b32 s27, s1, s0
	s_lshl_b32 s0, s27, 12
	s_or_b32 s1, s0, 0x80f80
	s_mov_b32 m0, s24
	s_nop 0
	buffer_load_dwordx4 v131, s[48:51], s1 offen lds
	s_or_b32 s0, s0, 0xc0f80
	s_mov_b32 m0, s25
	s_nop 0
	buffer_load_dwordx4 v131, s[48:51], s0 offen lds
	s_barrier
	s_waitcnt lgkmcnt(0)
	s_setprio 1
	v_mfma_f32_16x16x32_bf16 v[124:127], v[170:173], v[154:157], v[124:127]
	v_mfma_f32_16x16x32_bf16 v[120:123], v[170:173], v[162:165], v[120:123]
	v_mfma_f32_16x16x32_bf16 v[116:119], v[178:181], v[154:157], v[116:119]
	v_mfma_f32_16x16x32_bf16 v[112:115], v[178:181], v[162:165], v[112:115]
	v_mfma_f32_16x16x32_bf16 v[108:111], v[186:189], v[154:157], v[108:111]
	v_mfma_f32_16x16x32_bf16 v[104:107], v[186:189], v[162:165], v[104:107]
	v_mfma_f32_16x16x32_bf16 v[100:103], v[194:197], v[154:157], v[100:103]
	v_mfma_f32_16x16x32_bf16 v[96:99], v[194:197], v[162:165], v[96:99]
	v_mfma_f32_16x16x32_bf16 v[124:127], v[174:177], v[158:161], v[124:127]
	v_mfma_f32_16x16x32_bf16 v[120:123], v[174:177], v[166:169], v[120:123]
	v_mfma_f32_16x16x32_bf16 v[116:119], v[182:185], v[158:161], v[116:119]
	v_mfma_f32_16x16x32_bf16 v[112:115], v[182:185], v[166:169], v[112:115]
	v_mfma_f32_16x16x32_bf16 v[108:111], v[190:193], v[158:161], v[108:111]
	v_mfma_f32_16x16x32_bf16 v[104:107], v[190:193], v[166:169], v[104:107]
	v_mfma_f32_16x16x32_bf16 v[100:103], v[198:201], v[158:161], v[100:103]
	v_mfma_f32_16x16x32_bf16 v[96:99], v[198:201], v[166:169], v[96:99]
	s_setprio 0
	s_barrier
	ds_read_b128 v[202:205], v150
	ds_read_b128 v[206:209], v150 offset:1024
	ds_read_b128 v[210:213], v150 offset:2048
	ds_read_b128 v[214:217], v150 offset:3072
	s_barrier
	s_waitcnt lgkmcnt(0)
	s_setprio 1
	v_mfma_f32_16x16x32_bf16 v[92:95], v[170:173], v[202:205], v[92:95]
	v_mfma_f32_16x16x32_bf16 v[88:91], v[170:173], v[210:213], v[88:91]
	v_mfma_f32_16x16x32_bf16 v[76:79], v[186:189], v[202:205], v[76:79]
	v_mfma_f32_16x16x32_bf16 v[72:75], v[186:189], v[210:213], v[72:75]
	v_mfma_f32_16x16x32_bf16 v[68:71], v[194:197], v[202:205], v[68:71]
	v_mfma_f32_16x16x32_bf16 v[64:67], v[194:197], v[210:213], v[64:67]
	v_mfma_f32_16x16x32_bf16 v[84:87], v[178:181], v[202:205], v[84:87]
	v_mfma_f32_16x16x32_bf16 v[80:83], v[178:181], v[210:213], v[80:83]
	v_mfma_f32_16x16x32_bf16 v[92:95], v[174:177], v[206:209], v[92:95]
	v_mfma_f32_16x16x32_bf16 v[88:91], v[174:177], v[214:217], v[88:91]
	v_mfma_f32_16x16x32_bf16 v[76:79], v[190:193], v[206:209], v[76:79]
	v_mfma_f32_16x16x32_bf16 v[72:75], v[190:193], v[214:217], v[72:75]
	v_mfma_f32_16x16x32_bf16 v[68:71], v[198:201], v[206:209], v[68:71]
	v_mfma_f32_16x16x32_bf16 v[64:67], v[198:201], v[214:217], v[64:67]
	v_mfma_f32_16x16x32_bf16 v[170:173], v[182:185], v[206:209], v[84:87]
	v_mfma_f32_16x16x32_bf16 v[174:177], v[182:185], v[214:217], v[80:83]
	s_setprio 0
	s_barrier
	s_nop 0
	ds_read_b128 v[80:83], v146 offset:16384
	ds_read_b128 v[84:87], v146 offset:17408
	ds_read_b128 v[178:181], v147 offset:16384
	ds_read_b128 v[182:185], v147 offset:17408
	ds_read_b128 v[186:189], v148 offset:16384
	ds_read_b128 v[190:193], v148 offset:17408
	ds_read_b128 v[194:197], v149 offset:16384
	ds_read_b128 v[198:201], v149 offset:17408
	s_waitcnt vmcnt(4)
	s_barrier
	s_waitcnt lgkmcnt(0)
	s_setprio 1
	v_mfma_f32_16x16x32_bf16 v[52:55], v[178:181], v[154:157], v[52:55]
	v_mfma_f32_16x16x32_bf16 v[48:51], v[178:181], v[162:165], v[48:51]
	v_mfma_f32_16x16x32_bf16 v[44:47], v[186:189], v[154:157], v[44:47]
	v_mfma_f32_16x16x32_bf16 v[40:43], v[186:189], v[162:165], v[40:43]
	v_mfma_f32_16x16x32_bf16 v[36:39], v[194:197], v[154:157], v[36:39]
	v_mfma_f32_16x16x32_bf16 v[32:35], v[194:197], v[162:165], v[32:35]
	v_mfma_f32_16x16x32_bf16 v[60:63], v[80:83], v[154:157], v[60:63]
	v_mfma_f32_16x16x32_bf16 v[56:59], v[80:83], v[162:165], v[56:59]
	v_mfma_f32_16x16x32_bf16 v[52:55], v[182:185], v[158:161], v[52:55]
	v_mfma_f32_16x16x32_bf16 v[48:51], v[182:185], v[166:169], v[48:51]
	v_mfma_f32_16x16x32_bf16 v[44:47], v[190:193], v[158:161], v[44:47]
	v_mfma_f32_16x16x32_bf16 v[40:43], v[190:193], v[166:169], v[40:43]
	v_mfma_f32_16x16x32_bf16 v[36:39], v[198:201], v[158:161], v[36:39]
	v_mfma_f32_16x16x32_bf16 v[32:35], v[198:201], v[166:169], v[32:35]
	v_mfma_f32_16x16x32_bf16 v[154:157], v[84:87], v[158:161], v[60:63]
	v_mfma_f32_16x16x32_bf16 v[162:165], v[84:87], v[166:169], v[56:59]
	s_setprio 0
	s_setprio 1
	v_mfma_f32_16x16x32_bf16 v[28:31], v[80:83], v[202:205], v[28:31]
	v_mfma_f32_16x16x32_bf16 v[24:27], v[80:83], v[210:213], v[24:27]
	v_mfma_f32_16x16x32_bf16 v[12:15], v[186:189], v[202:205], v[12:15]
	v_mfma_f32_16x16x32_bf16 v[8:11], v[186:189], v[210:213], v[8:11]
	v_mfma_f32_16x16x32_bf16 v[20:23], v[178:181], v[202:205], v[20:23]
	v_mfma_f32_16x16x32_bf16 v[16:19], v[178:181], v[210:213], v[16:19]
	v_mfma_f32_16x16x32_bf16 v[4:7], v[194:197], v[202:205], v[4:7]
	v_mfma_f32_16x16x32_bf16 v[0:3], v[194:197], v[210:213], v[0:3]
	v_mfma_f32_16x16x32_bf16 v[28:31], v[84:87], v[206:209], v[28:31]
	v_mfma_f32_16x16x32_bf16 v[24:27], v[84:87], v[214:217], v[24:27]
	v_mfma_f32_16x16x32_bf16 v[12:15], v[190:193], v[206:209], v[12:15]
	v_mfma_f32_16x16x32_bf16 v[8:11], v[190:193], v[214:217], v[8:11]
	v_mfma_f32_16x16x32_bf16 v[158:161], v[182:185], v[206:209], v[20:23]
	v_mfma_f32_16x16x32_bf16 v[166:169], v[182:185], v[214:217], v[16:19]
	v_mfma_f32_16x16x32_bf16 v[178:181], v[198:201], v[206:209], v[4:7]
	v_mfma_f32_16x16x32_bf16 v[182:185], v[198:201], v[214:217], v[0:3]
	s_setprio 0
	s_barrier
; #define LDA(dst, b, h) _Pragma("unroll") for (int m = 0; m < 4; ++m) _Pragma("unroll") for (int k = 0; k < 2; ++k) \
;     dst[m][k] = *reinterpret_cast<const bf16x8*>((char*)SA(b, h) + lds_byte(wr * 64 + m * 16 + fr, k * 32 + fq * 8))
; #define LDB(dst, b, h) _Pragma("unroll") for (int n = 0; n < 2; ++n) _Pragma("unroll") for (int k = 0; k < 2; ++k) \
;     dst[n][k] = *reinterpret_cast<const bf16x8*>((char*)SB(b, h) + lds_byte(wc * 32 + n * 16 + fr, k * 32 + fq * 8))
; #define MMA(ai, bj, At_, Bt_) do { __builtin_amdgcn_s_setprio(1); \
;     _Pragma("unroll") for (int k = 0; k < 2; ++k) _Pragma("unroll") for (int m = 0; m < 4; ++m) _Pragma("unroll") for (int n = 0; n < 2; ++n) \
;       acc[ai][bj][m][n] = __builtin_amdgcn_mfma_f32_16x16x32_bf16(At_[m][k], Bt_[n][k], acc[ai][bj][m][n], 0, 0, 0); \
;     __builtin_amdgcn_s_setprio(0); } while (0)
; #define WAIT_V(n) asm volatile("s_waitcnt vmcnt(" #n ")" ::: "memory")
; #define BAR __builtin_amdgcn_s_barrier()
; template <int EPI, int N, int K>
; __device__ __forceinline__ void gemm_phase(const bf16_t* __restrict__ A, const bf16_t* __restrict__ Bt, const EpiArgs ea) {
;     ...
;     { LDB(B0, 1, 0); LDA(At, 1, 0); WAIT_V(2); BAR; WAIT_L(0); MMA(0, 0, At, B0); BAR;
;       LDB(B1, 1, 1); WAIT_V(0); BAR; WAIT_L(0); MMA(0, 1, At, B1); BAR;
;       LDA(At, 1, 1); BAR; WAIT_L(0); MMA(1, 0, At, B0); MMA(1, 1, At, B1); BAR; }
;     if (wr == 0) BAR;
	s_nop 0
	ds_read_b128 v[0:3], v151
	ds_read_b128 v[4:7], v151 offset:1024
	ds_read_b128 v[16:19], v151 offset:2048
	ds_read_b128 v[186:189], v151 offset:3072
	ds_read_b128 v[20:23], v146 offset:32768
	ds_read_b128 v[190:193], v146 offset:33792
	ds_read_b128 v[194:197], v147 offset:32768
	ds_read_b128 v[198:201], v147 offset:33792
	ds_read_b128 v[202:205], v148 offset:32768
	ds_read_b128 v[206:209], v148 offset:33792
	ds_read_b128 v[210:213], v149 offset:32768
	ds_read_b128 v[214:217], v149 offset:33792
	s_waitcnt vmcnt(2)
	s_barrier
	s_waitcnt lgkmcnt(0)
	s_setprio 1
	v_mfma_f32_16x16x32_bf16 v[56:59], v[20:23], v[0:3], v[124:127]
	v_mfma_f32_16x16x32_bf16 v[60:63], v[20:23], v[16:19], v[120:123]
	v_mfma_f32_16x16x32_bf16 v[80:83], v[194:197], v[0:3], v[116:119]
	v_mfma_f32_16x16x32_bf16 v[84:87], v[194:197], v[16:19], v[112:115]
	v_mfma_f32_16x16x32_bf16 v[108:111], v[202:205], v[0:3], v[108:111]
	v_mfma_f32_16x16x32_bf16 v[104:107], v[202:205], v[16:19], v[104:107]
	v_mfma_f32_16x16x32_bf16 v[120:123], v[210:213], v[0:3], v[100:103]
	v_mfma_f32_16x16x32_bf16 v[124:127], v[210:213], v[16:19], v[96:99]
	v_mfma_f32_16x16x32_bf16 v[116:119], v[190:193], v[4:7], v[56:59]
	v_mfma_f32_16x16x32_bf16 v[112:115], v[190:193], v[186:189], v[60:63]
	v_mfma_f32_16x16x32_bf16 v[100:103], v[198:201], v[4:7], v[80:83]
	v_mfma_f32_16x16x32_bf16 v[96:99], v[198:201], v[186:189], v[84:87]
	v_mfma_f32_16x16x32_bf16 v[84:87], v[206:209], v[4:7], v[108:111]
	v_mfma_f32_16x16x32_bf16 v[80:83], v[206:209], v[186:189], v[104:107]
	v_mfma_f32_16x16x32_bf16 v[60:63], v[214:217], v[4:7], v[120:123]
	v_mfma_f32_16x16x32_bf16 v[56:59], v[214:217], v[186:189], v[124:127]
	s_setprio 0
	s_barrier
	ds_read_b128 v[218:221], v152
	ds_read_b128 v[222:225], v152 offset:1024
	ds_read_b128 v[226:229], v152 offset:2048
	ds_read_b128 v[230:233], v152 offset:3072
	s_waitcnt vmcnt(0)
	s_barrier
	s_waitcnt lgkmcnt(0)
	s_setprio 1
	v_mfma_f32_16x16x32_bf16 v[92:95], v[20:23], v[218:221], v[92:95]
	v_mfma_f32_16x16x32_bf16 v[20:23], v[20:23], v[226:229], v[88:91]
	v_mfma_f32_16x16x32_bf16 v[88:91], v[194:197], v[218:221], v[170:173]
	v_mfma_f32_16x16x32_bf16 v[104:107], v[194:197], v[226:229], v[174:177]
	v_mfma_f32_16x16x32_bf16 v[76:79], v[202:205], v[218:221], v[76:79]
	v_mfma_f32_16x16x32_bf16 v[72:75], v[202:205], v[226:229], v[72:75]
	v_mfma_f32_16x16x32_bf16 v[68:71], v[210:213], v[218:221], v[68:71]
	v_mfma_f32_16x16x32_bf16 v[64:67], v[210:213], v[226:229], v[64:67]
	v_mfma_f32_16x16x32_bf16 v[124:127], v[190:193], v[222:225], v[92:95]
	v_mfma_f32_16x16x32_bf16 v[120:123], v[190:193], v[230:233], v[20:23]
	v_mfma_f32_16x16x32_bf16 v[108:111], v[198:201], v[222:225], v[88:91]
	v_mfma_f32_16x16x32_bf16 v[104:107], v[198:201], v[230:233], v[104:107]
	v_mfma_f32_16x16x32_bf16 v[92:95], v[206:209], v[222:225], v[76:79]
	v_mfma_f32_16x16x32_bf16 v[88:91], v[206:209], v[230:233], v[72:75]
	v_mfma_f32_16x16x32_bf16 v[76:79], v[214:217], v[222:225], v[68:71]
	v_mfma_f32_16x16x32_bf16 v[72:75], v[214:217], v[230:233], v[64:67]
	s_setprio 0
	s_barrier
	s_nop 0
	ds_read_b128 v[64:67], v146 offset:49152
	ds_read_b128 v[170:173], v146 offset:50176
	ds_read_b128 v[68:71], v147 offset:49152
	ds_read_b128 v[174:177], v147 offset:50176
	ds_read_b128 v[190:193], v148 offset:49152
	ds_read_b128 v[194:197], v148 offset:50176
	ds_read_b128 v[198:201], v149 offset:49152
	ds_read_b128 v[202:205], v149 offset:50176
	s_barrier
	s_waitcnt lgkmcnt(0)
	s_setprio 1
	v_mfma_f32_16x16x32_bf16 v[20:23], v[64:67], v[0:3], v[154:157]
	v_mfma_f32_16x16x32_bf16 v[154:157], v[64:67], v[16:19], v[162:165]
	v_mfma_f32_16x16x32_bf16 v[162:165], v[68:71], v[0:3], v[52:55]
	v_mfma_f32_16x16x32_bf16 v[206:209], v[68:71], v[16:19], v[48:51]
	v_mfma_f32_16x16x32_bf16 v[44:47], v[190:193], v[0:3], v[44:47]
	v_mfma_f32_16x16x32_bf16 v[40:43], v[190:193], v[16:19], v[40:43]
	v_mfma_f32_16x16x32_bf16 v[0:3], v[198:201], v[0:3], v[36:39]
	v_mfma_f32_16x16x32_bf16 v[210:213], v[198:201], v[16:19], v[32:35]
	v_mfma_f32_16x16x32_bf16 v[52:55], v[170:173], v[4:7], v[20:23]
	v_mfma_f32_16x16x32_bf16 v[48:51], v[170:173], v[186:189], v[154:157]
	v_mfma_f32_16x16x32_bf16 v[36:39], v[174:177], v[4:7], v[162:165]
	v_mfma_f32_16x16x32_bf16 v[32:35], v[174:177], v[186:189], v[206:209]
	v_mfma_f32_16x16x32_bf16 v[20:23], v[194:197], v[4:7], v[44:47]
	v_mfma_f32_16x16x32_bf16 v[16:19], v[194:197], v[186:189], v[40:43]
	v_mfma_f32_16x16x32_bf16 v[4:7], v[202:205], v[4:7], v[0:3]
	v_mfma_f32_16x16x32_bf16 v[0:3], v[202:205], v[186:189], v[210:213]
	s_setprio 0
	s_setprio 1
	v_mfma_f32_16x16x32_bf16 v[28:31], v[64:67], v[218:221], v[28:31]
	v_mfma_f32_16x16x32_bf16 v[24:27], v[64:67], v[226:229], v[24:27]
	v_mfma_f32_16x16x32_bf16 v[40:43], v[68:71], v[218:221], v[158:161]
	v_mfma_f32_16x16x32_bf16 v[154:157], v[68:71], v[226:229], v[166:169]
	v_mfma_f32_16x16x32_bf16 v[12:15], v[190:193], v[218:221], v[12:15]
	v_mfma_f32_16x16x32_bf16 v[8:11], v[190:193], v[226:229], v[8:11]
	v_mfma_f32_16x16x32_bf16 v[158:161], v[198:201], v[218:221], v[178:181]
	v_mfma_f32_16x16x32_bf16 v[162:165], v[198:201], v[226:229], v[182:185]
	v_mfma_f32_16x16x32_bf16 v[68:71], v[170:173], v[222:225], v[28:31]
	v_mfma_f32_16x16x32_bf16 v[64:67], v[170:173], v[230:233], v[24:27]
	v_mfma_f32_16x16x32_bf16 v[44:47], v[174:177], v[222:225], v[40:43]
	v_mfma_f32_16x16x32_bf16 v[40:43], v[174:177], v[230:233], v[154:157]
	v_mfma_f32_16x16x32_bf16 v[28:31], v[194:197], v[222:225], v[12:15]
	v_mfma_f32_16x16x32_bf16 v[24:27], v[194:197], v[230:233], v[8:11]
	v_mfma_f32_16x16x32_bf16 v[12:15], v[202:205], v[222:225], v[158:161]
	v_mfma_f32_16x16x32_bf16 v[8:11], v[202:205], v[230:233], v[162:165]
	s_setprio 0
	s_barrier
	s_and_saveexec_b64 s[0:1], s[6:7]
	s_cbranch_execz .LBB0_273
	s_barrier

; #define STAGE_A(POFF, h, kt) STAGE_AX(POFF, h, kt, brow)
; #define LDA(dst, b, h) _Pragma("unroll") for (int m = 0; m < 4; ++m) _Pragma("unroll") for (int k = 0; k < 2; ++k) \
;     dst[m][k] = *reinterpret_cast<const bf16x8*>((char*)SA(b, h) + lds_byte(wr * 64 + m * 16 + fr, k * 32 + fq * 8))
; #define LDB(dst, b, h) _Pragma("unroll") for (int n = 0; n < 2; ++n) _Pragma("unroll") for (int k = 0; k < 2; ++k) \
;     dst[n][k] = *reinterpret_cast<const bf16x8*>((char*)SB(b, h) + lds_byte(wc * 32 + n * 16 + fr, k * 32 + fq * 8))
; #define MMA(ai, bj, At_, Bt_) do { __builtin_amdgcn_s_setprio(1); \
;     _Pragma("unroll") for (int k = 0; k < 2; ++k) _Pragma("unroll") for (int m = 0; m < 4; ++m) _Pragma("unroll") for (int n = 0; n < 2; ++n) \
;       acc[ai][bj][m][n] = __builtin_amdgcn_mfma_f32_16x16x32_bf16(At_[m][k], Bt_[n][k], acc[ai][bj][m][n], 0, 0, 0); \
;     __builtin_amdgcn_s_setprio(0); } while (0)
; #define WAIT_V(n) asm volatile("s_waitcnt vmcnt(" #n ")" ::: "memory")
; #define BAR __builtin_amdgcn_s_barrier()
; #define SCHED __builtin_amdgcn_sched_barrier(0)
; #define TILE_RC(w_, brow_, bcol_) do { const int wg_ = ((w_) & 7) * qx + ((w_) >> 3); const int gid_ = wg_ / nig; \
;     brow_ = (gid_ * 8 + ((wg_ % nig) & 7)) * 256; bcol_ = ((wg_ % nig) >> 3) * 256; } while (0)
; template <int EPI, int N, int K>
; __device__ __forceinline__ void gemm_phase(const bf16_t* __restrict__ A, const bf16_t* __restrict__ Bt, const EpiArgs ea) {
;     ...
;     int brow, bcol; TILE_RC(w, brow, bcol);
;     f32x4 acc[2][2][4][2];
; #pragma unroll
;     for (int a = 0; a < 2; ++a)
; #pragma unroll
;       for (int b = 0; b < 2; ++b)
; #pragma unroll
;         for (int m = 0; m < 4; ++m)
; #pragma unroll
;           for (int n = 0; n < 2; ++n) acc[a][b][m][n] = (f32x4){0.f, 0.f, 0.f, 0.f};
;     bf16x8 At[4][2], B0[2][2], B1[2][2];
;     if (wr == 1) BAR;
;     if (w == (int)blockIdx.x) { WAIT_V(0); } else { WAIT_V(24); }
;     BAR;
;     BAR;
;     for (int t = 0; t < nt - 2; t += 2) {
;       LDB(B0, 0, 0); SCHED; LDA(At, 0, 0); STAGE_A(SA_OFF(1, 1), 1, t + 1);
;       WAIT_L(8); BAR; WAIT_L(0); MMA(0, 0, At, B0); BAR; SCHED;
.LBB0_389:
	s_lshl_b32 s2, s30, 6
	s_and_b32 s2, s2, 0x1c0
	s_ashr_i32 s3, s30, 3
	s_add_i32 s3, s2, s3
	s_ashr_i32 s2, s3, 31
	s_lshr_b32 s2, s2, 26
	s_add_i32 s12, s3, s2
	s_ashr_i32 s2, s12, 6
	s_andn2_b32 s12, s12, 63
	s_sub_i32 s31, s3, s12
	s_lshl_b32 s3, s31, 8
	s_lshl_b32 s12, s31, 5
	s_lshl_b32 s13, s31, 17
	s_and_b32 s31, s31, 7
	s_lshl_b32 s34, s2, 23
	s_lshl_b32 s31, s31, 20
	v_mov_b32_e32 v0, 0
	s_and_b32 s13, s13, 0xfff00000
	s_or_b32 s31, s34, s31
	s_mov_b32 s34, -2
	s_mov_b32 s35, 0
	v_mov_b32_e32 v1, v0
	v_mov_b32_e32 v2, v0
	v_mov_b32_e32 v3, v0
	v_mov_b32_e32 v4, v0
	v_mov_b32_e32 v5, v0
	v_mov_b32_e32 v6, v0
	v_mov_b32_e32 v7, v0
	v_mov_b32_e32 v8, v0
	v_mov_b32_e32 v9, v0
	v_mov_b32_e32 v10, v0
	v_mov_b32_e32 v11, v0
	v_mov_b32_e32 v12, v0
	v_mov_b32_e32 v13, v0
	v_mov_b32_e32 v14, v0
	v_mov_b32_e32 v15, v0
	v_mov_b32_e32 v16, v0
	v_mov_b32_e32 v17, v0
	v_mov_b32_e32 v18, v0
	v_mov_b32_e32 v19, v0
	v_mov_b32_e32 v20, v0
	v_mov_b32_e32 v21, v0
	v_mov_b32_e32 v22, v0
	v_mov_b32_e32 v23, v0
	v_mov_b32_e32 v24, v0
	v_mov_b32_e32 v25, v0
	v_mov_b32_e32 v26, v0
	v_mov_b32_e32 v27, v0
	v_mov_b32_e32 v28, v0
	v_mov_b32_e32 v29, v0
	v_mov_b32_e32 v30, v0
	v_mov_b32_e32 v31, v0
	v_mov_b32_e32 v32, v0
	v_mov_b32_e32 v33, v0
	v_mov_b32_e32 v34, v0
	v_mov_b32_e32 v35, v0
	v_mov_b32_e32 v36, v0
	v_mov_b32_e32 v37, v0
	v_mov_b32_e32 v38, v0
	v_mov_b32_e32 v39, v0
	v_mov_b32_e32 v40, v0
	v_mov_b32_e32 v41, v0
	v_mov_b32_e32 v42, v0
	v_mov_b32_e32 v43, v0
	v_mov_b32_e32 v44, v0
	v_mov_b32_e32 v45, v0
	v_mov_b32_e32 v46, v0
	v_mov_b32_e32 v47, v0
	v_mov_b32_e32 v48, v0
	v_mov_b32_e32 v49, v0
	v_mov_b32_e32 v50, v0
	v_mov_b32_e32 v51, v0
	v_mov_b32_e32 v52, v0
	v_mov_b32_e32 v53, v0
	v_mov_b32_e32 v54, v0
	v_mov_b32_e32 v55, v0
	v_mov_b32_e32 v56, v0
	v_mov_b32_e32 v57, v0
	v_mov_b32_e32 v58, v0
	v_mov_b32_e32 v59, v0
	v_mov_b32_e32 v60, v0
	v_mov_b32_e32 v61, v0
	v_mov_b32_e32 v62, v0
	v_mov_b32_e32 v63, v0
	v_mov_b32_e32 v64, v0
	v_mov_b32_e32 v65, v0
	v_mov_b32_e32 v66, v0
	v_mov_b32_e32 v67, v0
	v_mov_b32_e32 v68, v0
	v_mov_b32_e32 v69, v0
	v_mov_b32_e32 v70, v0
	v_mov_b32_e32 v71, v0
	v_mov_b32_e32 v72, v0
	v_mov_b32_e32 v73, v0
	v_mov_b32_e32 v74, v0
	v_mov_b32_e32 v75, v0
	v_mov_b32_e32 v76, v0
	v_mov_b32_e32 v77, v0
	v_mov_b32_e32 v78, v0
	v_mov_b32_e32 v79, v0
	v_mov_b32_e32 v80, v0
	v_mov_b32_e32 v81, v0
	v_mov_b32_e32 v82, v0
	v_mov_b32_e32 v83, v0
	v_mov_b32_e32 v84, v0
	v_mov_b32_e32 v85, v0
	v_mov_b32_e32 v86, v0
	v_mov_b32_e32 v87, v0
	v_mov_b32_e32 v88, v0
	v_mov_b32_e32 v89, v0
	v_mov_b32_e32 v90, v0
	v_mov_b32_e32 v91, v0
	v_mov_b32_e32 v92, v0
	v_mov_b32_e32 v93, v0
	v_mov_b32_e32 v94, v0
	v_mov_b32_e32 v95, v0
	v_mov_b32_e32 v96, v0
	v_mov_b32_e32 v97, v0
	v_mov_b32_e32 v98, v0
	v_mov_b32_e32 v99, v0
	v_mov_b32_e32 v100, v0
	v_mov_b32_e32 v101, v0
	v_mov_b32_e32 v102, v0
	v_mov_b32_e32 v103, v0
	v_mov_b32_e32 v104, v0
	v_mov_b32_e32 v105, v0
	v_mov_b32_e32 v106, v0
	v_mov_b32_e32 v107, v0
	v_mov_b32_e32 v108, v0
	v_mov_b32_e32 v109, v0
	v_mov_b32_e32 v110, v0
	v_mov_b32_e32 v111, v0
	v_mov_b32_e32 v112, v0
	v_mov_b32_e32 v113, v0
	v_mov_b32_e32 v114, v0
	v_mov_b32_e32 v115, v0
	v_mov_b32_e32 v116, v0
	v_mov_b32_e32 v117, v0
	v_mov_b32_e32 v118, v0
	v_mov_b32_e32 v119, v0
	v_mov_b32_e32 v120, v0
	v_mov_b32_e32 v121, v0
	v_mov_b32_e32 v122, v0
	v_mov_b32_e32 v123, v0
	v_mov_b32_e32 v124, v0
	v_mov_b32_e32 v125, v0
	v_mov_b32_e32 v126, v0
	v_mov_b32_e32 v127, v0
	s_barrier
	s_barrier
	ds_read_b128 v[132:135], v147
	ds_read_b128 v[156:159], v147 offset:1024
	ds_read_b128 v[160:163], v147 offset:2048
	ds_read_b128 v[164:167], v147 offset:3072
.LBB0_390:
	ds_read_b128 v[168:171], v148
	ds_read_b128 v[172:175], v148 offset:1024
	ds_read_b128 v[176:179], v149
	ds_read_b128 v[180:183], v149 offset:1024
	ds_read_b128 v[184:187], v150
	ds_read_b128 v[188:191], v150 offset:1024
	ds_read_b128 v[192:195], v151
	ds_read_b128 v[196:199], v151 offset:1024
	s_add_i32 s36, s31, s35
	s_or_b32 s37, s36, 0x80080
	s_mov_b32 s62, s50
	s_mov_b32 s63, s51
	s_mov_b32 m0, s28
	s_nop 0
	buffer_load_dwordx4 v131, s[60:63], s37 offen lds
	s_or_b32 s37, s36, 0xc0080
	s_mov_b32 m0, s29
	s_nop 0
	buffer_load_dwordx4 v131, s[60:63], s37 offen lds
	s_waitcnt lgkmcnt(8)
	s_barrier
	s_waitcnt lgkmcnt(0)
	s_setprio 1
	v_mfma_f32_16x16x32_bf16 v[124:127], v[168:171], v[132:135], v[124:127]
	v_mfma_f32_16x16x32_bf16 v[120:123], v[168:171], v[160:163], v[120:123]
	v_mfma_f32_16x16x32_bf16 v[116:119], v[176:179], v[132:135], v[116:119]
	v_mfma_f32_16x16x32_bf16 v[112:115], v[176:179], v[160:163], v[112:115]
	v_mfma_f32_16x16x32_bf16 v[108:111], v[184:187], v[132:135], v[108:111]
	v_mfma_f32_16x16x32_bf16 v[104:107], v[184:187], v[160:163], v[104:107]
	v_mfma_f32_16x16x32_bf16 v[100:103], v[192:195], v[132:135], v[100:103]
	v_mfma_f32_16x16x32_bf16 v[96:99], v[192:195], v[160:163], v[96:99]
	v_mfma_f32_16x16x32_bf16 v[124:127], v[172:175], v[156:159], v[124:127]
	v_mfma_f32_16x16x32_bf16 v[120:123], v[172:175], v[164:167], v[120:123]
	v_mfma_f32_16x16x32_bf16 v[116:119], v[180:183], v[156:159], v[116:119]
	v_mfma_f32_16x16x32_bf16 v[112:115], v[180:183], v[164:167], v[112:115]
	v_mfma_f32_16x16x32_bf16 v[108:111], v[188:191], v[156:159], v[108:111]
	v_mfma_f32_16x16x32_bf16 v[104:107], v[188:191], v[164:167], v[104:107]
	v_mfma_f32_16x16x32_bf16 v[100:103], v[196:199], v[156:159], v[100:103]
	v_mfma_f32_16x16x32_bf16 v[96:99], v[196:199], v[164:167], v[96:99]
	s_setprio 0
	s_barrier
; #define STAGE_A(POFF, h, kt) STAGE_AX(POFF, h, kt, brow)
; #define STAGE_B(POFF, h, kt) STAGE_BX(POFF, h, kt, bcol)
; #define LDA(dst, b, h) _Pragma("unroll") for (int m = 0; m < 4; ++m) _Pragma("unroll") for (int k = 0; k < 2; ++k) \
;     dst[m][k] = *reinterpret_cast<const bf16x8*>((char*)SA(b, h) + lds_byte(wr * 64 + m * 16 + fr, k * 32 + fq * 8))
; #define LDB(dst, b, h) _Pragma("unroll") for (int n = 0; n < 2; ++n) _Pragma("unroll") for (int k = 0; k < 2; ++k) \
;     dst[n][k] = *reinterpret_cast<const bf16x8*>((char*)SB(b, h) + lds_byte(wc * 32 + n * 16 + fr, k * 32 + fq * 8))
; #define MMA(ai, bj, At_, Bt_) do { __builtin_amdgcn_s_setprio(1); \
;     _Pragma("unroll") for (int k = 0; k < 2; ++k) _Pragma("unroll") for (int m = 0; m < 4; ++m) _Pragma("unroll") for (int n = 0; n < 2; ++n) \
;       acc[ai][bj][m][n] = __builtin_amdgcn_mfma_f32_16x16x32_bf16(At_[m][k], Bt_[n][k], acc[ai][bj][m][n], 0, 0, 0); \
;     __builtin_amdgcn_s_setprio(0); } while (0)
; #define WAIT_V(n) asm volatile("s_waitcnt vmcnt(" #n ")" ::: "memory")
; #define BAR __builtin_amdgcn_s_barrier()
; #define SCHED __builtin_amdgcn_sched_barrier(0)
; template <int EPI, int N, int K>
; __device__ __forceinline__ void gemm_phase(const bf16_t* __restrict__ A, const bf16_t* __restrict__ Bt, const EpiArgs ea) {
;     ...
;       LDB(B1, 0, 1); STAGE_B(SB_OFF(0, 0), 0, t + 2);
;       BAR; WAIT_L(0); MMA(0, 1, At, B1); BAR;
;       LDA(At, 0, 1); STAGE_A(SA_OFF(0, 0), 0, t + 2);
;       BAR; WAIT_L(0); MMA(1, 0, At, B0); BAR; SCHED;
;       STAGE_B(SB_OFF(0, 1), 1, t + 2);
;       WAIT_V(6); BAR; MMA(1, 1, At, B1); BAR;
;       LDB(B0, 1, 0); SCHED; LDA(At, 1, 0); STAGE_A(SA_OFF(0, 1), 1, t + 2);
;       WAIT_L(8); BAR; WAIT_L(0); MMA(0, 0, At, B0); BAR; SCHED;
	ds_read_b128 v[200:203], v152
	ds_read_b128 v[204:207], v152 offset:1024
	ds_read_b128 v[208:211], v152 offset:2048
	ds_read_b128 v[212:215], v152 offset:3072
	s_add_i32 s37, s13, s35
	s_add_i32 s38, s37, 0x100
	s_mov_b32 m0, s15
	s_nop 0
	buffer_load_dwordx4 v144, s[76:79], s38 offen lds
	s_add_i32 s38, s37, 0x80100
	s_mov_b32 m0, s16
	s_nop 0
	buffer_load_dwordx4 v144, s[76:79], s38 offen lds
	s_barrier
	s_waitcnt lgkmcnt(0)
	s_setprio 1
	v_mfma_f32_16x16x32_bf16 v[92:95], v[168:171], v[200:203], v[92:95]
	v_mfma_f32_16x16x32_bf16 v[88:91], v[168:171], v[208:211], v[88:91]
	v_mfma_f32_16x16x32_bf16 v[84:87], v[176:179], v[200:203], v[84:87]
	v_mfma_f32_16x16x32_bf16 v[80:83], v[176:179], v[208:211], v[80:83]
	v_mfma_f32_16x16x32_bf16 v[76:79], v[184:187], v[200:203], v[76:79]
	v_mfma_f32_16x16x32_bf16 v[72:75], v[184:187], v[208:211], v[72:75]
	v_mfma_f32_16x16x32_bf16 v[68:71], v[192:195], v[200:203], v[68:71]
	v_mfma_f32_16x16x32_bf16 v[64:67], v[192:195], v[208:211], v[64:67]
	v_mfma_f32_16x16x32_bf16 v[92:95], v[172:175], v[204:207], v[92:95]
	v_mfma_f32_16x16x32_bf16 v[88:91], v[172:175], v[212:215], v[88:91]
	v_mfma_f32_16x16x32_bf16 v[84:87], v[180:183], v[204:207], v[84:87]
	v_mfma_f32_16x16x32_bf16 v[80:83], v[180:183], v[212:215], v[80:83]
	v_mfma_f32_16x16x32_bf16 v[76:79], v[188:191], v[204:207], v[76:79]
	v_mfma_f32_16x16x32_bf16 v[72:75], v[188:191], v[212:215], v[72:75]
	v_mfma_f32_16x16x32_bf16 v[68:71], v[196:199], v[204:207], v[68:71]
	v_mfma_f32_16x16x32_bf16 v[64:67], v[196:199], v[212:215], v[64:67]
	s_setprio 0
	s_barrier
	ds_read_b128 v[168:171], v148 offset:16384
	ds_read_b128 v[172:175], v148 offset:17408
	ds_read_b128 v[176:179], v149 offset:16384
	ds_read_b128 v[180:183], v149 offset:17408
	ds_read_b128 v[184:187], v150 offset:16384
	ds_read_b128 v[188:191], v150 offset:17408
	ds_read_b128 v[192:195], v151 offset:16384
	ds_read_b128 v[196:199], v151 offset:17408
	s_add_i32 s38, s36, 0x100
	s_mov_b32 m0, s14
	s_nop 0
	buffer_load_dwordx4 v131, s[60:63], s38 offen lds
	s_add_i32 s39, s36, 0x40100
	s_mov_b32 m0, s17
	s_nop 0
	buffer_load_dwordx4 v131, s[60:63], s39 offen lds
	s_waitcnt vmcnt(10)
	s_barrier
	s_waitcnt lgkmcnt(0)
	s_setprio 1
	v_mfma_f32_16x16x32_bf16 v[60:63], v[168:171], v[132:135], v[60:63]
	v_mfma_f32_16x16x32_bf16 v[56:59], v[168:171], v[160:163], v[56:59]
	v_mfma_f32_16x16x32_bf16 v[52:55], v[176:179], v[132:135], v[52:55]
	v_mfma_f32_16x16x32_bf16 v[48:51], v[176:179], v[160:163], v[48:51]
	v_mfma_f32_16x16x32_bf16 v[44:47], v[184:187], v[132:135], v[44:47]
	v_mfma_f32_16x16x32_bf16 v[40:43], v[184:187], v[160:163], v[40:43]
	v_mfma_f32_16x16x32_bf16 v[36:39], v[192:195], v[132:135], v[36:39]
	v_mfma_f32_16x16x32_bf16 v[32:35], v[192:195], v[160:163], v[32:35]
	v_mfma_f32_16x16x32_bf16 v[60:63], v[172:175], v[156:159], v[60:63]
	v_mfma_f32_16x16x32_bf16 v[56:59], v[172:175], v[164:167], v[56:59]
	v_mfma_f32_16x16x32_bf16 v[52:55], v[180:183], v[156:159], v[52:55]
	v_mfma_f32_16x16x32_bf16 v[48:51], v[180:183], v[164:167], v[48:51]
	v_mfma_f32_16x16x32_bf16 v[44:47], v[188:191], v[156:159], v[44:47]
	v_mfma_f32_16x16x32_bf16 v[40:43], v[188:191], v[164:167], v[40:43]
	v_mfma_f32_16x16x32_bf16 v[36:39], v[196:199], v[156:159], v[36:39]
	v_mfma_f32_16x16x32_bf16 v[32:35], v[196:199], v[164:167], v[32:35]
	s_setprio 0
	s_barrier
	ds_read_b128 v[132:135], v153
	ds_read_b128 v[156:159], v153 offset:1024
	ds_read_b128 v[160:163], v153 offset:2048
	ds_read_b128 v[164:167], v153 offset:3072
	s_add_i32 s39, s37, 0x2100
	s_mov_b32 m0, s18
	s_nop 0
	buffer_load_dwordx4 v144, s[76:79], s39 offen lds
	s_add_i32 s39, s37, 0x82100
	s_mov_b32 m0, s19
	s_nop 0
	buffer_load_dwordx4 v144, s[76:79], s39 offen lds
	s_waitcnt vmcnt(6)
	s_barrier
	s_setprio 1
	v_mfma_f32_16x16x32_bf16 v[28:31], v[168:171], v[200:203], v[28:31]
	v_mfma_f32_16x16x32_bf16 v[24:27], v[168:171], v[208:211], v[24:27]
	v_mfma_f32_16x16x32_bf16 v[20:23], v[176:179], v[200:203], v[20:23]
	v_mfma_f32_16x16x32_bf16 v[16:19], v[176:179], v[208:211], v[16:19]
	v_mfma_f32_16x16x32_bf16 v[12:15], v[184:187], v[200:203], v[12:15]
	v_mfma_f32_16x16x32_bf16 v[8:11], v[184:187], v[208:211], v[8:11]
	v_mfma_f32_16x16x32_bf16 v[4:7], v[192:195], v[200:203], v[4:7]
	v_mfma_f32_16x16x32_bf16 v[0:3], v[192:195], v[208:211], v[0:3]
	v_mfma_f32_16x16x32_bf16 v[28:31], v[172:175], v[204:207], v[28:31]
	v_mfma_f32_16x16x32_bf16 v[24:27], v[172:175], v[212:215], v[24:27]
	v_mfma_f32_16x16x32_bf16 v[20:23], v[180:183], v[204:207], v[20:23]
	v_mfma_f32_16x16x32_bf16 v[16:19], v[180:183], v[212:215], v[16:19]
	v_mfma_f32_16x16x32_bf16 v[12:15], v[188:191], v[204:207], v[12:15]
	v_mfma_f32_16x16x32_bf16 v[8:11], v[188:191], v[212:215], v[8:11]
	v_mfma_f32_16x16x32_bf16 v[4:7], v[196:199], v[204:207], v[4:7]
	v_mfma_f32_16x16x32_bf16 v[0:3], v[196:199], v[212:215], v[0:3]
	s_setprio 0
	s_barrier
	ds_read_b128 v[168:171], v148 offset:32768
	ds_read_b128 v[172:175], v148 offset:33792
	ds_read_b128 v[176:179], v149 offset:32768
	ds_read_b128 v[180:183], v149 offset:33792
	ds_read_b128 v[184:187], v150 offset:32768
	ds_read_b128 v[188:191], v150 offset:33792
	ds_read_b128 v[192:195], v151 offset:32768
	ds_read_b128 v[196:199], v151 offset:33792
	s_or_b32 s39, s38, 0x80000
	s_mov_b32 m0, s20
	s_nop 0
	buffer_load_dwordx4 v131, s[60:63], s39 offen lds
	s_or_b32 s38, s38, 0xc0000
	s_mov_b32 m0, s21
	s_nop 0
	buffer_load_dwordx4 v131, s[60:63], s38 offen lds
	s_waitcnt lgkmcnt(8)
	s_barrier
; #define STAGE_A(POFF, h, kt) STAGE_AX(POFF, h, kt, brow)
; #define STAGE_B(POFF, h, kt) STAGE_BX(POFF, h, kt, bcol)
; #define LDA(dst, b, h) _Pragma("unroll") for (int m = 0; m < 4; ++m) _Pragma("unroll") for (int k = 0; k < 2; ++k) \
;     dst[m][k] = *reinterpret_cast<const bf16x8*>((char*)SA(b, h) + lds_byte(wr * 64 + m * 16 + fr, k * 32 + fq * 8))
; #define LDB(dst, b, h) _Pragma("unroll") for (int n = 0; n < 2; ++n) _Pragma("unroll") for (int k = 0; k < 2; ++k) \
;     dst[n][k] = *reinterpret_cast<const bf16x8*>((char*)SB(b, h) + lds_byte(wc * 32 + n * 16 + fr, k * 32 + fq * 8))
; #define MMA(ai, bj, At_, Bt_) do { __builtin_amdgcn_s_setprio(1); \
;     _Pragma("unroll") for (int k = 0; k < 2; ++k) _Pragma("unroll") for (int m = 0; m < 4; ++m) _Pragma("unroll") for (int n = 0; n < 2; ++n) \
;       acc[ai][bj][m][n] = __builtin_amdgcn_mfma_f32_16x16x32_bf16(At_[m][k], Bt_[n][k], acc[ai][bj][m][n], 0, 0, 0); \
;     __builtin_amdgcn_s_setprio(0); } while (0)
; #define WAIT_V(n) asm volatile("s_waitcnt vmcnt(" #n ")" ::: "memory")
; #define BAR __builtin_amdgcn_s_barrier()
; #define SCHED __builtin_amdgcn_sched_barrier(0)
; template <int EPI, int N, int K>
; __device__ __forceinline__ void gemm_phase(const bf16_t* __restrict__ A, const bf16_t* __restrict__ Bt, const EpiArgs ea) {
;     ...
;       WAIT_L(8); BAR; WAIT_L(0); MMA(0, 0, At, B0); BAR; SCHED;
;       LDB(B1, 1, 1); STAGE_B(SB_OFF(1, 0), 0, t + 3);
;       BAR; WAIT_L(0); MMA(0, 1, At, B1); BAR;
;       LDA(At, 1, 1); STAGE_A(SA_OFF(1, 0), 0, t + 3);
;       BAR; WAIT_L(0); MMA(1, 0, At, B0); BAR; SCHED;
;       STAGE_B(SB_OFF(1, 1), 1, t + 3);
;       WAIT_V(6); BAR; MMA(1, 1, At, B1); BAR;
	s_waitcnt lgkmcnt(0)
	s_setprio 1
	v_mfma_f32_16x16x32_bf16 v[124:127], v[168:171], v[132:135], v[124:127]
	v_mfma_f32_16x16x32_bf16 v[120:123], v[168:171], v[160:163], v[120:123]
	v_mfma_f32_16x16x32_bf16 v[116:119], v[176:179], v[132:135], v[116:119]
	v_mfma_f32_16x16x32_bf16 v[112:115], v[176:179], v[160:163], v[112:115]
	v_mfma_f32_16x16x32_bf16 v[108:111], v[184:187], v[132:135], v[108:111]
	v_mfma_f32_16x16x32_bf16 v[104:107], v[184:187], v[160:163], v[104:107]
	v_mfma_f32_16x16x32_bf16 v[100:103], v[192:195], v[132:135], v[100:103]
	v_mfma_f32_16x16x32_bf16 v[96:99], v[192:195], v[160:163], v[96:99]
	v_mfma_f32_16x16x32_bf16 v[124:127], v[172:175], v[156:159], v[124:127]
	v_mfma_f32_16x16x32_bf16 v[120:123], v[172:175], v[164:167], v[120:123]
	v_mfma_f32_16x16x32_bf16 v[116:119], v[180:183], v[156:159], v[116:119]
	v_mfma_f32_16x16x32_bf16 v[112:115], v[180:183], v[164:167], v[112:115]
	v_mfma_f32_16x16x32_bf16 v[108:111], v[188:191], v[156:159], v[108:111]
	v_mfma_f32_16x16x32_bf16 v[104:107], v[188:191], v[164:167], v[104:107]
	v_mfma_f32_16x16x32_bf16 v[100:103], v[196:199], v[156:159], v[100:103]
	v_mfma_f32_16x16x32_bf16 v[96:99], v[196:199], v[164:167], v[96:99]
	s_setprio 0
	s_barrier
	ds_read_b128 v[200:203], v154
	ds_read_b128 v[204:207], v154 offset:1024
	ds_read_b128 v[208:211], v154 offset:2048
	ds_read_b128 v[212:215], v154 offset:3072
	s_add_i32 s38, s37, 0x180
	s_mov_b32 m0, s22
	s_nop 0
	buffer_load_dwordx4 v144, s[76:79], s38 offen lds
	s_add_i32 s38, s37, 0x80180
	s_mov_b32 m0, s23
	s_nop 0
	buffer_load_dwordx4 v144, s[76:79], s38 offen lds
	s_barrier
	s_waitcnt lgkmcnt(0)
	s_setprio 1
	v_mfma_f32_16x16x32_bf16 v[92:95], v[168:171], v[200:203], v[92:95]
	v_mfma_f32_16x16x32_bf16 v[88:91], v[168:171], v[208:211], v[88:91]
	v_mfma_f32_16x16x32_bf16 v[84:87], v[176:179], v[200:203], v[84:87]
	v_mfma_f32_16x16x32_bf16 v[80:83], v[176:179], v[208:211], v[80:83]
	v_mfma_f32_16x16x32_bf16 v[76:79], v[184:187], v[200:203], v[76:79]
	v_mfma_f32_16x16x32_bf16 v[72:75], v[184:187], v[208:211], v[72:75]
	v_mfma_f32_16x16x32_bf16 v[68:71], v[192:195], v[200:203], v[68:71]
	v_mfma_f32_16x16x32_bf16 v[64:67], v[192:195], v[208:211], v[64:67]
	v_mfma_f32_16x16x32_bf16 v[92:95], v[172:175], v[204:207], v[92:95]
	v_mfma_f32_16x16x32_bf16 v[88:91], v[172:175], v[212:215], v[88:91]
	v_mfma_f32_16x16x32_bf16 v[84:87], v[180:183], v[204:207], v[84:87]
	v_mfma_f32_16x16x32_bf16 v[80:83], v[180:183], v[212:215], v[80:83]
	v_mfma_f32_16x16x32_bf16 v[76:79], v[188:191], v[204:207], v[76:79]
	v_mfma_f32_16x16x32_bf16 v[72:75], v[188:191], v[212:215], v[72:75]
	v_mfma_f32_16x16x32_bf16 v[68:71], v[196:199], v[204:207], v[68:71]
	v_mfma_f32_16x16x32_bf16 v[64:67], v[196:199], v[212:215], v[64:67]
	s_setprio 0
	s_barrier
	ds_read_b128 v[168:171], v148 offset:49152
	ds_read_b128 v[172:175], v148 offset:50176
	ds_read_b128 v[176:179], v149 offset:49152
	ds_read_b128 v[180:183], v149 offset:50176
	ds_read_b128 v[184:187], v150 offset:49152
	ds_read_b128 v[188:191], v150 offset:50176
	ds_read_b128 v[192:195], v151 offset:49152
	ds_read_b128 v[196:199], v151 offset:50176
	s_add_i32 s38, s36, 0x180
	s_mov_b32 m0, s24
	s_nop 0
	buffer_load_dwordx4 v131, s[60:63], s38 offen lds
	s_add_i32 s36, s36, 0x40180
	s_mov_b32 m0, s25
	s_nop 0
	buffer_load_dwordx4 v131, s[60:63], s36 offen lds
	s_waitcnt vmcnt(10)
	s_barrier
	s_waitcnt lgkmcnt(0)
	s_setprio 1
	v_mfma_f32_16x16x32_bf16 v[60:63], v[168:171], v[132:135], v[60:63]
	v_mfma_f32_16x16x32_bf16 v[56:59], v[168:171], v[160:163], v[56:59]
	v_mfma_f32_16x16x32_bf16 v[52:55], v[176:179], v[132:135], v[52:55]
	v_mfma_f32_16x16x32_bf16 v[48:51], v[176:179], v[160:163], v[48:51]
	v_mfma_f32_16x16x32_bf16 v[44:47], v[184:187], v[132:135], v[44:47]
	v_mfma_f32_16x16x32_bf16 v[40:43], v[184:187], v[160:163], v[40:43]
	v_mfma_f32_16x16x32_bf16 v[36:39], v[192:195], v[132:135], v[36:39]
	v_mfma_f32_16x16x32_bf16 v[32:35], v[192:195], v[160:163], v[32:35]
	v_mfma_f32_16x16x32_bf16 v[60:63], v[172:175], v[156:159], v[60:63]
	v_mfma_f32_16x16x32_bf16 v[56:59], v[172:175], v[164:167], v[56:59]
	v_mfma_f32_16x16x32_bf16 v[52:55], v[180:183], v[156:159], v[52:55]
	v_mfma_f32_16x16x32_bf16 v[48:51], v[180:183], v[164:167], v[48:51]
	v_mfma_f32_16x16x32_bf16 v[44:47], v[188:191], v[156:159], v[44:47]
	v_mfma_f32_16x16x32_bf16 v[40:43], v[188:191], v[164:167], v[40:43]
	v_mfma_f32_16x16x32_bf16 v[36:39], v[196:199], v[156:159], v[36:39]
	v_mfma_f32_16x16x32_bf16 v[32:35], v[196:199], v[164:167], v[32:35]
	s_setprio 0
	s_barrier
	ds_read_b128 v[132:135], v147
	ds_read_b128 v[156:159], v147 offset:1024
	ds_read_b128 v[160:163], v147 offset:2048
	ds_read_b128 v[164:167], v147 offset:3072
	s_add_i32 s36, s37, 0x2180
	s_mov_b32 m0, s26
	s_nop 0
	buffer_load_dwordx4 v144, s[76:79], s36 offen lds
	s_add_i32 s37, s37, 0x82180
	s_mov_b32 m0, s27
	s_nop 0
	buffer_load_dwordx4 v144, s[76:79], s37 offen lds
	s_waitcnt vmcnt(6)
	s_barrier
	s_setprio 1
	v_mfma_f32_16x16x32_bf16 v[28:31], v[168:171], v[200:203], v[28:31]
	v_mfma_f32_16x16x32_bf16 v[24:27], v[168:171], v[208:211], v[24:27]
	v_mfma_f32_16x16x32_bf16 v[20:23], v[176:179], v[200:203], v[20:23]
	v_mfma_f32_16x16x32_bf16 v[16:19], v[176:179], v[208:211], v[16:19]
	v_mfma_f32_16x16x32_bf16 v[12:15], v[184:187], v[200:203], v[12:15]
	v_mfma_f32_16x16x32_bf16 v[8:11], v[184:187], v[208:211], v[8:11]
	v_mfma_f32_16x16x32_bf16 v[4:7], v[192:195], v[200:203], v[4:7]
	v_mfma_f32_16x16x32_bf16 v[0:3], v[192:195], v[208:211], v[0:3]
	v_mfma_f32_16x16x32_bf16 v[28:31], v[172:175], v[204:207], v[28:31]
	v_mfma_f32_16x16x32_bf16 v[24:27], v[172:175], v[212:215], v[24:27]
	v_mfma_f32_16x16x32_bf16 v[20:23], v[180:183], v[204:207], v[20:23]
	v_mfma_f32_16x16x32_bf16 v[16:19], v[180:183], v[212:215], v[16:19]
	v_mfma_f32_16x16x32_bf16 v[12:15], v[188:191], v[204:207], v[12:15]
	v_mfma_f32_16x16x32_bf16 v[8:11], v[188:191], v[212:215], v[8:11]
	v_mfma_f32_16x16x32_bf16 v[4:7], v[196:199], v[204:207], v[4:7]
	v_mfma_f32_16x16x32_bf16 v[0:3], v[196:199], v[212:215], v[0:3]
	s_setprio 0
	s_add_i32 s34, s34, 2
	s_addk_i32 s35, 0x100
	s_cmp_lt_u32 s34, 28
	s_barrier
; #define STAGE_A(POFF, h, kt) STAGE_AX(POFF, h, kt, brow)
; #define LDA(dst, b, h) _Pragma("unroll") for (int m = 0; m < 4; ++m) _Pragma("unroll") for (int k = 0; k < 2; ++k) \
;     dst[m][k] = *reinterpret_cast<const bf16x8*>((char*)SA(b, h) + lds_byte(wr * 64 + m * 16 + fr, k * 32 + fq * 8))
; #define LDB(dst, b, h) _Pragma("unroll") for (int n = 0; n < 2; ++n) _Pragma("unroll") for (int k = 0; k < 2; ++k) \
;     dst[n][k] = *reinterpret_cast<const bf16x8*>((char*)SB(b, h) + lds_byte(wc * 32 + n * 16 + fr, k * 32 + fq * 8))
; #define MMA(ai, bj, At_, Bt_) do { __builtin_amdgcn_s_setprio(1); \
;     _Pragma("unroll") for (int k = 0; k < 2; ++k) _Pragma("unroll") for (int m = 0; m < 4; ++m) _Pragma("unroll") for (int n = 0; n < 2; ++n) \
;       acc[ai][bj][m][n] = __builtin_amdgcn_mfma_f32_16x16x32_bf16(At_[m][k], Bt_[n][k], acc[ai][bj][m][n], 0, 0, 0); \
;     __builtin_amdgcn_s_setprio(0); } while (0)
; #define WAIT_V(n) asm volatile("s_waitcnt vmcnt(" #n ")" ::: "memory")
; #define BAR __builtin_amdgcn_s_barrier()
; template <int EPI, int N, int K>
; __device__ __forceinline__ void gemm_phase(const bf16_t* __restrict__ A, const bf16_t* __restrict__ Bt, const EpiArgs ea) {
;     ...
;     { LDB(B0, 0, 0); LDA(At, 0, 0); STAGE_A(SA_OFF(1, 1), 1, nt - 1);
;       BAR; WAIT_L(0); MMA(0, 0, At, B0); BAR;
;       LDB(B1, 0, 1); BAR; WAIT_L(0); MMA(0, 1, At, B1); BAR;
;       LDA(At, 0, 1); WAIT_V(4); BAR; WAIT_L(0); MMA(1, 0, At, B0); MMA(1, 1, At, B1); BAR; }
;     { LDB(B0, 1, 0); LDA(At, 1, 0); WAIT_V(2); BAR; WAIT_L(0); MMA(0, 0, At, B0); BAR;
	s_cbranch_scc1 .LBB0_390
	ds_read_b128 v[168:171], v148
	ds_read_b128 v[172:175], v148 offset:1024
	ds_read_b128 v[176:179], v149
	ds_read_b128 v[180:183], v149 offset:1024
	ds_read_b128 v[184:187], v150
	ds_read_b128 v[188:191], v150 offset:1024
	ds_read_b128 v[192:195], v151
	ds_read_b128 v[196:199], v151 offset:1024
	s_and_b32 s3, s3, 0x700
	s_lshl_b32 s2, s2, 11
	s_or_b32 s31, s3, s2
	s_lshl_b32 s2, s31, 12
	s_or_b32 s3, s2, 0x80f80
	s_mov_b32 m0, s28
	s_nop 0
	buffer_load_dwordx4 v131, s[60:63], s3 offen lds
	s_or_b32 s2, s2, 0xc0f80
	s_mov_b32 m0, s29
	s_nop 0
	buffer_load_dwordx4 v131, s[60:63], s2 offen lds
	s_barrier
	s_waitcnt lgkmcnt(0)
	s_setprio 1
	v_mfma_f32_16x16x32_bf16 v[124:127], v[168:171], v[132:135], v[124:127]
	v_mfma_f32_16x16x32_bf16 v[120:123], v[168:171], v[160:163], v[120:123]
	v_mfma_f32_16x16x32_bf16 v[116:119], v[176:179], v[132:135], v[116:119]
	v_mfma_f32_16x16x32_bf16 v[112:115], v[176:179], v[160:163], v[112:115]
	v_mfma_f32_16x16x32_bf16 v[108:111], v[184:187], v[132:135], v[108:111]
	v_mfma_f32_16x16x32_bf16 v[104:107], v[184:187], v[160:163], v[104:107]
	v_mfma_f32_16x16x32_bf16 v[100:103], v[192:195], v[132:135], v[100:103]
	v_mfma_f32_16x16x32_bf16 v[96:99], v[192:195], v[160:163], v[96:99]
	v_mfma_f32_16x16x32_bf16 v[124:127], v[172:175], v[156:159], v[124:127]
	v_mfma_f32_16x16x32_bf16 v[120:123], v[172:175], v[164:167], v[120:123]
	v_mfma_f32_16x16x32_bf16 v[116:119], v[180:183], v[156:159], v[116:119]
	v_mfma_f32_16x16x32_bf16 v[112:115], v[180:183], v[164:167], v[112:115]
	v_mfma_f32_16x16x32_bf16 v[108:111], v[188:191], v[156:159], v[108:111]
	v_mfma_f32_16x16x32_bf16 v[104:107], v[188:191], v[164:167], v[104:107]
	v_mfma_f32_16x16x32_bf16 v[100:103], v[196:199], v[156:159], v[100:103]
	v_mfma_f32_16x16x32_bf16 v[96:99], v[196:199], v[164:167], v[96:99]
	s_setprio 0
	s_barrier
	ds_read_b128 v[200:203], v152
	ds_read_b128 v[204:207], v152 offset:1024
	ds_read_b128 v[208:211], v152 offset:2048
	ds_read_b128 v[212:215], v152 offset:3072
	s_barrier
	s_waitcnt lgkmcnt(0)
	s_setprio 1
	v_mfma_f32_16x16x32_bf16 v[92:95], v[168:171], v[200:203], v[92:95]
	v_mfma_f32_16x16x32_bf16 v[88:91], v[168:171], v[208:211], v[88:91]
	v_mfma_f32_16x16x32_bf16 v[76:79], v[184:187], v[200:203], v[76:79]
	v_mfma_f32_16x16x32_bf16 v[72:75], v[184:187], v[208:211], v[72:75]
	v_mfma_f32_16x16x32_bf16 v[84:87], v[176:179], v[200:203], v[84:87]
	v_mfma_f32_16x16x32_bf16 v[80:83], v[176:179], v[208:211], v[80:83]
	v_mfma_f32_16x16x32_bf16 v[68:71], v[192:195], v[200:203], v[68:71]
	v_mfma_f32_16x16x32_bf16 v[64:67], v[192:195], v[208:211], v[64:67]
	v_mfma_f32_16x16x32_bf16 v[92:95], v[172:175], v[204:207], v[92:95]
	v_mfma_f32_16x16x32_bf16 v[88:91], v[172:175], v[212:215], v[88:91]
	v_mfma_f32_16x16x32_bf16 v[76:79], v[188:191], v[204:207], v[76:79]
	v_mfma_f32_16x16x32_bf16 v[72:75], v[188:191], v[212:215], v[72:75]
	v_mfma_f32_16x16x32_bf16 v[168:171], v[180:183], v[204:207], v[84:87]
	v_mfma_f32_16x16x32_bf16 v[172:175], v[180:183], v[212:215], v[80:83]
	v_mfma_f32_16x16x32_bf16 v[176:179], v[196:199], v[204:207], v[68:71]
	v_mfma_f32_16x16x32_bf16 v[180:183], v[196:199], v[212:215], v[64:67]
	s_setprio 0
	s_barrier
	s_nop 0
	ds_read_b128 v[64:67], v148 offset:16384
	ds_read_b128 v[68:71], v148 offset:17408
	ds_read_b128 v[80:83], v149 offset:16384
	ds_read_b128 v[84:87], v149 offset:17408
	ds_read_b128 v[184:187], v150 offset:16384
	ds_read_b128 v[188:191], v150 offset:17408
	ds_read_b128 v[192:195], v151 offset:16384
	ds_read_b128 v[196:199], v151 offset:17408
	s_waitcnt vmcnt(4)
	s_barrier
	s_waitcnt lgkmcnt(0)
	s_setprio 1
	v_mfma_f32_16x16x32_bf16 v[60:63], v[64:67], v[132:135], v[60:63]
	v_mfma_f32_16x16x32_bf16 v[56:59], v[64:67], v[160:163], v[56:59]
	v_mfma_f32_16x16x32_bf16 v[52:55], v[80:83], v[132:135], v[52:55]
	v_mfma_f32_16x16x32_bf16 v[48:51], v[80:83], v[160:163], v[48:51]
	v_mfma_f32_16x16x32_bf16 v[44:47], v[184:187], v[132:135], v[44:47]
	v_mfma_f32_16x16x32_bf16 v[40:43], v[184:187], v[160:163], v[40:43]
	v_mfma_f32_16x16x32_bf16 v[36:39], v[192:195], v[132:135], v[36:39]
	v_mfma_f32_16x16x32_bf16 v[32:35], v[192:195], v[160:163], v[32:35]
	v_mfma_f32_16x16x32_bf16 v[60:63], v[68:71], v[156:159], v[60:63]
	v_mfma_f32_16x16x32_bf16 v[56:59], v[68:71], v[164:167], v[56:59]
	v_mfma_f32_16x16x32_bf16 v[52:55], v[84:87], v[156:159], v[52:55]
	v_mfma_f32_16x16x32_bf16 v[48:51], v[84:87], v[164:167], v[48:51]
	v_mfma_f32_16x16x32_bf16 v[44:47], v[188:191], v[156:159], v[44:47]
	v_mfma_f32_16x16x32_bf16 v[40:43], v[188:191], v[164:167], v[40:43]
	v_mfma_f32_16x16x32_bf16 v[36:39], v[196:199], v[156:159], v[36:39]
	v_mfma_f32_16x16x32_bf16 v[32:35], v[196:199], v[164:167], v[32:35]
	s_setprio 0
	s_setprio 1
	v_mfma_f32_16x16x32_bf16 v[28:31], v[64:67], v[200:203], v[28:31]
	v_mfma_f32_16x16x32_bf16 v[24:27], v[64:67], v[208:211], v[24:27]
	v_mfma_f32_16x16x32_bf16 v[4:7], v[192:195], v[200:203], v[4:7]
	v_mfma_f32_16x16x32_bf16 v[0:3], v[192:195], v[208:211], v[0:3]
	v_mfma_f32_16x16x32_bf16 v[20:23], v[80:83], v[200:203], v[20:23]
	v_mfma_f32_16x16x32_bf16 v[16:19], v[80:83], v[208:211], v[16:19]
	v_mfma_f32_16x16x32_bf16 v[12:15], v[184:187], v[200:203], v[12:15]
	v_mfma_f32_16x16x32_bf16 v[8:11], v[184:187], v[208:211], v[8:11]
	v_mfma_f32_16x16x32_bf16 v[28:31], v[68:71], v[204:207], v[28:31]
	v_mfma_f32_16x16x32_bf16 v[24:27], v[68:71], v[212:215], v[24:27]
	v_mfma_f32_16x16x32_bf16 v[4:7], v[196:199], v[204:207], v[4:7]
	v_mfma_f32_16x16x32_bf16 v[0:3], v[196:199], v[212:215], v[0:3]
	v_mfma_f32_16x16x32_bf16 v[132:135], v[84:87], v[204:207], v[20:23]
	v_mfma_f32_16x16x32_bf16 v[156:159], v[84:87], v[212:215], v[16:19]
	v_mfma_f32_16x16x32_bf16 v[160:163], v[188:191], v[204:207], v[12:15]
	v_mfma_f32_16x16x32_bf16 v[164:167], v[188:191], v[212:215], v[8:11]
	s_setprio 0
	s_barrier
; #define LDA(dst, b, h) _Pragma("unroll") for (int m = 0; m < 4; ++m) _Pragma("unroll") for (int k = 0; k < 2; ++k) \
;     dst[m][k] = *reinterpret_cast<const bf16x8*>((char*)SA(b, h) + lds_byte(wr * 64 + m * 16 + fr, k * 32 + fq * 8))
; #define LDB(dst, b, h) _Pragma("unroll") for (int n = 0; n < 2; ++n) _Pragma("unroll") for (int k = 0; k < 2; ++k) \
;     dst[n][k] = *reinterpret_cast<const bf16x8*>((char*)SB(b, h) + lds_byte(wc * 32 + n * 16 + fr, k * 32 + fq * 8))
; #define MMA(ai, bj, At_, Bt_) do { __builtin_amdgcn_s_setprio(1); \
;     _Pragma("unroll") for (int k = 0; k < 2; ++k) _Pragma("unroll") for (int m = 0; m < 4; ++m) _Pragma("unroll") for (int n = 0; n < 2; ++n) \
;       acc[ai][bj][m][n] = __builtin_amdgcn_mfma_f32_16x16x32_bf16(At_[m][k], Bt_[n][k], acc[ai][bj][m][n], 0, 0, 0); \
;     __builtin_amdgcn_s_setprio(0); } while (0)
; #define WAIT_V(n) asm volatile("s_waitcnt vmcnt(" #n ")" ::: "memory")
; #define BAR __builtin_amdgcn_s_barrier()
; template <int EPI, int N, int K>
; __device__ __forceinline__ void gemm_phase(const bf16_t* __restrict__ A, const bf16_t* __restrict__ Bt, const EpiArgs ea) {
;     ...
;     { LDB(B0, 1, 0); LDA(At, 1, 0); WAIT_V(2); BAR; WAIT_L(0); MMA(0, 0, At, B0); BAR;
;       LDB(B1, 1, 1); WAIT_V(0); BAR; WAIT_L(0); MMA(0, 1, At, B1); BAR;
;       LDA(At, 1, 1); BAR; WAIT_L(0); MMA(1, 0, At, B0); MMA(1, 1, At, B1); BAR; }
;     if (wr == 0) BAR;
	s_nop 0
	ds_read_b128 v[8:11], v153
	ds_read_b128 v[12:15], v153 offset:1024
	ds_read_b128 v[16:19], v153 offset:2048
	ds_read_b128 v[184:187], v153 offset:3072
	ds_read_b128 v[20:23], v148 offset:32768
	ds_read_b128 v[188:191], v148 offset:33792
	ds_read_b128 v[192:195], v149 offset:32768
	ds_read_b128 v[196:199], v149 offset:33792
	ds_read_b128 v[200:203], v150 offset:32768
	ds_read_b128 v[204:207], v150 offset:33792
	ds_read_b128 v[208:211], v151 offset:32768
	ds_read_b128 v[212:215], v151 offset:33792
	s_waitcnt vmcnt(2)
	s_barrier
	s_waitcnt lgkmcnt(0)
	s_setprio 1
	v_mfma_f32_16x16x32_bf16 v[64:67], v[20:23], v[8:11], v[124:127]
	v_mfma_f32_16x16x32_bf16 v[68:71], v[20:23], v[16:19], v[120:123]
	v_mfma_f32_16x16x32_bf16 v[80:83], v[192:195], v[8:11], v[116:119]
	v_mfma_f32_16x16x32_bf16 v[84:87], v[192:195], v[16:19], v[112:115]
	v_mfma_f32_16x16x32_bf16 v[108:111], v[200:203], v[8:11], v[108:111]
	v_mfma_f32_16x16x32_bf16 v[104:107], v[200:203], v[16:19], v[104:107]
	v_mfma_f32_16x16x32_bf16 v[120:123], v[208:211], v[8:11], v[100:103]
	v_mfma_f32_16x16x32_bf16 v[124:127], v[208:211], v[16:19], v[96:99]
	v_mfma_f32_16x16x32_bf16 v[116:119], v[188:191], v[12:15], v[64:67]
	v_mfma_f32_16x16x32_bf16 v[112:115], v[188:191], v[184:187], v[68:71]
	v_mfma_f32_16x16x32_bf16 v[100:103], v[196:199], v[12:15], v[80:83]
	v_mfma_f32_16x16x32_bf16 v[96:99], v[196:199], v[184:187], v[84:87]
	v_mfma_f32_16x16x32_bf16 v[84:87], v[204:207], v[12:15], v[108:111]
	v_mfma_f32_16x16x32_bf16 v[80:83], v[204:207], v[184:187], v[104:107]
	v_mfma_f32_16x16x32_bf16 v[68:71], v[212:215], v[12:15], v[120:123]
	v_mfma_f32_16x16x32_bf16 v[64:67], v[212:215], v[184:187], v[124:127]
	s_setprio 0
	s_barrier
	ds_read_b128 v[216:219], v154
	ds_read_b128 v[220:223], v154 offset:1024
	ds_read_b128 v[224:227], v154 offset:2048
	ds_read_b128 v[228:231], v154 offset:3072
	s_waitcnt vmcnt(0)
	s_barrier
	s_waitcnt lgkmcnt(0)
	s_setprio 1
	v_mfma_f32_16x16x32_bf16 v[92:95], v[20:23], v[216:219], v[92:95]
	v_mfma_f32_16x16x32_bf16 v[20:23], v[20:23], v[224:227], v[88:91]
	v_mfma_f32_16x16x32_bf16 v[88:91], v[192:195], v[216:219], v[168:171]
	v_mfma_f32_16x16x32_bf16 v[104:107], v[192:195], v[224:227], v[172:175]
	v_mfma_f32_16x16x32_bf16 v[76:79], v[200:203], v[216:219], v[76:79]
	v_mfma_f32_16x16x32_bf16 v[72:75], v[200:203], v[224:227], v[72:75]
	v_mfma_f32_16x16x32_bf16 v[168:171], v[208:211], v[216:219], v[176:179]
	v_mfma_f32_16x16x32_bf16 v[172:175], v[208:211], v[224:227], v[180:183]
	v_mfma_f32_16x16x32_bf16 v[124:127], v[188:191], v[220:223], v[92:95]
	v_mfma_f32_16x16x32_bf16 v[120:123], v[188:191], v[228:231], v[20:23]
	v_mfma_f32_16x16x32_bf16 v[108:111], v[196:199], v[220:223], v[88:91]
	v_mfma_f32_16x16x32_bf16 v[104:107], v[196:199], v[228:231], v[104:107]
	v_mfma_f32_16x16x32_bf16 v[92:95], v[204:207], v[220:223], v[76:79]
	v_mfma_f32_16x16x32_bf16 v[88:91], v[204:207], v[228:231], v[72:75]
	v_mfma_f32_16x16x32_bf16 v[76:79], v[212:215], v[220:223], v[168:171]
	v_mfma_f32_16x16x32_bf16 v[72:75], v[212:215], v[228:231], v[172:175]
	s_setprio 0
	s_barrier
	ds_read_b128 v[168:171], v148 offset:49152
	ds_read_b128 v[172:175], v148 offset:50176
	ds_read_b128 v[176:179], v149 offset:49152
	ds_read_b128 v[180:183], v149 offset:50176
	ds_read_b128 v[188:191], v150 offset:49152
	ds_read_b128 v[192:195], v150 offset:50176
	ds_read_b128 v[196:199], v151 offset:49152
	ds_read_b128 v[200:203], v151 offset:50176
	s_barrier
	s_waitcnt lgkmcnt(0)
	s_setprio 1
	v_mfma_f32_16x16x32_bf16 v[20:23], v[168:171], v[8:11], v[60:63]
	v_mfma_f32_16x16x32_bf16 v[56:59], v[168:171], v[16:19], v[56:59]
	v_mfma_f32_16x16x32_bf16 v[60:63], v[176:179], v[8:11], v[52:55]
	v_mfma_f32_16x16x32_bf16 v[204:207], v[176:179], v[16:19], v[48:51]
	v_mfma_f32_16x16x32_bf16 v[44:47], v[188:191], v[8:11], v[44:47]
	v_mfma_f32_16x16x32_bf16 v[40:43], v[188:191], v[16:19], v[40:43]
	v_mfma_f32_16x16x32_bf16 v[8:11], v[196:199], v[8:11], v[36:39]
	v_mfma_f32_16x16x32_bf16 v[208:211], v[196:199], v[16:19], v[32:35]
	v_mfma_f32_16x16x32_bf16 v[52:55], v[172:175], v[12:15], v[20:23]
	v_mfma_f32_16x16x32_bf16 v[48:51], v[172:175], v[184:187], v[56:59]
	v_mfma_f32_16x16x32_bf16 v[36:39], v[180:183], v[12:15], v[60:63]
	v_mfma_f32_16x16x32_bf16 v[32:35], v[180:183], v[184:187], v[204:207]
	v_mfma_f32_16x16x32_bf16 v[20:23], v[192:195], v[12:15], v[44:47]
	v_mfma_f32_16x16x32_bf16 v[16:19], v[192:195], v[184:187], v[40:43]
	v_mfma_f32_16x16x32_bf16 v[8:11], v[200:203], v[12:15], v[8:11]
	v_mfma_f32_16x16x32_bf16 v[12:15], v[200:203], v[184:187], v[208:211]
	s_setprio 0
	s_setprio 1
	v_mfma_f32_16x16x32_bf16 v[28:31], v[168:171], v[216:219], v[28:31]
	v_mfma_f32_16x16x32_bf16 v[24:27], v[168:171], v[224:227], v[24:27]
	v_mfma_f32_16x16x32_bf16 v[40:43], v[176:179], v[216:219], v[132:135]
	v_mfma_f32_16x16x32_bf16 v[132:135], v[176:179], v[224:227], v[156:159]
	v_mfma_f32_16x16x32_bf16 v[156:159], v[188:191], v[216:219], v[160:163]
	v_mfma_f32_16x16x32_bf16 v[160:163], v[188:191], v[224:227], v[164:167]
	v_mfma_f32_16x16x32_bf16 v[4:7], v[196:199], v[216:219], v[4:7]
	v_mfma_f32_16x16x32_bf16 v[0:3], v[196:199], v[224:227], v[0:3]
	v_mfma_f32_16x16x32_bf16 v[60:63], v[172:175], v[220:223], v[28:31]
	v_mfma_f32_16x16x32_bf16 v[56:59], v[172:175], v[228:231], v[24:27]
	v_mfma_f32_16x16x32_bf16 v[44:47], v[180:183], v[220:223], v[40:43]
	v_mfma_f32_16x16x32_bf16 v[40:43], v[180:183], v[228:231], v[132:135]
	v_mfma_f32_16x16x32_bf16 v[28:31], v[192:195], v[220:223], v[156:159]
	v_mfma_f32_16x16x32_bf16 v[24:27], v[192:195], v[228:231], v[160:163]
	v_mfma_f32_16x16x32_bf16 v[4:7], v[200:203], v[220:223], v[4:7]
	v_mfma_f32_16x16x32_bf16 v[0:3], v[200:203], v[228:231], v[0:3]
	s_setprio 0
	s_barrier
	s_and_saveexec_b64 s[2:3], s[8:9]
	s_cbranch_execz .LBB0_393
	s_barrier

; #define STAGE_A(POFF, h, kt) STAGE_AX(POFF, h, kt, brow)
; #define STAGE_B(POFF, h, kt) STAGE_BX(POFF, h, kt, bcol)
; #define LDA(dst, b, h) _Pragma("unroll") for (int m = 0; m < 4; ++m) _Pragma("unroll") for (int k = 0; k < 2; ++k) \
;     dst[m][k] = *reinterpret_cast<const bf16x8*>((char*)SA(b, h) + lds_byte(wr * 64 + m * 16 + fr, k * 32 + fq * 8))
; #define LDB(dst, b, h) _Pragma("unroll") for (int n = 0; n < 2; ++n) _Pragma("unroll") for (int k = 0; k < 2; ++k) \
;     dst[n][k] = *reinterpret_cast<const bf16x8*>((char*)SB(b, h) + lds_byte(wc * 32 + n * 16 + fr, k * 32 + fq * 8))
; #define MMA(ai, bj, At_, Bt_) do { __builtin_amdgcn_s_setprio(1); \
;     _Pragma("unroll") for (int k = 0; k < 2; ++k) _Pragma("unroll") for (int m = 0; m < 4; ++m) _Pragma("unroll") for (int n = 0; n < 2; ++n) \
;       acc[ai][bj][m][n] = __builtin_amdgcn_mfma_f32_16x16x32_bf16(At_[m][k], Bt_[n][k], acc[ai][bj][m][n], 0, 0, 0); \
;     __builtin_amdgcn_s_setprio(0); } while (0)
; #define WAIT_V(n) asm volatile("s_waitcnt vmcnt(" #n ")" ::: "memory")
; #define BAR __builtin_amdgcn_s_barrier()
; #define SCHED __builtin_amdgcn_sched_barrier(0)
; #define TILE_RC(w_, brow_, bcol_) do { const int wg_ = ((w_) & 7) * qx + ((w_) >> 3); const int gid_ = wg_ / nig; \
;     brow_ = (gid_ * 8 + ((wg_ % nig) & 7)) * 256; bcol_ = ((wg_ % nig) >> 3) * 256; } while (0)
; template <int EPI, int N, int K>
; __device__ __forceinline__ void gemm_phase(const bf16_t* __restrict__ A, const bf16_t* __restrict__ Bt, const EpiArgs ea) {
;     ...
;     int brow, bcol; TILE_RC(w, brow, bcol);
;     f32x4 acc[2][2][4][2];
; #pragma unroll
;     for (int a = 0; a < 2; ++a)
; #pragma unroll
;       for (int b = 0; b < 2; ++b)
; #pragma unroll
;         for (int m = 0; m < 4; ++m)
; #pragma unroll
;           for (int n = 0; n < 2; ++n) acc[a][b][m][n] = (f32x4){0.f, 0.f, 0.f, 0.f};
;     bf16x8 At[4][2], B0[2][2], B1[2][2];
;     if (wr == 1) BAR;
;     if (w == (int)blockIdx.x) { WAIT_V(0); } else { WAIT_V(24); }
;     BAR;
;     BAR;
;     for (int t = 0; t < nt - 2; t += 2) {
;       LDB(B0, 0, 0); SCHED; LDA(At, 0, 0); STAGE_A(SA_OFF(1, 1), 1, t + 1);
;       WAIT_L(8); BAR; WAIT_L(0); MMA(0, 0, At, B0); BAR; SCHED;
;       LDB(B1, 0, 1); STAGE_B(SB_OFF(0, 0), 0, t + 2);
.LBB0_508:
	s_lshl_b32 s2, s31, 8
	s_and_b32 s2, s2, 0x700
	s_ashr_i32 s3, s31, 3
	s_add_i32 s3, s2, s3
	s_ashr_i32 s2, s3, 31
	s_lshr_b32 s2, s2, 24
	s_add_i32 s12, s3, s2
	s_ashr_i32 s2, s12, 8
	s_and_b32 s12, s12, 0xffffff00
	s_sub_i32 s34, s3, s12
	s_lshl_b32 s3, s34, 8
	s_lshl_b32 s12, s34, 5
	s_lshl_b32 s13, s34, 17
	s_and_b32 s34, s34, 7
	s_lshl_b32 s35, s2, 23
	s_lshl_b32 s34, s34, 20
	v_mov_b32_e32 v0, 0
	s_and_b32 s13, s13, 0xfff00000
	s_or_b32 s34, s35, s34
	s_mov_b32 s35, -2
	s_mov_b32 s36, 0
	v_mov_b32_e32 v1, v0
	v_mov_b32_e32 v2, v0
	v_mov_b32_e32 v3, v0
	v_mov_b32_e32 v4, v0
	v_mov_b32_e32 v5, v0
	v_mov_b32_e32 v6, v0
	v_mov_b32_e32 v7, v0
	v_mov_b32_e32 v8, v0
	v_mov_b32_e32 v9, v0
	v_mov_b32_e32 v10, v0
	v_mov_b32_e32 v11, v0
	v_mov_b32_e32 v12, v0
	v_mov_b32_e32 v13, v0
	v_mov_b32_e32 v14, v0
	v_mov_b32_e32 v15, v0
	v_mov_b32_e32 v16, v0
	v_mov_b32_e32 v17, v0
	v_mov_b32_e32 v18, v0
	v_mov_b32_e32 v19, v0
	v_mov_b32_e32 v20, v0
	v_mov_b32_e32 v21, v0
	v_mov_b32_e32 v22, v0
	v_mov_b32_e32 v23, v0
	v_mov_b32_e32 v24, v0
	v_mov_b32_e32 v25, v0
	v_mov_b32_e32 v26, v0
	v_mov_b32_e32 v27, v0
	v_mov_b32_e32 v28, v0
	v_mov_b32_e32 v29, v0
	v_mov_b32_e32 v30, v0
	v_mov_b32_e32 v31, v0
	v_mov_b32_e32 v32, v0
	v_mov_b32_e32 v33, v0
	v_mov_b32_e32 v34, v0
	v_mov_b32_e32 v35, v0
	v_mov_b32_e32 v36, v0
	v_mov_b32_e32 v37, v0
	v_mov_b32_e32 v38, v0
	v_mov_b32_e32 v39, v0
	v_mov_b32_e32 v40, v0
	v_mov_b32_e32 v41, v0
	v_mov_b32_e32 v42, v0
	v_mov_b32_e32 v43, v0
	v_mov_b32_e32 v44, v0
	v_mov_b32_e32 v45, v0
	v_mov_b32_e32 v46, v0
	v_mov_b32_e32 v47, v0
	v_mov_b32_e32 v48, v0
	v_mov_b32_e32 v49, v0
	v_mov_b32_e32 v50, v0
	v_mov_b32_e32 v51, v0
	v_mov_b32_e32 v52, v0
	v_mov_b32_e32 v53, v0
	v_mov_b32_e32 v54, v0
	v_mov_b32_e32 v55, v0
	v_mov_b32_e32 v56, v0
	v_mov_b32_e32 v57, v0
	v_mov_b32_e32 v58, v0
	v_mov_b32_e32 v59, v0
	v_mov_b32_e32 v60, v0
	v_mov_b32_e32 v61, v0
	v_mov_b32_e32 v62, v0
	v_mov_b32_e32 v63, v0
	v_mov_b32_e32 v64, v0
	v_mov_b32_e32 v65, v0
	v_mov_b32_e32 v66, v0
	v_mov_b32_e32 v67, v0
	v_mov_b32_e32 v68, v0
	v_mov_b32_e32 v69, v0
	v_mov_b32_e32 v70, v0
	v_mov_b32_e32 v71, v0
	v_mov_b32_e32 v72, v0
	v_mov_b32_e32 v73, v0
	v_mov_b32_e32 v74, v0
	v_mov_b32_e32 v75, v0
	v_mov_b32_e32 v76, v0
	v_mov_b32_e32 v77, v0
	v_mov_b32_e32 v78, v0
	v_mov_b32_e32 v79, v0
	v_mov_b32_e32 v80, v0
	v_mov_b32_e32 v81, v0
	v_mov_b32_e32 v82, v0
	v_mov_b32_e32 v83, v0
	v_mov_b32_e32 v84, v0
	v_mov_b32_e32 v85, v0
	v_mov_b32_e32 v86, v0
	v_mov_b32_e32 v87, v0
	v_mov_b32_e32 v88, v0
	v_mov_b32_e32 v89, v0
	v_mov_b32_e32 v90, v0
	v_mov_b32_e32 v91, v0
	v_mov_b32_e32 v92, v0
	v_mov_b32_e32 v93, v0
	v_mov_b32_e32 v94, v0
	v_mov_b32_e32 v95, v0
	v_mov_b32_e32 v96, v0
	v_mov_b32_e32 v97, v0
	v_mov_b32_e32 v98, v0
	v_mov_b32_e32 v99, v0
	v_mov_b32_e32 v100, v0
	v_mov_b32_e32 v101, v0
	v_mov_b32_e32 v102, v0
	v_mov_b32_e32 v103, v0
	v_mov_b32_e32 v104, v0
	v_mov_b32_e32 v105, v0
	v_mov_b32_e32 v106, v0
	v_mov_b32_e32 v107, v0
	v_mov_b32_e32 v108, v0
	v_mov_b32_e32 v109, v0
	v_mov_b32_e32 v110, v0
	v_mov_b32_e32 v111, v0
	v_mov_b32_e32 v112, v0
	v_mov_b32_e32 v113, v0
	v_mov_b32_e32 v114, v0
	v_mov_b32_e32 v115, v0
	v_mov_b32_e32 v116, v0
	v_mov_b32_e32 v117, v0
	v_mov_b32_e32 v118, v0
	v_mov_b32_e32 v119, v0
	v_mov_b32_e32 v120, v0
	v_mov_b32_e32 v121, v0
	v_mov_b32_e32 v122, v0
	v_mov_b32_e32 v123, v0
	v_mov_b32_e32 v124, v0
	v_mov_b32_e32 v125, v0
	v_mov_b32_e32 v126, v0
	v_mov_b32_e32 v127, v0
	s_barrier
	s_barrier
	ds_read_b128 v[132:135], v148
	ds_read_b128 v[156:159], v148 offset:1024
	ds_read_b128 v[160:163], v148 offset:2048
	ds_read_b128 v[164:167], v148 offset:3072
.LBB0_509:
	ds_read_b128 v[168:171], v149
	ds_read_b128 v[172:175], v149 offset:1024
	ds_read_b128 v[176:179], v150
	ds_read_b128 v[180:183], v150 offset:1024
	ds_read_b128 v[184:187], v151
	ds_read_b128 v[188:191], v151 offset:1024
	ds_read_b128 v[192:195], v152
	ds_read_b128 v[196:199], v152 offset:1024
	s_add_i32 s37, s34, s36
	s_or_b32 s38, s37, 0x80080
	s_mov_b32 m0, s29
	s_nop 0
	buffer_load_dwordx4 v136, s[48:51], s38 offen lds
	s_or_b32 s38, s37, 0xc0080
	s_mov_b32 m0, s30
	s_nop 0
	buffer_load_dwordx4 v136, s[48:51], s38 offen lds
	s_waitcnt lgkmcnt(8)
	s_barrier
	s_waitcnt lgkmcnt(0)
	s_setprio 1
	v_mfma_f32_16x16x32_bf16 v[124:127], v[168:171], v[132:135], v[124:127]
	v_mfma_f32_16x16x32_bf16 v[120:123], v[168:171], v[160:163], v[120:123]
	v_mfma_f32_16x16x32_bf16 v[116:119], v[176:179], v[132:135], v[116:119]
	v_mfma_f32_16x16x32_bf16 v[112:115], v[176:179], v[160:163], v[112:115]
	v_mfma_f32_16x16x32_bf16 v[108:111], v[184:187], v[132:135], v[108:111]
	v_mfma_f32_16x16x32_bf16 v[104:107], v[184:187], v[160:163], v[104:107]
	v_mfma_f32_16x16x32_bf16 v[100:103], v[192:195], v[132:135], v[100:103]
	v_mfma_f32_16x16x32_bf16 v[96:99], v[192:195], v[160:163], v[96:99]
	v_mfma_f32_16x16x32_bf16 v[124:127], v[172:175], v[156:159], v[124:127]
	v_mfma_f32_16x16x32_bf16 v[120:123], v[172:175], v[164:167], v[120:123]
	v_mfma_f32_16x16x32_bf16 v[116:119], v[180:183], v[156:159], v[116:119]
	v_mfma_f32_16x16x32_bf16 v[112:115], v[180:183], v[164:167], v[112:115]
	v_mfma_f32_16x16x32_bf16 v[108:111], v[188:191], v[156:159], v[108:111]
	v_mfma_f32_16x16x32_bf16 v[104:107], v[188:191], v[164:167], v[104:107]
	v_mfma_f32_16x16x32_bf16 v[100:103], v[196:199], v[156:159], v[100:103]
	v_mfma_f32_16x16x32_bf16 v[96:99], v[196:199], v[164:167], v[96:99]
	s_setprio 0
	s_barrier
	ds_read_b128 v[200:203], v153
	ds_read_b128 v[204:207], v153 offset:1024
	ds_read_b128 v[208:211], v153 offset:2048
	ds_read_b128 v[212:215], v153 offset:3072
	s_add_i32 s38, s13, s36
	s_add_i32 s39, s38, 0x100
	s_mov_b32 m0, s15
	s_nop 0
	buffer_load_dwordx4 v137, s[80:83], s39 offen lds
	s_add_i32 s39, s38, 0x80100
	s_mov_b32 m0, s16
	s_nop 0
	buffer_load_dwordx4 v137, s[80:83], s39 offen lds
	s_barrier
; #define STAGE_A(POFF, h, kt) STAGE_AX(POFF, h, kt, brow)
; #define STAGE_B(POFF, h, kt) STAGE_BX(POFF, h, kt, bcol)
; #define LDA(dst, b, h) _Pragma("unroll") for (int m = 0; m < 4; ++m) _Pragma("unroll") for (int k = 0; k < 2; ++k) \
;     dst[m][k] = *reinterpret_cast<const bf16x8*>((char*)SA(b, h) + lds_byte(wr * 64 + m * 16 + fr, k * 32 + fq * 8))
; #define LDB(dst, b, h) _Pragma("unroll") for (int n = 0; n < 2; ++n) _Pragma("unroll") for (int k = 0; k < 2; ++k) \
;     dst[n][k] = *reinterpret_cast<const bf16x8*>((char*)SB(b, h) + lds_byte(wc * 32 + n * 16 + fr, k * 32 + fq * 8))
; #define MMA(ai, bj, At_, Bt_) do { __builtin_amdgcn_s_setprio(1); \
;     _Pragma("unroll") for (int k = 0; k < 2; ++k) _Pragma("unroll") for (int m = 0; m < 4; ++m) _Pragma("unroll") for (int n = 0; n < 2; ++n) \
;       acc[ai][bj][m][n] = __builtin_amdgcn_mfma_f32_16x16x32_bf16(At_[m][k], Bt_[n][k], acc[ai][bj][m][n], 0, 0, 0); \
;     __builtin_amdgcn_s_setprio(0); } while (0)
; #define WAIT_V(n) asm volatile("s_waitcnt vmcnt(" #n ")" ::: "memory")
; #define BAR __builtin_amdgcn_s_barrier()
; #define SCHED __builtin_amdgcn_sched_barrier(0)
; template <int EPI, int N, int K>
; __device__ __forceinline__ void gemm_phase(const bf16_t* __restrict__ A, const bf16_t* __restrict__ Bt, const EpiArgs ea) {
;     ...
;       BAR; WAIT_L(0); MMA(0, 1, At, B1); BAR;
;       LDA(At, 0, 1); STAGE_A(SA_OFF(0, 0), 0, t + 2);
;       BAR; WAIT_L(0); MMA(1, 0, At, B0); BAR; SCHED;
;       STAGE_B(SB_OFF(0, 1), 1, t + 2);
;       WAIT_V(6); BAR; MMA(1, 1, At, B1); BAR;
;       LDB(B0, 1, 0); SCHED; LDA(At, 1, 0); STAGE_A(SA_OFF(0, 1), 1, t + 2);
;       WAIT_L(8); BAR; WAIT_L(0); MMA(0, 0, At, B0); BAR; SCHED;
	s_waitcnt lgkmcnt(0)
	s_setprio 1
	v_mfma_f32_16x16x32_bf16 v[92:95], v[168:171], v[200:203], v[92:95]
	v_mfma_f32_16x16x32_bf16 v[88:91], v[168:171], v[208:211], v[88:91]
	v_mfma_f32_16x16x32_bf16 v[84:87], v[176:179], v[200:203], v[84:87]
	v_mfma_f32_16x16x32_bf16 v[80:83], v[176:179], v[208:211], v[80:83]
	v_mfma_f32_16x16x32_bf16 v[76:79], v[184:187], v[200:203], v[76:79]
	v_mfma_f32_16x16x32_bf16 v[72:75], v[184:187], v[208:211], v[72:75]
	v_mfma_f32_16x16x32_bf16 v[68:71], v[192:195], v[200:203], v[68:71]
	v_mfma_f32_16x16x32_bf16 v[64:67], v[192:195], v[208:211], v[64:67]
	v_mfma_f32_16x16x32_bf16 v[92:95], v[172:175], v[204:207], v[92:95]
	v_mfma_f32_16x16x32_bf16 v[88:91], v[172:175], v[212:215], v[88:91]
	v_mfma_f32_16x16x32_bf16 v[84:87], v[180:183], v[204:207], v[84:87]
	v_mfma_f32_16x16x32_bf16 v[80:83], v[180:183], v[212:215], v[80:83]
	v_mfma_f32_16x16x32_bf16 v[76:79], v[188:191], v[204:207], v[76:79]
	v_mfma_f32_16x16x32_bf16 v[72:75], v[188:191], v[212:215], v[72:75]
	v_mfma_f32_16x16x32_bf16 v[68:71], v[196:199], v[204:207], v[68:71]
	v_mfma_f32_16x16x32_bf16 v[64:67], v[196:199], v[212:215], v[64:67]
	s_setprio 0
	s_barrier
	ds_read_b128 v[168:171], v149 offset:16384
	ds_read_b128 v[172:175], v149 offset:17408
	ds_read_b128 v[176:179], v150 offset:16384
	ds_read_b128 v[180:183], v150 offset:17408
	ds_read_b128 v[184:187], v151 offset:16384
	ds_read_b128 v[188:191], v151 offset:17408
	ds_read_b128 v[192:195], v152 offset:16384
	ds_read_b128 v[196:199], v152 offset:17408
	s_add_i32 s39, s37, 0x100
	s_mov_b32 m0, s14
	s_nop 0
	buffer_load_dwordx4 v136, s[48:51], s39 offen lds
	s_add_i32 s40, s37, 0x40100
	s_mov_b32 m0, s17
	s_nop 0
	buffer_load_dwordx4 v136, s[48:51], s40 offen lds
	s_waitcnt vmcnt(10)
	s_barrier
	s_waitcnt lgkmcnt(0)
	s_setprio 1
	v_mfma_f32_16x16x32_bf16 v[60:63], v[168:171], v[132:135], v[60:63]
	v_mfma_f32_16x16x32_bf16 v[56:59], v[168:171], v[160:163], v[56:59]
	v_mfma_f32_16x16x32_bf16 v[52:55], v[176:179], v[132:135], v[52:55]
	v_mfma_f32_16x16x32_bf16 v[48:51], v[176:179], v[160:163], v[48:51]
	v_mfma_f32_16x16x32_bf16 v[44:47], v[184:187], v[132:135], v[44:47]
	v_mfma_f32_16x16x32_bf16 v[40:43], v[184:187], v[160:163], v[40:43]
	v_mfma_f32_16x16x32_bf16 v[36:39], v[192:195], v[132:135], v[36:39]
	v_mfma_f32_16x16x32_bf16 v[32:35], v[192:195], v[160:163], v[32:35]
	v_mfma_f32_16x16x32_bf16 v[60:63], v[172:175], v[156:159], v[60:63]
	v_mfma_f32_16x16x32_bf16 v[56:59], v[172:175], v[164:167], v[56:59]
	v_mfma_f32_16x16x32_bf16 v[52:55], v[180:183], v[156:159], v[52:55]
	v_mfma_f32_16x16x32_bf16 v[48:51], v[180:183], v[164:167], v[48:51]
	v_mfma_f32_16x16x32_bf16 v[44:47], v[188:191], v[156:159], v[44:47]
	v_mfma_f32_16x16x32_bf16 v[40:43], v[188:191], v[164:167], v[40:43]
	v_mfma_f32_16x16x32_bf16 v[36:39], v[196:199], v[156:159], v[36:39]
	v_mfma_f32_16x16x32_bf16 v[32:35], v[196:199], v[164:167], v[32:35]
	s_setprio 0
	s_barrier
	ds_read_b128 v[132:135], v154
	ds_read_b128 v[156:159], v154 offset:1024
	ds_read_b128 v[160:163], v154 offset:2048
	ds_read_b128 v[164:167], v154 offset:3072
	s_add_i32 s40, s38, 0x2100
	s_mov_b32 m0, s18
	s_nop 0
	buffer_load_dwordx4 v137, s[80:83], s40 offen lds
	s_add_i32 s40, s38, 0x82100
	s_mov_b32 m0, s19
	s_nop 0
	buffer_load_dwordx4 v137, s[80:83], s40 offen lds
	s_waitcnt vmcnt(6)
	s_barrier
	s_setprio 1
	v_mfma_f32_16x16x32_bf16 v[28:31], v[168:171], v[200:203], v[28:31]
	v_mfma_f32_16x16x32_bf16 v[24:27], v[168:171], v[208:211], v[24:27]
	v_mfma_f32_16x16x32_bf16 v[20:23], v[176:179], v[200:203], v[20:23]
	v_mfma_f32_16x16x32_bf16 v[16:19], v[176:179], v[208:211], v[16:19]
	v_mfma_f32_16x16x32_bf16 v[12:15], v[184:187], v[200:203], v[12:15]
	v_mfma_f32_16x16x32_bf16 v[8:11], v[184:187], v[208:211], v[8:11]
	v_mfma_f32_16x16x32_bf16 v[4:7], v[192:195], v[200:203], v[4:7]
	v_mfma_f32_16x16x32_bf16 v[0:3], v[192:195], v[208:211], v[0:3]
	v_mfma_f32_16x16x32_bf16 v[28:31], v[172:175], v[204:207], v[28:31]
	v_mfma_f32_16x16x32_bf16 v[24:27], v[172:175], v[212:215], v[24:27]
	v_mfma_f32_16x16x32_bf16 v[20:23], v[180:183], v[204:207], v[20:23]
	v_mfma_f32_16x16x32_bf16 v[16:19], v[180:183], v[212:215], v[16:19]
	v_mfma_f32_16x16x32_bf16 v[12:15], v[188:191], v[204:207], v[12:15]
	v_mfma_f32_16x16x32_bf16 v[8:11], v[188:191], v[212:215], v[8:11]
	v_mfma_f32_16x16x32_bf16 v[4:7], v[196:199], v[204:207], v[4:7]
	v_mfma_f32_16x16x32_bf16 v[0:3], v[196:199], v[212:215], v[0:3]
	s_setprio 0
	s_barrier
	ds_read_b128 v[168:171], v149 offset:32768
	ds_read_b128 v[172:175], v149 offset:33792
	ds_read_b128 v[176:179], v150 offset:32768
	ds_read_b128 v[180:183], v150 offset:33792
	ds_read_b128 v[184:187], v151 offset:32768
	ds_read_b128 v[188:191], v151 offset:33792
	ds_read_b128 v[192:195], v152 offset:32768
	ds_read_b128 v[196:199], v152 offset:33792
	s_or_b32 s40, s39, 0x80000
	s_mov_b32 m0, s21
	s_nop 0
	buffer_load_dwordx4 v136, s[48:51], s40 offen lds
	s_or_b32 s39, s39, 0xc0000
	s_mov_b32 m0, s22
	s_nop 0
	buffer_load_dwordx4 v136, s[48:51], s39 offen lds
	s_waitcnt lgkmcnt(8)
	s_barrier
; #define STAGE_A(POFF, h, kt) STAGE_AX(POFF, h, kt, brow)
; #define STAGE_B(POFF, h, kt) STAGE_BX(POFF, h, kt, bcol)
; #define LDA(dst, b, h) _Pragma("unroll") for (int m = 0; m < 4; ++m) _Pragma("unroll") for (int k = 0; k < 2; ++k) \
;     dst[m][k] = *reinterpret_cast<const bf16x8*>((char*)SA(b, h) + lds_byte(wr * 64 + m * 16 + fr, k * 32 + fq * 8))
; #define LDB(dst, b, h) _Pragma("unroll") for (int n = 0; n < 2; ++n) _Pragma("unroll") for (int k = 0; k < 2; ++k) \
;     dst[n][k] = *reinterpret_cast<const bf16x8*>((char*)SB(b, h) + lds_byte(wc * 32 + n * 16 + fr, k * 32 + fq * 8))
; #define MMA(ai, bj, At_, Bt_) do { __builtin_amdgcn_s_setprio(1); \
;     _Pragma("unroll") for (int k = 0; k < 2; ++k) _Pragma("unroll") for (int m = 0; m < 4; ++m) _Pragma("unroll") for (int n = 0; n < 2; ++n) \
;       acc[ai][bj][m][n] = __builtin_amdgcn_mfma_f32_16x16x32_bf16(At_[m][k], Bt_[n][k], acc[ai][bj][m][n], 0, 0, 0); \
;     __builtin_amdgcn_s_setprio(0); } while (0)
; #define WAIT_V(n) asm volatile("s_waitcnt vmcnt(" #n ")" ::: "memory")
; #define BAR __builtin_amdgcn_s_barrier()
; #define SCHED __builtin_amdgcn_sched_barrier(0)
; template <int EPI, int N, int K>
; __device__ __forceinline__ void gemm_phase(const bf16_t* __restrict__ A, const bf16_t* __restrict__ Bt, const EpiArgs ea) {
;     ...
;       WAIT_L(8); BAR; WAIT_L(0); MMA(0, 0, At, B0); BAR; SCHED;
;       LDB(B1, 1, 1); STAGE_B(SB_OFF(1, 0), 0, t + 3);
;       BAR; WAIT_L(0); MMA(0, 1, At, B1); BAR;
;       LDA(At, 1, 1); STAGE_A(SA_OFF(1, 0), 0, t + 3);
;       BAR; WAIT_L(0); MMA(1, 0, At, B0); BAR; SCHED;
;       STAGE_B(SB_OFF(1, 1), 1, t + 3);
;       WAIT_V(6); BAR; MMA(1, 1, At, B1); BAR;
	s_waitcnt lgkmcnt(0)
	s_setprio 1
	v_mfma_f32_16x16x32_bf16 v[124:127], v[168:171], v[132:135], v[124:127]
	v_mfma_f32_16x16x32_bf16 v[120:123], v[168:171], v[160:163], v[120:123]
	v_mfma_f32_16x16x32_bf16 v[116:119], v[176:179], v[132:135], v[116:119]
	v_mfma_f32_16x16x32_bf16 v[112:115], v[176:179], v[160:163], v[112:115]
	v_mfma_f32_16x16x32_bf16 v[108:111], v[184:187], v[132:135], v[108:111]
	v_mfma_f32_16x16x32_bf16 v[104:107], v[184:187], v[160:163], v[104:107]
	v_mfma_f32_16x16x32_bf16 v[100:103], v[192:195], v[132:135], v[100:103]
	v_mfma_f32_16x16x32_bf16 v[96:99], v[192:195], v[160:163], v[96:99]
	v_mfma_f32_16x16x32_bf16 v[124:127], v[172:175], v[156:159], v[124:127]
	v_mfma_f32_16x16x32_bf16 v[120:123], v[172:175], v[164:167], v[120:123]
	v_mfma_f32_16x16x32_bf16 v[116:119], v[180:183], v[156:159], v[116:119]
	v_mfma_f32_16x16x32_bf16 v[112:115], v[180:183], v[164:167], v[112:115]
	v_mfma_f32_16x16x32_bf16 v[108:111], v[188:191], v[156:159], v[108:111]
	v_mfma_f32_16x16x32_bf16 v[104:107], v[188:191], v[164:167], v[104:107]
	v_mfma_f32_16x16x32_bf16 v[100:103], v[196:199], v[156:159], v[100:103]
	v_mfma_f32_16x16x32_bf16 v[96:99], v[196:199], v[164:167], v[96:99]
	s_setprio 0
	s_barrier
	ds_read_b128 v[200:203], v155
	ds_read_b128 v[204:207], v155 offset:1024
	ds_read_b128 v[208:211], v155 offset:2048
	ds_read_b128 v[212:215], v155 offset:3072
	s_add_i32 s39, s38, 0x180
	s_mov_b32 m0, s23
	s_nop 0
	buffer_load_dwordx4 v137, s[80:83], s39 offen lds
	s_add_i32 s39, s38, 0x80180
	s_mov_b32 m0, s24
	s_nop 0
	buffer_load_dwordx4 v137, s[80:83], s39 offen lds
	s_barrier
	s_waitcnt lgkmcnt(0)
	s_setprio 1
	v_mfma_f32_16x16x32_bf16 v[92:95], v[168:171], v[200:203], v[92:95]
	v_mfma_f32_16x16x32_bf16 v[88:91], v[168:171], v[208:211], v[88:91]
	v_mfma_f32_16x16x32_bf16 v[84:87], v[176:179], v[200:203], v[84:87]
	v_mfma_f32_16x16x32_bf16 v[80:83], v[176:179], v[208:211], v[80:83]
	v_mfma_f32_16x16x32_bf16 v[76:79], v[184:187], v[200:203], v[76:79]
	v_mfma_f32_16x16x32_bf16 v[72:75], v[184:187], v[208:211], v[72:75]
	v_mfma_f32_16x16x32_bf16 v[68:71], v[192:195], v[200:203], v[68:71]
	v_mfma_f32_16x16x32_bf16 v[64:67], v[192:195], v[208:211], v[64:67]
	v_mfma_f32_16x16x32_bf16 v[92:95], v[172:175], v[204:207], v[92:95]
	v_mfma_f32_16x16x32_bf16 v[88:91], v[172:175], v[212:215], v[88:91]
	v_mfma_f32_16x16x32_bf16 v[84:87], v[180:183], v[204:207], v[84:87]
	v_mfma_f32_16x16x32_bf16 v[80:83], v[180:183], v[212:215], v[80:83]
	v_mfma_f32_16x16x32_bf16 v[76:79], v[188:191], v[204:207], v[76:79]
	v_mfma_f32_16x16x32_bf16 v[72:75], v[188:191], v[212:215], v[72:75]
	v_mfma_f32_16x16x32_bf16 v[68:71], v[196:199], v[204:207], v[68:71]
	v_mfma_f32_16x16x32_bf16 v[64:67], v[196:199], v[212:215], v[64:67]
	s_setprio 0
	s_barrier
	ds_read_b128 v[168:171], v149 offset:49152
	ds_read_b128 v[172:175], v149 offset:50176
	ds_read_b128 v[176:179], v150 offset:49152
	ds_read_b128 v[180:183], v150 offset:50176
	ds_read_b128 v[184:187], v151 offset:49152
	ds_read_b128 v[188:191], v151 offset:50176
	ds_read_b128 v[192:195], v152 offset:49152
	ds_read_b128 v[196:199], v152 offset:50176
	s_add_i32 s39, s37, 0x180
	s_mov_b32 m0, s25
	s_nop 0
	buffer_load_dwordx4 v136, s[48:51], s39 offen lds
	s_add_i32 s37, s37, 0x40180
	s_mov_b32 m0, s26
	s_nop 0
	buffer_load_dwordx4 v136, s[48:51], s37 offen lds
	s_waitcnt vmcnt(10)
	s_barrier
	s_waitcnt lgkmcnt(0)
	s_setprio 1
	v_mfma_f32_16x16x32_bf16 v[60:63], v[168:171], v[132:135], v[60:63]
	v_mfma_f32_16x16x32_bf16 v[56:59], v[168:171], v[160:163], v[56:59]
	v_mfma_f32_16x16x32_bf16 v[52:55], v[176:179], v[132:135], v[52:55]
	v_mfma_f32_16x16x32_bf16 v[48:51], v[176:179], v[160:163], v[48:51]
	v_mfma_f32_16x16x32_bf16 v[44:47], v[184:187], v[132:135], v[44:47]
	v_mfma_f32_16x16x32_bf16 v[40:43], v[184:187], v[160:163], v[40:43]
	v_mfma_f32_16x16x32_bf16 v[36:39], v[192:195], v[132:135], v[36:39]
	v_mfma_f32_16x16x32_bf16 v[32:35], v[192:195], v[160:163], v[32:35]
	v_mfma_f32_16x16x32_bf16 v[60:63], v[172:175], v[156:159], v[60:63]
	v_mfma_f32_16x16x32_bf16 v[56:59], v[172:175], v[164:167], v[56:59]
	v_mfma_f32_16x16x32_bf16 v[52:55], v[180:183], v[156:159], v[52:55]
	v_mfma_f32_16x16x32_bf16 v[48:51], v[180:183], v[164:167], v[48:51]
	v_mfma_f32_16x16x32_bf16 v[44:47], v[188:191], v[156:159], v[44:47]
	v_mfma_f32_16x16x32_bf16 v[40:43], v[188:191], v[164:167], v[40:43]
	v_mfma_f32_16x16x32_bf16 v[36:39], v[196:199], v[156:159], v[36:39]
	v_mfma_f32_16x16x32_bf16 v[32:35], v[196:199], v[164:167], v[32:35]
	s_setprio 0
	s_barrier
	ds_read_b128 v[132:135], v148
	ds_read_b128 v[156:159], v148 offset:1024
	ds_read_b128 v[160:163], v148 offset:2048
	ds_read_b128 v[164:167], v148 offset:3072
	s_add_i32 s37, s38, 0x2180
	s_mov_b32 m0, s27
	s_nop 0
	buffer_load_dwordx4 v137, s[80:83], s37 offen lds
	s_add_i32 s38, s38, 0x82180
	s_mov_b32 m0, s28
	s_nop 0
	buffer_load_dwordx4 v137, s[80:83], s38 offen lds
	s_waitcnt vmcnt(6)
	s_barrier
	s_setprio 1
	v_mfma_f32_16x16x32_bf16 v[28:31], v[168:171], v[200:203], v[28:31]
	v_mfma_f32_16x16x32_bf16 v[24:27], v[168:171], v[208:211], v[24:27]
	v_mfma_f32_16x16x32_bf16 v[20:23], v[176:179], v[200:203], v[20:23]
	v_mfma_f32_16x16x32_bf16 v[16:19], v[176:179], v[208:211], v[16:19]
	v_mfma_f32_16x16x32_bf16 v[12:15], v[184:187], v[200:203], v[12:15]
	v_mfma_f32_16x16x32_bf16 v[8:11], v[184:187], v[208:211], v[8:11]
	v_mfma_f32_16x16x32_bf16 v[4:7], v[192:195], v[200:203], v[4:7]
	v_mfma_f32_16x16x32_bf16 v[0:3], v[192:195], v[208:211], v[0:3]
	v_mfma_f32_16x16x32_bf16 v[28:31], v[172:175], v[204:207], v[28:31]
	v_mfma_f32_16x16x32_bf16 v[24:27], v[172:175], v[212:215], v[24:27]
	v_mfma_f32_16x16x32_bf16 v[20:23], v[180:183], v[204:207], v[20:23]
	v_mfma_f32_16x16x32_bf16 v[16:19], v[180:183], v[212:215], v[16:19]
	v_mfma_f32_16x16x32_bf16 v[12:15], v[188:191], v[204:207], v[12:15]
	v_mfma_f32_16x16x32_bf16 v[8:11], v[188:191], v[212:215], v[8:11]
	v_mfma_f32_16x16x32_bf16 v[4:7], v[196:199], v[204:207], v[4:7]
	v_mfma_f32_16x16x32_bf16 v[0:3], v[196:199], v[212:215], v[0:3]
	s_setprio 0
	s_add_i32 s35, s35, 2
	s_addk_i32 s36, 0x100
	s_cmp_lt_u32 s35, 28
	s_barrier
; #define STAGE_A(POFF, h, kt) STAGE_AX(POFF, h, kt, brow)
; #define LDA(dst, b, h) _Pragma("unroll") for (int m = 0; m < 4; ++m) _Pragma("unroll") for (int k = 0; k < 2; ++k) \
;     dst[m][k] = *reinterpret_cast<const bf16x8*>((char*)SA(b, h) + lds_byte(wr * 64 + m * 16 + fr, k * 32 + fq * 8))
; #define LDB(dst, b, h) _Pragma("unroll") for (int n = 0; n < 2; ++n) _Pragma("unroll") for (int k = 0; k < 2; ++k) \
;     dst[n][k] = *reinterpret_cast<const bf16x8*>((char*)SB(b, h) + lds_byte(wc * 32 + n * 16 + fr, k * 32 + fq * 8))
; #define MMA(ai, bj, At_, Bt_) do { __builtin_amdgcn_s_setprio(1); \
;     _Pragma("unroll") for (int k = 0; k < 2; ++k) _Pragma("unroll") for (int m = 0; m < 4; ++m) _Pragma("unroll") for (int n = 0; n < 2; ++n) \
;       acc[ai][bj][m][n] = __builtin_amdgcn_mfma_f32_16x16x32_bf16(At_[m][k], Bt_[n][k], acc[ai][bj][m][n], 0, 0, 0); \
;     __builtin_amdgcn_s_setprio(0); } while (0)
; #define WAIT_V(n) asm volatile("s_waitcnt vmcnt(" #n ")" ::: "memory")
; #define BAR __builtin_amdgcn_s_barrier()
; template <int EPI, int N, int K>
; __device__ __forceinline__ void gemm_phase(const bf16_t* __restrict__ A, const bf16_t* __restrict__ Bt, const EpiArgs ea) {
;     ...
;     { LDB(B0, 0, 0); LDA(At, 0, 0); STAGE_A(SA_OFF(1, 1), 1, nt - 1);
;       BAR; WAIT_L(0); MMA(0, 0, At, B0); BAR;
;       LDB(B1, 0, 1); BAR; WAIT_L(0); MMA(0, 1, At, B1); BAR;
;       LDA(At, 0, 1); WAIT_V(4); BAR; WAIT_L(0); MMA(1, 0, At, B0); MMA(1, 1, At, B1); BAR; }
;     { LDB(B0, 1, 0); LDA(At, 1, 0); WAIT_V(2); BAR; WAIT_L(0); MMA(0, 0, At, B0); BAR;
	s_cbranch_scc1 .LBB0_509
	ds_read_b128 v[168:171], v149
	ds_read_b128 v[172:175], v149 offset:1024
	ds_read_b128 v[176:179], v150
	ds_read_b128 v[180:183], v150 offset:1024
	ds_read_b128 v[184:187], v151
	ds_read_b128 v[188:191], v151 offset:1024
	ds_read_b128 v[192:195], v152
	ds_read_b128 v[196:199], v152 offset:1024
	s_and_b32 s3, s3, 0x700
	s_lshl_b32 s2, s2, 11
	s_or_b32 s34, s3, s2
	s_lshl_b32 s2, s34, 12
	s_or_b32 s3, s2, 0x80f80
	s_mov_b32 m0, s29
	s_nop 0
	buffer_load_dwordx4 v136, s[48:51], s3 offen lds
	s_or_b32 s2, s2, 0xc0f80
	s_mov_b32 m0, s30
	s_nop 0
	buffer_load_dwordx4 v136, s[48:51], s2 offen lds
	s_barrier
	s_waitcnt lgkmcnt(0)
	s_setprio 1
	v_mfma_f32_16x16x32_bf16 v[124:127], v[168:171], v[132:135], v[124:127]
	v_mfma_f32_16x16x32_bf16 v[120:123], v[168:171], v[160:163], v[120:123]
	v_mfma_f32_16x16x32_bf16 v[116:119], v[176:179], v[132:135], v[116:119]
	v_mfma_f32_16x16x32_bf16 v[112:115], v[176:179], v[160:163], v[112:115]
	v_mfma_f32_16x16x32_bf16 v[108:111], v[184:187], v[132:135], v[108:111]
	v_mfma_f32_16x16x32_bf16 v[104:107], v[184:187], v[160:163], v[104:107]
	v_mfma_f32_16x16x32_bf16 v[100:103], v[192:195], v[132:135], v[100:103]
	v_mfma_f32_16x16x32_bf16 v[96:99], v[192:195], v[160:163], v[96:99]
	v_mfma_f32_16x16x32_bf16 v[124:127], v[172:175], v[156:159], v[124:127]
	v_mfma_f32_16x16x32_bf16 v[120:123], v[172:175], v[164:167], v[120:123]
	v_mfma_f32_16x16x32_bf16 v[116:119], v[180:183], v[156:159], v[116:119]
	v_mfma_f32_16x16x32_bf16 v[112:115], v[180:183], v[164:167], v[112:115]
	v_mfma_f32_16x16x32_bf16 v[108:111], v[188:191], v[156:159], v[108:111]
	v_mfma_f32_16x16x32_bf16 v[104:107], v[188:191], v[164:167], v[104:107]
	v_mfma_f32_16x16x32_bf16 v[100:103], v[196:199], v[156:159], v[100:103]
	v_mfma_f32_16x16x32_bf16 v[96:99], v[196:199], v[164:167], v[96:99]
	s_setprio 0
	s_barrier
	ds_read_b128 v[200:203], v153
	ds_read_b128 v[204:207], v153 offset:1024
	ds_read_b128 v[208:211], v153 offset:2048
	ds_read_b128 v[212:215], v153 offset:3072
	s_barrier
	s_waitcnt lgkmcnt(0)
	s_setprio 1
	v_mfma_f32_16x16x32_bf16 v[92:95], v[168:171], v[200:203], v[92:95]
	v_mfma_f32_16x16x32_bf16 v[88:91], v[168:171], v[208:211], v[88:91]
	v_mfma_f32_16x16x32_bf16 v[76:79], v[184:187], v[200:203], v[76:79]
	v_mfma_f32_16x16x32_bf16 v[72:75], v[184:187], v[208:211], v[72:75]
	v_mfma_f32_16x16x32_bf16 v[84:87], v[176:179], v[200:203], v[84:87]
	v_mfma_f32_16x16x32_bf16 v[80:83], v[176:179], v[208:211], v[80:83]
	v_mfma_f32_16x16x32_bf16 v[68:71], v[192:195], v[200:203], v[68:71]
	v_mfma_f32_16x16x32_bf16 v[64:67], v[192:195], v[208:211], v[64:67]
	v_mfma_f32_16x16x32_bf16 v[92:95], v[172:175], v[204:207], v[92:95]
	v_mfma_f32_16x16x32_bf16 v[88:91], v[172:175], v[212:215], v[88:91]
	v_mfma_f32_16x16x32_bf16 v[76:79], v[188:191], v[204:207], v[76:79]
	v_mfma_f32_16x16x32_bf16 v[72:75], v[188:191], v[212:215], v[72:75]
	v_mfma_f32_16x16x32_bf16 v[168:171], v[180:183], v[204:207], v[84:87]
	v_mfma_f32_16x16x32_bf16 v[172:175], v[180:183], v[212:215], v[80:83]
	v_mfma_f32_16x16x32_bf16 v[176:179], v[196:199], v[204:207], v[68:71]
	v_mfma_f32_16x16x32_bf16 v[180:183], v[196:199], v[212:215], v[64:67]
	s_setprio 0
	s_barrier
	s_nop 0
	ds_read_b128 v[64:67], v149 offset:16384
	ds_read_b128 v[68:71], v149 offset:17408
	ds_read_b128 v[80:83], v150 offset:16384
	ds_read_b128 v[84:87], v150 offset:17408
	ds_read_b128 v[184:187], v151 offset:16384
	ds_read_b128 v[188:191], v151 offset:17408
	ds_read_b128 v[192:195], v152 offset:16384
	ds_read_b128 v[196:199], v152 offset:17408
	s_waitcnt vmcnt(4)
	s_barrier
	s_waitcnt lgkmcnt(0)
	s_setprio 1
	v_mfma_f32_16x16x32_bf16 v[60:63], v[64:67], v[132:135], v[60:63]
	v_mfma_f32_16x16x32_bf16 v[56:59], v[64:67], v[160:163], v[56:59]
	v_mfma_f32_16x16x32_bf16 v[52:55], v[80:83], v[132:135], v[52:55]
	v_mfma_f32_16x16x32_bf16 v[48:51], v[80:83], v[160:163], v[48:51]
	v_mfma_f32_16x16x32_bf16 v[44:47], v[184:187], v[132:135], v[44:47]
	v_mfma_f32_16x16x32_bf16 v[40:43], v[184:187], v[160:163], v[40:43]
	v_mfma_f32_16x16x32_bf16 v[36:39], v[192:195], v[132:135], v[36:39]
	v_mfma_f32_16x16x32_bf16 v[32:35], v[192:195], v[160:163], v[32:35]
	v_mfma_f32_16x16x32_bf16 v[60:63], v[68:71], v[156:159], v[60:63]
	v_mfma_f32_16x16x32_bf16 v[56:59], v[68:71], v[164:167], v[56:59]
	v_mfma_f32_16x16x32_bf16 v[52:55], v[84:87], v[156:159], v[52:55]
	v_mfma_f32_16x16x32_bf16 v[48:51], v[84:87], v[164:167], v[48:51]
	v_mfma_f32_16x16x32_bf16 v[44:47], v[188:191], v[156:159], v[44:47]
	v_mfma_f32_16x16x32_bf16 v[40:43], v[188:191], v[164:167], v[40:43]
	v_mfma_f32_16x16x32_bf16 v[36:39], v[196:199], v[156:159], v[36:39]
	v_mfma_f32_16x16x32_bf16 v[32:35], v[196:199], v[164:167], v[32:35]
	s_setprio 0
	s_setprio 1
	v_mfma_f32_16x16x32_bf16 v[28:31], v[64:67], v[200:203], v[28:31]
	v_mfma_f32_16x16x32_bf16 v[24:27], v[64:67], v[208:211], v[24:27]
	v_mfma_f32_16x16x32_bf16 v[12:15], v[184:187], v[200:203], v[12:15]
	v_mfma_f32_16x16x32_bf16 v[8:11], v[184:187], v[208:211], v[8:11]
	v_mfma_f32_16x16x32_bf16 v[20:23], v[80:83], v[200:203], v[20:23]
	v_mfma_f32_16x16x32_bf16 v[16:19], v[80:83], v[208:211], v[16:19]
	v_mfma_f32_16x16x32_bf16 v[4:7], v[192:195], v[200:203], v[4:7]
	v_mfma_f32_16x16x32_bf16 v[0:3], v[192:195], v[208:211], v[0:3]
	v_mfma_f32_16x16x32_bf16 v[28:31], v[68:71], v[204:207], v[28:31]
	v_mfma_f32_16x16x32_bf16 v[24:27], v[68:71], v[212:215], v[24:27]
	v_mfma_f32_16x16x32_bf16 v[12:15], v[188:191], v[204:207], v[12:15]
	v_mfma_f32_16x16x32_bf16 v[8:11], v[188:191], v[212:215], v[8:11]
	v_mfma_f32_16x16x32_bf16 v[132:135], v[84:87], v[204:207], v[20:23]
	v_mfma_f32_16x16x32_bf16 v[156:159], v[84:87], v[212:215], v[16:19]
	v_mfma_f32_16x16x32_bf16 v[160:163], v[196:199], v[204:207], v[4:7]
	v_mfma_f32_16x16x32_bf16 v[164:167], v[196:199], v[212:215], v[0:3]
	s_setprio 0
	s_barrier
; #define LDA(dst, b, h) _Pragma("unroll") for (int m = 0; m < 4; ++m) _Pragma("unroll") for (int k = 0; k < 2; ++k) \
;     dst[m][k] = *reinterpret_cast<const bf16x8*>((char*)SA(b, h) + lds_byte(wr * 64 + m * 16 + fr, k * 32 + fq * 8))
; #define LDB(dst, b, h) _Pragma("unroll") for (int n = 0; n < 2; ++n) _Pragma("unroll") for (int k = 0; k < 2; ++k) \
;     dst[n][k] = *reinterpret_cast<const bf16x8*>((char*)SB(b, h) + lds_byte(wc * 32 + n * 16 + fr, k * 32 + fq * 8))
; #define MMA(ai, bj, At_, Bt_) do { __builtin_amdgcn_s_setprio(1); \
;     _Pragma("unroll") for (int k = 0; k < 2; ++k) _Pragma("unroll") for (int m = 0; m < 4; ++m) _Pragma("unroll") for (int n = 0; n < 2; ++n) \
;       acc[ai][bj][m][n] = __builtin_amdgcn_mfma_f32_16x16x32_bf16(At_[m][k], Bt_[n][k], acc[ai][bj][m][n], 0, 0, 0); \
;     __builtin_amdgcn_s_setprio(0); } while (0)
; #define WAIT_V(n) asm volatile("s_waitcnt vmcnt(" #n ")" ::: "memory")
; #define BAR __builtin_amdgcn_s_barrier()
; template <int EPI, int N, int K>
; __device__ __forceinline__ void gemm_phase(const bf16_t* __restrict__ A, const bf16_t* __restrict__ Bt, const EpiArgs ea) {
;     ...
;     { LDB(B0, 1, 0); LDA(At, 1, 0); WAIT_V(2); BAR; WAIT_L(0); MMA(0, 0, At, B0); BAR;
;       LDB(B1, 1, 1); WAIT_V(0); BAR; WAIT_L(0); MMA(0, 1, At, B1); BAR;
;       LDA(At, 1, 1); BAR; WAIT_L(0); MMA(1, 0, At, B0); MMA(1, 1, At, B1); BAR; }
;     if (wr == 0) BAR;
	s_nop 0
	ds_read_b128 v[0:3], v154
	ds_read_b128 v[4:7], v154 offset:1024
	ds_read_b128 v[16:19], v154 offset:2048
	ds_read_b128 v[184:187], v154 offset:3072
	ds_read_b128 v[20:23], v149 offset:32768
	ds_read_b128 v[188:191], v149 offset:33792
	ds_read_b128 v[192:195], v150 offset:32768
	ds_read_b128 v[196:199], v150 offset:33792
	ds_read_b128 v[200:203], v151 offset:32768
	ds_read_b128 v[204:207], v151 offset:33792
	ds_read_b128 v[208:211], v152 offset:32768
	ds_read_b128 v[212:215], v152 offset:33792
	s_waitcnt vmcnt(2)
	s_barrier
	s_waitcnt lgkmcnt(0)
	s_setprio 1
	v_mfma_f32_16x16x32_bf16 v[64:67], v[20:23], v[0:3], v[124:127]
	v_mfma_f32_16x16x32_bf16 v[68:71], v[20:23], v[16:19], v[120:123]
	v_mfma_f32_16x16x32_bf16 v[80:83], v[192:195], v[0:3], v[116:119]
	v_mfma_f32_16x16x32_bf16 v[84:87], v[192:195], v[16:19], v[112:115]
	v_mfma_f32_16x16x32_bf16 v[108:111], v[200:203], v[0:3], v[108:111]
	v_mfma_f32_16x16x32_bf16 v[104:107], v[200:203], v[16:19], v[104:107]
	v_mfma_f32_16x16x32_bf16 v[120:123], v[208:211], v[0:3], v[100:103]
	v_mfma_f32_16x16x32_bf16 v[124:127], v[208:211], v[16:19], v[96:99]
	v_mfma_f32_16x16x32_bf16 v[112:115], v[188:191], v[4:7], v[64:67]
	v_mfma_f32_16x16x32_bf16 v[116:119], v[188:191], v[184:187], v[68:71]
	v_mfma_f32_16x16x32_bf16 v[96:99], v[196:199], v[4:7], v[80:83]
	v_mfma_f32_16x16x32_bf16 v[100:103], v[196:199], v[184:187], v[84:87]
	v_mfma_f32_16x16x32_bf16 v[80:83], v[204:207], v[4:7], v[108:111]
	v_mfma_f32_16x16x32_bf16 v[84:87], v[204:207], v[184:187], v[104:107]
	v_mfma_f32_16x16x32_bf16 v[64:67], v[212:215], v[4:7], v[120:123]
	v_mfma_f32_16x16x32_bf16 v[68:71], v[212:215], v[184:187], v[124:127]
	s_setprio 0
	s_barrier
	ds_read_b128 v[216:219], v155
	ds_read_b128 v[220:223], v155 offset:1024
	ds_read_b128 v[224:227], v155 offset:2048
	ds_read_b128 v[228:231], v155 offset:3072
	s_waitcnt vmcnt(0)
	s_barrier
	s_waitcnt lgkmcnt(0)
	s_setprio 1
	v_mfma_f32_16x16x32_bf16 v[92:95], v[20:23], v[216:219], v[92:95]
	v_mfma_f32_16x16x32_bf16 v[20:23], v[20:23], v[224:227], v[88:91]
	v_mfma_f32_16x16x32_bf16 v[88:91], v[192:195], v[216:219], v[168:171]
	v_mfma_f32_16x16x32_bf16 v[108:111], v[192:195], v[224:227], v[172:175]
	v_mfma_f32_16x16x32_bf16 v[76:79], v[200:203], v[216:219], v[76:79]
	v_mfma_f32_16x16x32_bf16 v[72:75], v[200:203], v[224:227], v[72:75]
	v_mfma_f32_16x16x32_bf16 v[168:171], v[208:211], v[216:219], v[176:179]
	v_mfma_f32_16x16x32_bf16 v[172:175], v[208:211], v[224:227], v[180:183]
	v_mfma_f32_16x16x32_bf16 v[120:123], v[188:191], v[220:223], v[92:95]
	v_mfma_f32_16x16x32_bf16 v[124:127], v[188:191], v[228:231], v[20:23]
	v_mfma_f32_16x16x32_bf16 v[104:107], v[196:199], v[220:223], v[88:91]
	v_mfma_f32_16x16x32_bf16 v[108:111], v[196:199], v[228:231], v[108:111]
	v_mfma_f32_16x16x32_bf16 v[88:91], v[204:207], v[220:223], v[76:79]
	v_mfma_f32_16x16x32_bf16 v[92:95], v[204:207], v[228:231], v[72:75]
	v_mfma_f32_16x16x32_bf16 v[72:75], v[212:215], v[220:223], v[168:171]
	v_mfma_f32_16x16x32_bf16 v[76:79], v[212:215], v[228:231], v[172:175]
	s_setprio 0
	s_barrier
	ds_read_b128 v[168:171], v149 offset:49152
	ds_read_b128 v[172:175], v149 offset:50176
	ds_read_b128 v[176:179], v150 offset:49152
	ds_read_b128 v[180:183], v150 offset:50176
	ds_read_b128 v[188:191], v151 offset:49152
	ds_read_b128 v[192:195], v151 offset:50176
	ds_read_b128 v[196:199], v152 offset:49152
	ds_read_b128 v[200:203], v152 offset:50176
	s_barrier
	s_waitcnt lgkmcnt(0)
	s_setprio 1
	v_mfma_f32_16x16x32_bf16 v[20:23], v[168:171], v[0:3], v[60:63]
	v_mfma_f32_16x16x32_bf16 v[56:59], v[168:171], v[16:19], v[56:59]
	v_mfma_f32_16x16x32_bf16 v[60:63], v[176:179], v[0:3], v[52:55]
	v_mfma_f32_16x16x32_bf16 v[204:207], v[176:179], v[16:19], v[48:51]
	v_mfma_f32_16x16x32_bf16 v[44:47], v[188:191], v[0:3], v[44:47]
	v_mfma_f32_16x16x32_bf16 v[40:43], v[188:191], v[16:19], v[40:43]
	v_mfma_f32_16x16x32_bf16 v[0:3], v[196:199], v[0:3], v[36:39]
	v_mfma_f32_16x16x32_bf16 v[208:211], v[196:199], v[16:19], v[32:35]
	v_mfma_f32_16x16x32_bf16 v[48:51], v[172:175], v[4:7], v[20:23]
	v_mfma_f32_16x16x32_bf16 v[52:55], v[172:175], v[184:187], v[56:59]
	v_mfma_f32_16x16x32_bf16 v[32:35], v[180:183], v[4:7], v[60:63]
	v_mfma_f32_16x16x32_bf16 v[36:39], v[180:183], v[184:187], v[204:207]
	v_mfma_f32_16x16x32_bf16 v[16:19], v[192:195], v[4:7], v[44:47]
	v_mfma_f32_16x16x32_bf16 v[20:23], v[192:195], v[184:187], v[40:43]
	v_mfma_f32_16x16x32_bf16 v[0:3], v[200:203], v[4:7], v[0:3]
	v_mfma_f32_16x16x32_bf16 v[4:7], v[200:203], v[184:187], v[208:211]
	s_setprio 0
	s_setprio 1
	v_mfma_f32_16x16x32_bf16 v[28:31], v[168:171], v[216:219], v[28:31]
	v_mfma_f32_16x16x32_bf16 v[24:27], v[168:171], v[224:227], v[24:27]
	v_mfma_f32_16x16x32_bf16 v[40:43], v[176:179], v[216:219], v[132:135]
	v_mfma_f32_16x16x32_bf16 v[44:47], v[176:179], v[224:227], v[156:159]
	v_mfma_f32_16x16x32_bf16 v[12:15], v[188:191], v[216:219], v[12:15]
	v_mfma_f32_16x16x32_bf16 v[8:11], v[188:191], v[224:227], v[8:11]
	v_mfma_f32_16x16x32_bf16 v[132:135], v[196:199], v[216:219], v[160:163]
	v_mfma_f32_16x16x32_bf16 v[156:159], v[196:199], v[224:227], v[164:167]
	v_mfma_f32_16x16x32_bf16 v[56:59], v[172:175], v[220:223], v[28:31]
	v_mfma_f32_16x16x32_bf16 v[60:63], v[172:175], v[228:231], v[24:27]
	v_mfma_f32_16x16x32_bf16 v[40:43], v[180:183], v[220:223], v[40:43]
	v_mfma_f32_16x16x32_bf16 v[44:47], v[180:183], v[228:231], v[44:47]
	v_mfma_f32_16x16x32_bf16 v[24:27], v[192:195], v[220:223], v[12:15]
	v_mfma_f32_16x16x32_bf16 v[28:31], v[192:195], v[228:231], v[8:11]
	v_mfma_f32_16x16x32_bf16 v[8:11], v[200:203], v[220:223], v[132:135]
	v_mfma_f32_16x16x32_bf16 v[12:15], v[200:203], v[228:231], v[156:159]
	s_setprio 0
	s_barrier
	s_and_saveexec_b64 s[2:3], s[8:9]
	s_cbranch_execz .LBB0_512
	s_barrier

; #define STAGE_A(POFF, h, kt) STAGE_AX(POFF, h, kt, brow)
; #define STAGE_B(POFF, h, kt) STAGE_BX(POFF, h, kt, bcol)
; #define LDA(dst, b, h) _Pragma("unroll") for (int m = 0; m < 4; ++m) _Pragma("unroll") for (int k = 0; k < 2; ++k) \
;     dst[m][k] = *reinterpret_cast<const bf16x8*>((char*)SA(b, h) + lds_byte(wr * 64 + m * 16 + fr, k * 32 + fq * 8))
; #define LDB(dst, b, h) _Pragma("unroll") for (int n = 0; n < 2; ++n) _Pragma("unroll") for (int k = 0; k < 2; ++k) \
;     dst[n][k] = *reinterpret_cast<const bf16x8*>((char*)SB(b, h) + lds_byte(wc * 32 + n * 16 + fr, k * 32 + fq * 8))
; #define MMA(ai, bj, At_, Bt_) do { __builtin_amdgcn_s_setprio(1); \
;     _Pragma("unroll") for (int k = 0; k < 2; ++k) _Pragma("unroll") for (int m = 0; m < 4; ++m) _Pragma("unroll") for (int n = 0; n < 2; ++n) \
;       acc[ai][bj][m][n] = __builtin_amdgcn_mfma_f32_16x16x32_bf16(At_[m][k], Bt_[n][k], acc[ai][bj][m][n], 0, 0, 0); \
;     __builtin_amdgcn_s_setprio(0); } while (0)
; #define WAIT_V(n) asm volatile("s_waitcnt vmcnt(" #n ")" ::: "memory")
; #define BAR __builtin_amdgcn_s_barrier()
; #define SCHED __builtin_amdgcn_sched_barrier(0)
; #define TILE_RC(w_, brow_, bcol_) do { const int wg_ = ((w_) & 7) * qx + ((w_) >> 3); const int gid_ = wg_ / nig; \
;     brow_ = (gid_ * 8 + ((wg_ % nig) & 7)) * 256; bcol_ = ((wg_ % nig) >> 3) * 256; } while (0)
; template <int EPI, int N, int K>
; __device__ __forceinline__ void gemm_phase(const bf16_t* __restrict__ A, const bf16_t* __restrict__ Bt, const EpiArgs ea) {
;     ...
;     int brow, bcol; TILE_RC(w, brow, bcol);
;     f32x4 acc[2][2][4][2];
; #pragma unroll
;     for (int a = 0; a < 2; ++a)
; #pragma unroll
;       for (int b = 0; b < 2; ++b)
; #pragma unroll
;         for (int m = 0; m < 4; ++m)
; #pragma unroll
;           for (int n = 0; n < 2; ++n) acc[a][b][m][n] = (f32x4){0.f, 0.f, 0.f, 0.f};
;     bf16x8 At[4][2], B0[2][2], B1[2][2];
;     if (wr == 1) BAR;
;     if (w == (int)blockIdx.x) { WAIT_V(0); } else { WAIT_V(24); }
;     BAR;
;     BAR;
;     for (int t = 0; t < nt - 2; t += 2) {
;       LDB(B0, 0, 0); SCHED; LDA(At, 0, 0); STAGE_A(SA_OFF(1, 1), 1, t + 1);
;       WAIT_L(8); BAR; WAIT_L(0); MMA(0, 0, At, B0); BAR; SCHED;
;       LDB(B1, 0, 1); STAGE_B(SB_OFF(0, 0), 0, t + 2);
.LBB0_567:
	s_lshl_b32 s2, s28, 6
	s_and_b32 s2, s2, 0x1c0
	s_ashr_i32 s3, s28, 3
	s_add_i32 s3, s2, s3
	s_ashr_i32 s2, s3, 31
	s_lshr_b32 s2, s2, 26
	s_add_i32 s10, s3, s2
	s_ashr_i32 s2, s10, 6
	s_andn2_b32 s10, s10, 63
	s_sub_i32 s29, s3, s10
	s_lshl_b32 s3, s29, 8
	s_lshl_b32 s10, s29, 5
	s_lshl_b32 s11, s29, 19
	s_and_b32 s29, s29, 7
	s_lshl_b32 s30, s2, 25
	s_lshl_b32 s29, s29, 22
	v_mov_b32_e32 v0, 0
	s_and_b32 s11, s11, 0xffc00000
	s_or_b32 s29, s30, s29
	s_mov_b32 s30, -2
	s_mov_b32 s31, 0
	v_mov_b32_e32 v1, v0
	v_mov_b32_e32 v2, v0
	v_mov_b32_e32 v3, v0
	v_mov_b32_e32 v4, v0
	v_mov_b32_e32 v5, v0
	v_mov_b32_e32 v6, v0
	v_mov_b32_e32 v7, v0
	v_mov_b32_e32 v8, v0
	v_mov_b32_e32 v9, v0
	v_mov_b32_e32 v10, v0
	v_mov_b32_e32 v11, v0
	v_mov_b32_e32 v12, v0
	v_mov_b32_e32 v13, v0
	v_mov_b32_e32 v14, v0
	v_mov_b32_e32 v15, v0
	v_mov_b32_e32 v16, v0
	v_mov_b32_e32 v17, v0
	v_mov_b32_e32 v18, v0
	v_mov_b32_e32 v19, v0
	v_mov_b32_e32 v20, v0
	v_mov_b32_e32 v21, v0
	v_mov_b32_e32 v22, v0
	v_mov_b32_e32 v23, v0
	v_mov_b32_e32 v24, v0
	v_mov_b32_e32 v25, v0
	v_mov_b32_e32 v26, v0
	v_mov_b32_e32 v27, v0
	v_mov_b32_e32 v28, v0
	v_mov_b32_e32 v29, v0
	v_mov_b32_e32 v30, v0
	v_mov_b32_e32 v31, v0
	v_mov_b32_e32 v32, v0
	v_mov_b32_e32 v33, v0
	v_mov_b32_e32 v34, v0
	v_mov_b32_e32 v35, v0
	v_mov_b32_e32 v36, v0
	v_mov_b32_e32 v37, v0
	v_mov_b32_e32 v38, v0
	v_mov_b32_e32 v39, v0
	v_mov_b32_e32 v40, v0
	v_mov_b32_e32 v41, v0
	v_mov_b32_e32 v42, v0
	v_mov_b32_e32 v43, v0
	v_mov_b32_e32 v44, v0
	v_mov_b32_e32 v45, v0
	v_mov_b32_e32 v46, v0
	v_mov_b32_e32 v47, v0
	v_mov_b32_e32 v48, v0
	v_mov_b32_e32 v49, v0
	v_mov_b32_e32 v50, v0
	v_mov_b32_e32 v51, v0
	v_mov_b32_e32 v52, v0
	v_mov_b32_e32 v53, v0
	v_mov_b32_e32 v54, v0
	v_mov_b32_e32 v55, v0
	v_mov_b32_e32 v56, v0
	v_mov_b32_e32 v57, v0
	v_mov_b32_e32 v58, v0
	v_mov_b32_e32 v59, v0
	v_mov_b32_e32 v60, v0
	v_mov_b32_e32 v61, v0
	v_mov_b32_e32 v62, v0
	v_mov_b32_e32 v63, v0
	v_mov_b32_e32 v64, v0
	v_mov_b32_e32 v65, v0
	v_mov_b32_e32 v66, v0
	v_mov_b32_e32 v67, v0
	v_mov_b32_e32 v68, v0
	v_mov_b32_e32 v69, v0
	v_mov_b32_e32 v70, v0
	v_mov_b32_e32 v71, v0
	v_mov_b32_e32 v72, v0
	v_mov_b32_e32 v73, v0
	v_mov_b32_e32 v74, v0
	v_mov_b32_e32 v75, v0
	v_mov_b32_e32 v76, v0
	v_mov_b32_e32 v77, v0
	v_mov_b32_e32 v78, v0
	v_mov_b32_e32 v79, v0
	v_mov_b32_e32 v80, v0
	v_mov_b32_e32 v81, v0
	v_mov_b32_e32 v82, v0
	v_mov_b32_e32 v83, v0
	v_mov_b32_e32 v84, v0
	v_mov_b32_e32 v85, v0
	v_mov_b32_e32 v86, v0
	v_mov_b32_e32 v87, v0
	v_mov_b32_e32 v88, v0
	v_mov_b32_e32 v89, v0
	v_mov_b32_e32 v90, v0
	v_mov_b32_e32 v91, v0
	v_mov_b32_e32 v92, v0
	v_mov_b32_e32 v93, v0
	v_mov_b32_e32 v94, v0
	v_mov_b32_e32 v95, v0
	v_mov_b32_e32 v96, v0
	v_mov_b32_e32 v97, v0
	v_mov_b32_e32 v98, v0
	v_mov_b32_e32 v99, v0
	v_mov_b32_e32 v100, v0
	v_mov_b32_e32 v101, v0
	v_mov_b32_e32 v102, v0
	v_mov_b32_e32 v103, v0
	v_mov_b32_e32 v104, v0
	v_mov_b32_e32 v105, v0
	v_mov_b32_e32 v106, v0
	v_mov_b32_e32 v107, v0
	v_mov_b32_e32 v108, v0
	v_mov_b32_e32 v109, v0
	v_mov_b32_e32 v110, v0
	v_mov_b32_e32 v111, v0
	v_mov_b32_e32 v112, v0
	v_mov_b32_e32 v113, v0
	v_mov_b32_e32 v114, v0
	v_mov_b32_e32 v115, v0
	v_mov_b32_e32 v116, v0
	v_mov_b32_e32 v117, v0
	v_mov_b32_e32 v118, v0
	v_mov_b32_e32 v119, v0
	v_mov_b32_e32 v120, v0
	v_mov_b32_e32 v121, v0
	v_mov_b32_e32 v122, v0
	v_mov_b32_e32 v123, v0
	v_mov_b32_e32 v124, v0
	v_mov_b32_e32 v125, v0
	v_mov_b32_e32 v126, v0
	v_mov_b32_e32 v127, v0
	s_barrier
	s_barrier
	ds_read_b128 v[132:135], v147
	ds_read_b128 v[156:159], v147 offset:1024
	ds_read_b128 v[160:163], v147 offset:2048
	ds_read_b128 v[164:167], v147 offset:3072
.LBB0_568:
	ds_read_b128 v[168:171], v148
	ds_read_b128 v[172:175], v148 offset:1024
	ds_read_b128 v[176:179], v149
	ds_read_b128 v[180:183], v149 offset:1024
	ds_read_b128 v[184:187], v150
	ds_read_b128 v[188:191], v150 offset:1024
	ds_read_b128 v[192:195], v151
	ds_read_b128 v[196:199], v151 offset:1024
	s_add_i32 s34, s29, s31
	s_or_b32 s35, s34, 0x200080
	s_mov_b32 m0, s26
	s_nop 0
	buffer_load_dwordx4 v131, s[64:67], s35 offen lds
	s_or_b32 s35, s34, 0x300080
	s_mov_b32 m0, s27
	s_nop 0
	buffer_load_dwordx4 v131, s[64:67], s35 offen lds
	s_waitcnt lgkmcnt(8)
	s_barrier
	s_waitcnt lgkmcnt(0)
	s_setprio 1
	v_mfma_f32_16x16x32_bf16 v[124:127], v[168:171], v[132:135], v[124:127]
	v_mfma_f32_16x16x32_bf16 v[120:123], v[168:171], v[160:163], v[120:123]
	v_mfma_f32_16x16x32_bf16 v[116:119], v[176:179], v[132:135], v[116:119]
	v_mfma_f32_16x16x32_bf16 v[112:115], v[176:179], v[160:163], v[112:115]
	v_mfma_f32_16x16x32_bf16 v[108:111], v[184:187], v[132:135], v[108:111]
	v_mfma_f32_16x16x32_bf16 v[104:107], v[184:187], v[160:163], v[104:107]
	v_mfma_f32_16x16x32_bf16 v[100:103], v[192:195], v[132:135], v[100:103]
	v_mfma_f32_16x16x32_bf16 v[96:99], v[192:195], v[160:163], v[96:99]
	v_mfma_f32_16x16x32_bf16 v[124:127], v[172:175], v[156:159], v[124:127]
	v_mfma_f32_16x16x32_bf16 v[120:123], v[172:175], v[164:167], v[120:123]
	v_mfma_f32_16x16x32_bf16 v[116:119], v[180:183], v[156:159], v[116:119]
	v_mfma_f32_16x16x32_bf16 v[112:115], v[180:183], v[164:167], v[112:115]
	v_mfma_f32_16x16x32_bf16 v[108:111], v[188:191], v[156:159], v[108:111]
	v_mfma_f32_16x16x32_bf16 v[104:107], v[188:191], v[164:167], v[104:107]
	v_mfma_f32_16x16x32_bf16 v[100:103], v[196:199], v[156:159], v[100:103]
	v_mfma_f32_16x16x32_bf16 v[96:99], v[196:199], v[164:167], v[96:99]
	s_setprio 0
	s_barrier
	ds_read_b128 v[200:203], v152
	ds_read_b128 v[204:207], v152 offset:1024
	ds_read_b128 v[208:211], v152 offset:2048
	ds_read_b128 v[212:215], v152 offset:3072
	s_add_i32 s35, s11, s31
	s_add_i32 s36, s35, 0x100
	s_mov_b32 m0, s13
	s_nop 0
	buffer_load_dwordx4 v144, s[80:83], s36 offen lds
	s_add_i32 s36, s35, 0x200100
	s_mov_b32 m0, s14
	s_nop 0
	buffer_load_dwordx4 v144, s[80:83], s36 offen lds
	s_barrier
; #define STAGE_A(POFF, h, kt) STAGE_AX(POFF, h, kt, brow)
; #define STAGE_B(POFF, h, kt) STAGE_BX(POFF, h, kt, bcol)
; #define LDA(dst, b, h) _Pragma("unroll") for (int m = 0; m < 4; ++m) _Pragma("unroll") for (int k = 0; k < 2; ++k) \
;     dst[m][k] = *reinterpret_cast<const bf16x8*>((char*)SA(b, h) + lds_byte(wr * 64 + m * 16 + fr, k * 32 + fq * 8))
; #define LDB(dst, b, h) _Pragma("unroll") for (int n = 0; n < 2; ++n) _Pragma("unroll") for (int k = 0; k < 2; ++k) \
;     dst[n][k] = *reinterpret_cast<const bf16x8*>((char*)SB(b, h) + lds_byte(wc * 32 + n * 16 + fr, k * 32 + fq * 8))
; #define MMA(ai, bj, At_, Bt_) do { __builtin_amdgcn_s_setprio(1); \
;     _Pragma("unroll") for (int k = 0; k < 2; ++k) _Pragma("unroll") for (int m = 0; m < 4; ++m) _Pragma("unroll") for (int n = 0; n < 2; ++n) \
;       acc[ai][bj][m][n] = __builtin_amdgcn_mfma_f32_16x16x32_bf16(At_[m][k], Bt_[n][k], acc[ai][bj][m][n], 0, 0, 0); \
;     __builtin_amdgcn_s_setprio(0); } while (0)
; #define WAIT_V(n) asm volatile("s_waitcnt vmcnt(" #n ")" ::: "memory")
; #define BAR __builtin_amdgcn_s_barrier()
; #define SCHED __builtin_amdgcn_sched_barrier(0)
; template <int EPI, int N, int K>
; __device__ __forceinline__ void gemm_phase(const bf16_t* __restrict__ A, const bf16_t* __restrict__ Bt, const EpiArgs ea) {
;     ...
;       BAR; WAIT_L(0); MMA(0, 1, At, B1); BAR;
;       LDA(At, 0, 1); STAGE_A(SA_OFF(0, 0), 0, t + 2);
;       BAR; WAIT_L(0); MMA(1, 0, At, B0); BAR; SCHED;
;       STAGE_B(SB_OFF(0, 1), 1, t + 2);
;       WAIT_V(6); BAR; MMA(1, 1, At, B1); BAR;
;       LDB(B0, 1, 0); SCHED; LDA(At, 1, 0); STAGE_A(SA_OFF(0, 1), 1, t + 2);
;       WAIT_L(8); BAR; WAIT_L(0); MMA(0, 0, At, B0); BAR; SCHED;
	s_waitcnt lgkmcnt(0)
	s_setprio 1
	v_mfma_f32_16x16x32_bf16 v[92:95], v[168:171], v[200:203], v[92:95]
	v_mfma_f32_16x16x32_bf16 v[88:91], v[168:171], v[208:211], v[88:91]
	v_mfma_f32_16x16x32_bf16 v[84:87], v[176:179], v[200:203], v[84:87]
	v_mfma_f32_16x16x32_bf16 v[80:83], v[176:179], v[208:211], v[80:83]
	v_mfma_f32_16x16x32_bf16 v[76:79], v[184:187], v[200:203], v[76:79]
	v_mfma_f32_16x16x32_bf16 v[72:75], v[184:187], v[208:211], v[72:75]
	v_mfma_f32_16x16x32_bf16 v[68:71], v[192:195], v[200:203], v[68:71]
	v_mfma_f32_16x16x32_bf16 v[64:67], v[192:195], v[208:211], v[64:67]
	v_mfma_f32_16x16x32_bf16 v[92:95], v[172:175], v[204:207], v[92:95]
	v_mfma_f32_16x16x32_bf16 v[88:91], v[172:175], v[212:215], v[88:91]
	v_mfma_f32_16x16x32_bf16 v[84:87], v[180:183], v[204:207], v[84:87]
	v_mfma_f32_16x16x32_bf16 v[80:83], v[180:183], v[212:215], v[80:83]
	v_mfma_f32_16x16x32_bf16 v[76:79], v[188:191], v[204:207], v[76:79]
	v_mfma_f32_16x16x32_bf16 v[72:75], v[188:191], v[212:215], v[72:75]
	v_mfma_f32_16x16x32_bf16 v[68:71], v[196:199], v[204:207], v[68:71]
	v_mfma_f32_16x16x32_bf16 v[64:67], v[196:199], v[212:215], v[64:67]
	s_setprio 0
	s_barrier
	ds_read_b128 v[168:171], v148 offset:16384
	ds_read_b128 v[172:175], v148 offset:17408
	ds_read_b128 v[176:179], v149 offset:16384
	ds_read_b128 v[180:183], v149 offset:17408
	ds_read_b128 v[184:187], v150 offset:16384
	ds_read_b128 v[188:191], v150 offset:17408
	ds_read_b128 v[192:195], v151 offset:16384
	ds_read_b128 v[196:199], v151 offset:17408
	s_add_i32 s36, s34, 0x100
	s_mov_b32 m0, s12
	s_nop 0
	buffer_load_dwordx4 v131, s[64:67], s36 offen lds
	s_add_i32 s37, s34, 0x100100
	s_mov_b32 m0, s15
	s_nop 0
	buffer_load_dwordx4 v131, s[64:67], s37 offen lds
	s_waitcnt vmcnt(10)
	s_barrier
	s_waitcnt lgkmcnt(0)
	s_setprio 1
	v_mfma_f32_16x16x32_bf16 v[60:63], v[168:171], v[132:135], v[60:63]
	v_mfma_f32_16x16x32_bf16 v[56:59], v[168:171], v[160:163], v[56:59]
	v_mfma_f32_16x16x32_bf16 v[52:55], v[176:179], v[132:135], v[52:55]
	v_mfma_f32_16x16x32_bf16 v[48:51], v[176:179], v[160:163], v[48:51]
	v_mfma_f32_16x16x32_bf16 v[44:47], v[184:187], v[132:135], v[44:47]
	v_mfma_f32_16x16x32_bf16 v[40:43], v[184:187], v[160:163], v[40:43]
	v_mfma_f32_16x16x32_bf16 v[36:39], v[192:195], v[132:135], v[36:39]
	v_mfma_f32_16x16x32_bf16 v[32:35], v[192:195], v[160:163], v[32:35]
	v_mfma_f32_16x16x32_bf16 v[60:63], v[172:175], v[156:159], v[60:63]
	v_mfma_f32_16x16x32_bf16 v[56:59], v[172:175], v[164:167], v[56:59]
	v_mfma_f32_16x16x32_bf16 v[52:55], v[180:183], v[156:159], v[52:55]
	v_mfma_f32_16x16x32_bf16 v[48:51], v[180:183], v[164:167], v[48:51]
	v_mfma_f32_16x16x32_bf16 v[44:47], v[188:191], v[156:159], v[44:47]
	v_mfma_f32_16x16x32_bf16 v[40:43], v[188:191], v[164:167], v[40:43]
	v_mfma_f32_16x16x32_bf16 v[36:39], v[196:199], v[156:159], v[36:39]
	v_mfma_f32_16x16x32_bf16 v[32:35], v[196:199], v[164:167], v[32:35]
	s_setprio 0
	s_barrier
	ds_read_b128 v[132:135], v153
	ds_read_b128 v[156:159], v153 offset:1024
	ds_read_b128 v[160:163], v153 offset:2048
	ds_read_b128 v[164:167], v153 offset:3072
	s_add_i32 s37, s35, 0x8100
	s_mov_b32 m0, s16
	s_nop 0
	buffer_load_dwordx4 v144, s[80:83], s37 offen lds
	s_add_i32 s37, s35, 0x208100
	s_mov_b32 m0, s17
	s_nop 0
	buffer_load_dwordx4 v144, s[80:83], s37 offen lds
	s_waitcnt vmcnt(6)
	s_barrier
	s_setprio 1
	v_mfma_f32_16x16x32_bf16 v[28:31], v[168:171], v[200:203], v[28:31]
	v_mfma_f32_16x16x32_bf16 v[24:27], v[168:171], v[208:211], v[24:27]
	v_mfma_f32_16x16x32_bf16 v[20:23], v[176:179], v[200:203], v[20:23]
	v_mfma_f32_16x16x32_bf16 v[16:19], v[176:179], v[208:211], v[16:19]
	v_mfma_f32_16x16x32_bf16 v[12:15], v[184:187], v[200:203], v[12:15]
	v_mfma_f32_16x16x32_bf16 v[8:11], v[184:187], v[208:211], v[8:11]
	v_mfma_f32_16x16x32_bf16 v[4:7], v[192:195], v[200:203], v[4:7]
	v_mfma_f32_16x16x32_bf16 v[0:3], v[192:195], v[208:211], v[0:3]
	v_mfma_f32_16x16x32_bf16 v[28:31], v[172:175], v[204:207], v[28:31]
	v_mfma_f32_16x16x32_bf16 v[24:27], v[172:175], v[212:215], v[24:27]
	v_mfma_f32_16x16x32_bf16 v[20:23], v[180:183], v[204:207], v[20:23]
	v_mfma_f32_16x16x32_bf16 v[16:19], v[180:183], v[212:215], v[16:19]
	v_mfma_f32_16x16x32_bf16 v[12:15], v[188:191], v[204:207], v[12:15]
	v_mfma_f32_16x16x32_bf16 v[8:11], v[188:191], v[212:215], v[8:11]
	v_mfma_f32_16x16x32_bf16 v[4:7], v[196:199], v[204:207], v[4:7]
	v_mfma_f32_16x16x32_bf16 v[0:3], v[196:199], v[212:215], v[0:3]
	s_setprio 0
	s_barrier
	ds_read_b128 v[168:171], v148 offset:32768
	ds_read_b128 v[172:175], v148 offset:33792
	ds_read_b128 v[176:179], v149 offset:32768
	ds_read_b128 v[180:183], v149 offset:33792
	ds_read_b128 v[184:187], v150 offset:32768
	ds_read_b128 v[188:191], v150 offset:33792
	ds_read_b128 v[192:195], v151 offset:32768
	ds_read_b128 v[196:199], v151 offset:33792
	s_or_b32 s37, s36, 0x200000
	s_mov_b32 m0, s18
	s_nop 0
	buffer_load_dwordx4 v131, s[64:67], s37 offen lds
	s_or_b32 s36, s36, 0x300000
	s_mov_b32 m0, s19
	s_nop 0
	buffer_load_dwordx4 v131, s[64:67], s36 offen lds
	s_waitcnt lgkmcnt(8)
	s_barrier
; #define STAGE_A(POFF, h, kt) STAGE_AX(POFF, h, kt, brow)
; #define STAGE_B(POFF, h, kt) STAGE_BX(POFF, h, kt, bcol)
; #define LDA(dst, b, h) _Pragma("unroll") for (int m = 0; m < 4; ++m) _Pragma("unroll") for (int k = 0; k < 2; ++k) \
;     dst[m][k] = *reinterpret_cast<const bf16x8*>((char*)SA(b, h) + lds_byte(wr * 64 + m * 16 + fr, k * 32 + fq * 8))
; #define LDB(dst, b, h) _Pragma("unroll") for (int n = 0; n < 2; ++n) _Pragma("unroll") for (int k = 0; k < 2; ++k) \
;     dst[n][k] = *reinterpret_cast<const bf16x8*>((char*)SB(b, h) + lds_byte(wc * 32 + n * 16 + fr, k * 32 + fq * 8))
; #define MMA(ai, bj, At_, Bt_) do { __builtin_amdgcn_s_setprio(1); \
;     _Pragma("unroll") for (int k = 0; k < 2; ++k) _Pragma("unroll") for (int m = 0; m < 4; ++m) _Pragma("unroll") for (int n = 0; n < 2; ++n) \
;       acc[ai][bj][m][n] = __builtin_amdgcn_mfma_f32_16x16x32_bf16(At_[m][k], Bt_[n][k], acc[ai][bj][m][n], 0, 0, 0); \
;     __builtin_amdgcn_s_setprio(0); } while (0)
; #define WAIT_V(n) asm volatile("s_waitcnt vmcnt(" #n ")" ::: "memory")
; #define BAR __builtin_amdgcn_s_barrier()
; #define SCHED __builtin_amdgcn_sched_barrier(0)
; template <int EPI, int N, int K>
; __device__ __forceinline__ void gemm_phase(const bf16_t* __restrict__ A, const bf16_t* __restrict__ Bt, const EpiArgs ea) {
;     ...
;       LDB(B0, 1, 0); SCHED; LDA(At, 1, 0); STAGE_A(SA_OFF(0, 1), 1, t + 2);
;       WAIT_L(8); BAR; WAIT_L(0); MMA(0, 0, At, B0); BAR; SCHED;
;       LDB(B1, 1, 1); STAGE_B(SB_OFF(1, 0), 0, t + 3);
;       BAR; WAIT_L(0); MMA(0, 1, At, B1); BAR;
;       LDA(At, 1, 1); STAGE_A(SA_OFF(1, 0), 0, t + 3);
;       BAR; WAIT_L(0); MMA(1, 0, At, B0); BAR; SCHED;
;       STAGE_B(SB_OFF(1, 1), 1, t + 3);
;       WAIT_V(6); BAR; MMA(1, 1, At, B1); BAR;
	s_waitcnt lgkmcnt(0)
	s_setprio 1
	v_mfma_f32_16x16x32_bf16 v[124:127], v[168:171], v[132:135], v[124:127]
	v_mfma_f32_16x16x32_bf16 v[120:123], v[168:171], v[160:163], v[120:123]
	v_mfma_f32_16x16x32_bf16 v[116:119], v[176:179], v[132:135], v[116:119]
	v_mfma_f32_16x16x32_bf16 v[112:115], v[176:179], v[160:163], v[112:115]
	v_mfma_f32_16x16x32_bf16 v[108:111], v[184:187], v[132:135], v[108:111]
	v_mfma_f32_16x16x32_bf16 v[104:107], v[184:187], v[160:163], v[104:107]
	v_mfma_f32_16x16x32_bf16 v[100:103], v[192:195], v[132:135], v[100:103]
	v_mfma_f32_16x16x32_bf16 v[96:99], v[192:195], v[160:163], v[96:99]
	v_mfma_f32_16x16x32_bf16 v[124:127], v[172:175], v[156:159], v[124:127]
	v_mfma_f32_16x16x32_bf16 v[120:123], v[172:175], v[164:167], v[120:123]
	v_mfma_f32_16x16x32_bf16 v[116:119], v[180:183], v[156:159], v[116:119]
	v_mfma_f32_16x16x32_bf16 v[112:115], v[180:183], v[164:167], v[112:115]
	v_mfma_f32_16x16x32_bf16 v[108:111], v[188:191], v[156:159], v[108:111]
	v_mfma_f32_16x16x32_bf16 v[104:107], v[188:191], v[164:167], v[104:107]
	v_mfma_f32_16x16x32_bf16 v[100:103], v[196:199], v[156:159], v[100:103]
	v_mfma_f32_16x16x32_bf16 v[96:99], v[196:199], v[164:167], v[96:99]
	s_setprio 0
	s_barrier
	ds_read_b128 v[200:203], v154
	ds_read_b128 v[204:207], v154 offset:1024
	ds_read_b128 v[208:211], v154 offset:2048
	ds_read_b128 v[212:215], v154 offset:3072
	s_add_i32 s36, s35, 0x180
	s_mov_b32 m0, s20
	s_nop 0
	buffer_load_dwordx4 v144, s[80:83], s36 offen lds
	s_add_i32 s36, s35, 0x200180
	s_mov_b32 m0, s21
	s_nop 0
	buffer_load_dwordx4 v144, s[80:83], s36 offen lds
	s_barrier
	s_waitcnt lgkmcnt(0)
	s_setprio 1
	v_mfma_f32_16x16x32_bf16 v[92:95], v[168:171], v[200:203], v[92:95]
	v_mfma_f32_16x16x32_bf16 v[88:91], v[168:171], v[208:211], v[88:91]
	v_mfma_f32_16x16x32_bf16 v[84:87], v[176:179], v[200:203], v[84:87]
	v_mfma_f32_16x16x32_bf16 v[80:83], v[176:179], v[208:211], v[80:83]
	v_mfma_f32_16x16x32_bf16 v[76:79], v[184:187], v[200:203], v[76:79]
	v_mfma_f32_16x16x32_bf16 v[72:75], v[184:187], v[208:211], v[72:75]
	v_mfma_f32_16x16x32_bf16 v[68:71], v[192:195], v[200:203], v[68:71]
	v_mfma_f32_16x16x32_bf16 v[64:67], v[192:195], v[208:211], v[64:67]
	v_mfma_f32_16x16x32_bf16 v[92:95], v[172:175], v[204:207], v[92:95]
	v_mfma_f32_16x16x32_bf16 v[88:91], v[172:175], v[212:215], v[88:91]
	v_mfma_f32_16x16x32_bf16 v[84:87], v[180:183], v[204:207], v[84:87]
	v_mfma_f32_16x16x32_bf16 v[80:83], v[180:183], v[212:215], v[80:83]
	v_mfma_f32_16x16x32_bf16 v[76:79], v[188:191], v[204:207], v[76:79]
	v_mfma_f32_16x16x32_bf16 v[72:75], v[188:191], v[212:215], v[72:75]
	v_mfma_f32_16x16x32_bf16 v[68:71], v[196:199], v[204:207], v[68:71]
	v_mfma_f32_16x16x32_bf16 v[64:67], v[196:199], v[212:215], v[64:67]
	s_setprio 0
	s_barrier
	ds_read_b128 v[168:171], v148 offset:49152
	ds_read_b128 v[172:175], v148 offset:50176
	ds_read_b128 v[176:179], v149 offset:49152
	ds_read_b128 v[180:183], v149 offset:50176
	ds_read_b128 v[184:187], v150 offset:49152
	ds_read_b128 v[188:191], v150 offset:50176
	ds_read_b128 v[192:195], v151 offset:49152
	ds_read_b128 v[196:199], v151 offset:50176
	s_add_i32 s36, s34, 0x180
	s_mov_b32 m0, s22
	s_nop 0
	buffer_load_dwordx4 v131, s[64:67], s36 offen lds
	s_add_i32 s34, s34, 0x100180
	s_mov_b32 m0, s23
	s_nop 0
	buffer_load_dwordx4 v131, s[64:67], s34 offen lds
	s_waitcnt vmcnt(10)
	s_barrier
	s_waitcnt lgkmcnt(0)
	s_setprio 1
	v_mfma_f32_16x16x32_bf16 v[60:63], v[168:171], v[132:135], v[60:63]
	v_mfma_f32_16x16x32_bf16 v[56:59], v[168:171], v[160:163], v[56:59]
	v_mfma_f32_16x16x32_bf16 v[52:55], v[176:179], v[132:135], v[52:55]
	v_mfma_f32_16x16x32_bf16 v[48:51], v[176:179], v[160:163], v[48:51]
	v_mfma_f32_16x16x32_bf16 v[44:47], v[184:187], v[132:135], v[44:47]
	v_mfma_f32_16x16x32_bf16 v[40:43], v[184:187], v[160:163], v[40:43]
	v_mfma_f32_16x16x32_bf16 v[36:39], v[192:195], v[132:135], v[36:39]
	v_mfma_f32_16x16x32_bf16 v[32:35], v[192:195], v[160:163], v[32:35]
	v_mfma_f32_16x16x32_bf16 v[60:63], v[172:175], v[156:159], v[60:63]
	v_mfma_f32_16x16x32_bf16 v[56:59], v[172:175], v[164:167], v[56:59]
	v_mfma_f32_16x16x32_bf16 v[52:55], v[180:183], v[156:159], v[52:55]
	v_mfma_f32_16x16x32_bf16 v[48:51], v[180:183], v[164:167], v[48:51]
	v_mfma_f32_16x16x32_bf16 v[44:47], v[188:191], v[156:159], v[44:47]
	v_mfma_f32_16x16x32_bf16 v[40:43], v[188:191], v[164:167], v[40:43]
	v_mfma_f32_16x16x32_bf16 v[36:39], v[196:199], v[156:159], v[36:39]
	v_mfma_f32_16x16x32_bf16 v[32:35], v[196:199], v[164:167], v[32:35]
	s_setprio 0
	s_barrier
	ds_read_b128 v[132:135], v147
	ds_read_b128 v[156:159], v147 offset:1024
	ds_read_b128 v[160:163], v147 offset:2048
	ds_read_b128 v[164:167], v147 offset:3072
	s_add_i32 s34, s35, 0x8180
	s_mov_b32 m0, s24
	s_nop 0
	buffer_load_dwordx4 v144, s[80:83], s34 offen lds
	s_add_i32 s35, s35, 0x208180
	s_mov_b32 m0, s25
	s_nop 0
	buffer_load_dwordx4 v144, s[80:83], s35 offen lds
	s_waitcnt vmcnt(6)
	s_barrier
	s_setprio 1
	v_mfma_f32_16x16x32_bf16 v[28:31], v[168:171], v[200:203], v[28:31]
	v_mfma_f32_16x16x32_bf16 v[24:27], v[168:171], v[208:211], v[24:27]
	v_mfma_f32_16x16x32_bf16 v[20:23], v[176:179], v[200:203], v[20:23]
	v_mfma_f32_16x16x32_bf16 v[16:19], v[176:179], v[208:211], v[16:19]
	v_mfma_f32_16x16x32_bf16 v[12:15], v[184:187], v[200:203], v[12:15]
	v_mfma_f32_16x16x32_bf16 v[8:11], v[184:187], v[208:211], v[8:11]
	v_mfma_f32_16x16x32_bf16 v[4:7], v[192:195], v[200:203], v[4:7]
	v_mfma_f32_16x16x32_bf16 v[0:3], v[192:195], v[208:211], v[0:3]
	v_mfma_f32_16x16x32_bf16 v[28:31], v[172:175], v[204:207], v[28:31]
	v_mfma_f32_16x16x32_bf16 v[24:27], v[172:175], v[212:215], v[24:27]
	v_mfma_f32_16x16x32_bf16 v[20:23], v[180:183], v[204:207], v[20:23]
	v_mfma_f32_16x16x32_bf16 v[16:19], v[180:183], v[212:215], v[16:19]
	v_mfma_f32_16x16x32_bf16 v[12:15], v[188:191], v[204:207], v[12:15]
	v_mfma_f32_16x16x32_bf16 v[8:11], v[188:191], v[212:215], v[8:11]
	v_mfma_f32_16x16x32_bf16 v[4:7], v[196:199], v[204:207], v[4:7]
	v_mfma_f32_16x16x32_bf16 v[0:3], v[196:199], v[212:215], v[0:3]
	s_setprio 0
	s_add_i32 s30, s30, 2
	s_addk_i32 s31, 0x100
	s_cmpk_lt_u32 s30, 0x7c
	s_barrier
; #define STAGE_A(POFF, h, kt) STAGE_AX(POFF, h, kt, brow)
; #define LDA(dst, b, h) _Pragma("unroll") for (int m = 0; m < 4; ++m) _Pragma("unroll") for (int k = 0; k < 2; ++k) \
;     dst[m][k] = *reinterpret_cast<const bf16x8*>((char*)SA(b, h) + lds_byte(wr * 64 + m * 16 + fr, k * 32 + fq * 8))
; #define LDB(dst, b, h) _Pragma("unroll") for (int n = 0; n < 2; ++n) _Pragma("unroll") for (int k = 0; k < 2; ++k) \
;     dst[n][k] = *reinterpret_cast<const bf16x8*>((char*)SB(b, h) + lds_byte(wc * 32 + n * 16 + fr, k * 32 + fq * 8))
; #define MMA(ai, bj, At_, Bt_) do { __builtin_amdgcn_s_setprio(1); \
;     _Pragma("unroll") for (int k = 0; k < 2; ++k) _Pragma("unroll") for (int m = 0; m < 4; ++m) _Pragma("unroll") for (int n = 0; n < 2; ++n) \
;       acc[ai][bj][m][n] = __builtin_amdgcn_mfma_f32_16x16x32_bf16(At_[m][k], Bt_[n][k], acc[ai][bj][m][n], 0, 0, 0); \
;     __builtin_amdgcn_s_setprio(0); } while (0)
; #define WAIT_V(n) asm volatile("s_waitcnt vmcnt(" #n ")" ::: "memory")
; #define BAR __builtin_amdgcn_s_barrier()
; template <int EPI, int N, int K>
; __device__ __forceinline__ void gemm_phase(const bf16_t* __restrict__ A, const bf16_t* __restrict__ Bt, const EpiArgs ea) {
;     ...
;     { LDB(B0, 0, 0); LDA(At, 0, 0); STAGE_A(SA_OFF(1, 1), 1, nt - 1);
;       BAR; WAIT_L(0); MMA(0, 0, At, B0); BAR;
;       LDB(B1, 0, 1); BAR; WAIT_L(0); MMA(0, 1, At, B1); BAR;
;       LDA(At, 0, 1); WAIT_V(4); BAR; WAIT_L(0); MMA(1, 0, At, B0); MMA(1, 1, At, B1); BAR; }
	s_cbranch_scc1 .LBB0_568
	ds_read_b128 v[168:171], v148
	ds_read_b128 v[172:175], v148 offset:1024
	ds_read_b128 v[176:179], v149
	ds_read_b128 v[180:183], v149 offset:1024
	ds_read_b128 v[184:187], v150
	ds_read_b128 v[188:191], v150 offset:1024
	ds_read_b128 v[192:195], v151
	ds_read_b128 v[196:199], v151 offset:1024
	s_and_b32 s3, s3, 0x700
	s_lshl_b32 s2, s2, 11
	s_or_b32 s29, s3, s2
	s_lshl_b32 s2, s29, 14
	s_or_b32 s3, s2, 0x203f80
	s_mov_b32 m0, s26
	s_nop 0
	buffer_load_dwordx4 v131, s[64:67], s3 offen lds
	s_or_b32 s2, s2, 0x303f80
	s_mov_b32 m0, s27
	s_nop 0
	buffer_load_dwordx4 v131, s[64:67], s2 offen lds
	s_barrier
	s_waitcnt lgkmcnt(0)
	s_setprio 1
	v_mfma_f32_16x16x32_bf16 v[124:127], v[168:171], v[132:135], v[124:127]
	v_mfma_f32_16x16x32_bf16 v[120:123], v[168:171], v[160:163], v[120:123]
	v_mfma_f32_16x16x32_bf16 v[116:119], v[176:179], v[132:135], v[116:119]
	v_mfma_f32_16x16x32_bf16 v[112:115], v[176:179], v[160:163], v[112:115]
	v_mfma_f32_16x16x32_bf16 v[108:111], v[184:187], v[132:135], v[108:111]
	v_mfma_f32_16x16x32_bf16 v[104:107], v[184:187], v[160:163], v[104:107]
	v_mfma_f32_16x16x32_bf16 v[100:103], v[192:195], v[132:135], v[100:103]
	v_mfma_f32_16x16x32_bf16 v[96:99], v[192:195], v[160:163], v[96:99]
	v_mfma_f32_16x16x32_bf16 v[124:127], v[172:175], v[156:159], v[124:127]
	v_mfma_f32_16x16x32_bf16 v[120:123], v[172:175], v[164:167], v[120:123]
	v_mfma_f32_16x16x32_bf16 v[116:119], v[180:183], v[156:159], v[116:119]
	v_mfma_f32_16x16x32_bf16 v[112:115], v[180:183], v[164:167], v[112:115]
	v_mfma_f32_16x16x32_bf16 v[108:111], v[188:191], v[156:159], v[108:111]
	v_mfma_f32_16x16x32_bf16 v[104:107], v[188:191], v[164:167], v[104:107]
	v_mfma_f32_16x16x32_bf16 v[100:103], v[196:199], v[156:159], v[100:103]
	v_mfma_f32_16x16x32_bf16 v[96:99], v[196:199], v[164:167], v[96:99]
	s_setprio 0
	s_barrier
	ds_read_b128 v[200:203], v152
	ds_read_b128 v[204:207], v152 offset:1024
	ds_read_b128 v[208:211], v152 offset:2048
	ds_read_b128 v[212:215], v152 offset:3072
	s_barrier
	s_waitcnt lgkmcnt(0)
	s_setprio 1
	v_mfma_f32_16x16x32_bf16 v[92:95], v[168:171], v[200:203], v[92:95]
	v_mfma_f32_16x16x32_bf16 v[88:91], v[168:171], v[208:211], v[88:91]
	v_mfma_f32_16x16x32_bf16 v[76:79], v[184:187], v[200:203], v[76:79]
	v_mfma_f32_16x16x32_bf16 v[72:75], v[184:187], v[208:211], v[72:75]
	v_mfma_f32_16x16x32_bf16 v[84:87], v[176:179], v[200:203], v[84:87]
	v_mfma_f32_16x16x32_bf16 v[80:83], v[176:179], v[208:211], v[80:83]
	v_mfma_f32_16x16x32_bf16 v[68:71], v[192:195], v[200:203], v[68:71]
	v_mfma_f32_16x16x32_bf16 v[64:67], v[192:195], v[208:211], v[64:67]
	v_mfma_f32_16x16x32_bf16 v[92:95], v[172:175], v[204:207], v[92:95]
	v_mfma_f32_16x16x32_bf16 v[88:91], v[172:175], v[212:215], v[88:91]
	v_mfma_f32_16x16x32_bf16 v[76:79], v[188:191], v[204:207], v[76:79]
	v_mfma_f32_16x16x32_bf16 v[72:75], v[188:191], v[212:215], v[72:75]
	v_mfma_f32_16x16x32_bf16 v[168:171], v[180:183], v[204:207], v[84:87]
	v_mfma_f32_16x16x32_bf16 v[172:175], v[180:183], v[212:215], v[80:83]
	v_mfma_f32_16x16x32_bf16 v[176:179], v[196:199], v[204:207], v[68:71]
	v_mfma_f32_16x16x32_bf16 v[180:183], v[196:199], v[212:215], v[64:67]
	s_setprio 0
	s_barrier
	s_nop 0
	ds_read_b128 v[64:67], v148 offset:16384
	ds_read_b128 v[68:71], v148 offset:17408
	ds_read_b128 v[80:83], v149 offset:16384
	ds_read_b128 v[84:87], v149 offset:17408
	ds_read_b128 v[184:187], v150 offset:16384
	ds_read_b128 v[188:191], v150 offset:17408
	ds_read_b128 v[192:195], v151 offset:16384
	ds_read_b128 v[196:199], v151 offset:17408
	s_waitcnt vmcnt(4)
	s_barrier
	s_waitcnt lgkmcnt(0)
	s_setprio 1
	v_mfma_f32_16x16x32_bf16 v[60:63], v[64:67], v[132:135], v[60:63]
	v_mfma_f32_16x16x32_bf16 v[56:59], v[64:67], v[160:163], v[56:59]
	v_mfma_f32_16x16x32_bf16 v[52:55], v[80:83], v[132:135], v[52:55]
	v_mfma_f32_16x16x32_bf16 v[48:51], v[80:83], v[160:163], v[48:51]
	v_mfma_f32_16x16x32_bf16 v[44:47], v[184:187], v[132:135], v[44:47]
	v_mfma_f32_16x16x32_bf16 v[40:43], v[184:187], v[160:163], v[40:43]
	v_mfma_f32_16x16x32_bf16 v[36:39], v[192:195], v[132:135], v[36:39]
	v_mfma_f32_16x16x32_bf16 v[32:35], v[192:195], v[160:163], v[32:35]
	v_mfma_f32_16x16x32_bf16 v[60:63], v[68:71], v[156:159], v[60:63]
	v_mfma_f32_16x16x32_bf16 v[56:59], v[68:71], v[164:167], v[56:59]
	v_mfma_f32_16x16x32_bf16 v[52:55], v[84:87], v[156:159], v[52:55]
	v_mfma_f32_16x16x32_bf16 v[48:51], v[84:87], v[164:167], v[48:51]
	v_mfma_f32_16x16x32_bf16 v[44:47], v[188:191], v[156:159], v[44:47]
	v_mfma_f32_16x16x32_bf16 v[40:43], v[188:191], v[164:167], v[40:43]
	v_mfma_f32_16x16x32_bf16 v[36:39], v[196:199], v[156:159], v[36:39]
	v_mfma_f32_16x16x32_bf16 v[32:35], v[196:199], v[164:167], v[32:35]
	s_setprio 0
	s_setprio 1
	v_mfma_f32_16x16x32_bf16 v[28:31], v[64:67], v[200:203], v[28:31]
	v_mfma_f32_16x16x32_bf16 v[24:27], v[64:67], v[208:211], v[24:27]
	v_mfma_f32_16x16x32_bf16 v[4:7], v[192:195], v[200:203], v[4:7]
	v_mfma_f32_16x16x32_bf16 v[0:3], v[192:195], v[208:211], v[0:3]
	v_mfma_f32_16x16x32_bf16 v[20:23], v[80:83], v[200:203], v[20:23]
	v_mfma_f32_16x16x32_bf16 v[16:19], v[80:83], v[208:211], v[16:19]
	v_mfma_f32_16x16x32_bf16 v[12:15], v[184:187], v[200:203], v[12:15]
	v_mfma_f32_16x16x32_bf16 v[8:11], v[184:187], v[208:211], v[8:11]
	v_mfma_f32_16x16x32_bf16 v[28:31], v[68:71], v[204:207], v[28:31]
	v_mfma_f32_16x16x32_bf16 v[24:27], v[68:71], v[212:215], v[24:27]
	v_mfma_f32_16x16x32_bf16 v[4:7], v[196:199], v[204:207], v[4:7]
	v_mfma_f32_16x16x32_bf16 v[0:3], v[196:199], v[212:215], v[0:3]
	v_mfma_f32_16x16x32_bf16 v[132:135], v[84:87], v[204:207], v[20:23]
	v_mfma_f32_16x16x32_bf16 v[156:159], v[84:87], v[212:215], v[16:19]
	v_mfma_f32_16x16x32_bf16 v[160:163], v[188:191], v[204:207], v[12:15]
	v_mfma_f32_16x16x32_bf16 v[164:167], v[188:191], v[212:215], v[8:11]
	s_setprio 0
	s_barrier
; #define LDA(dst, b, h) _Pragma("unroll") for (int m = 0; m < 4; ++m) _Pragma("unroll") for (int k = 0; k < 2; ++k) \
;     dst[m][k] = *reinterpret_cast<const bf16x8*>((char*)SA(b, h) + lds_byte(wr * 64 + m * 16 + fr, k * 32 + fq * 8))
; #define LDB(dst, b, h) _Pragma("unroll") for (int n = 0; n < 2; ++n) _Pragma("unroll") for (int k = 0; k < 2; ++k) \
;     dst[n][k] = *reinterpret_cast<const bf16x8*>((char*)SB(b, h) + lds_byte(wc * 32 + n * 16 + fr, k * 32 + fq * 8))
; #define MMA(ai, bj, At_, Bt_) do { __builtin_amdgcn_s_setprio(1); \
;     _Pragma("unroll") for (int k = 0; k < 2; ++k) _Pragma("unroll") for (int m = 0; m < 4; ++m) _Pragma("unroll") for (int n = 0; n < 2; ++n) \
;       acc[ai][bj][m][n] = __builtin_amdgcn_mfma_f32_16x16x32_bf16(At_[m][k], Bt_[n][k], acc[ai][bj][m][n], 0, 0, 0); \
;     __builtin_amdgcn_s_setprio(0); } while (0)
; #define WAIT_V(n) asm volatile("s_waitcnt vmcnt(" #n ")" ::: "memory")
; #define BAR __builtin_amdgcn_s_barrier()
; template <int EPI, int N, int K>
; __device__ __forceinline__ void gemm_phase(const bf16_t* __restrict__ A, const bf16_t* __restrict__ Bt, const EpiArgs ea) {
;     ...
;     { LDB(B0, 1, 0); LDA(At, 1, 0); WAIT_V(2); BAR; WAIT_L(0); MMA(0, 0, At, B0); BAR;
;       LDB(B1, 1, 1); WAIT_V(0); BAR; WAIT_L(0); MMA(0, 1, At, B1); BAR;
;       LDA(At, 1, 1); BAR; WAIT_L(0); MMA(1, 0, At, B0); MMA(1, 1, At, B1); BAR; }
;     if (wr == 0) BAR;
	s_nop 0
	ds_read_b128 v[8:11], v153
	ds_read_b128 v[12:15], v153 offset:1024
	ds_read_b128 v[16:19], v153 offset:2048
	ds_read_b128 v[184:187], v153 offset:3072
	ds_read_b128 v[20:23], v148 offset:32768
	ds_read_b128 v[188:191], v148 offset:33792
	ds_read_b128 v[192:195], v149 offset:32768
	ds_read_b128 v[196:199], v149 offset:33792
	ds_read_b128 v[200:203], v150 offset:32768
	ds_read_b128 v[204:207], v150 offset:33792
	ds_read_b128 v[208:211], v151 offset:32768
	ds_read_b128 v[212:215], v151 offset:33792
	s_waitcnt vmcnt(2)
	s_barrier
	s_waitcnt lgkmcnt(0)
	s_setprio 1
	v_mfma_f32_16x16x32_bf16 v[64:67], v[20:23], v[8:11], v[124:127]
	v_mfma_f32_16x16x32_bf16 v[68:71], v[20:23], v[16:19], v[120:123]
	v_mfma_f32_16x16x32_bf16 v[80:83], v[192:195], v[8:11], v[116:119]
	v_mfma_f32_16x16x32_bf16 v[84:87], v[192:195], v[16:19], v[112:115]
	v_mfma_f32_16x16x32_bf16 v[108:111], v[200:203], v[8:11], v[108:111]
	v_mfma_f32_16x16x32_bf16 v[104:107], v[200:203], v[16:19], v[104:107]
	v_mfma_f32_16x16x32_bf16 v[120:123], v[208:211], v[8:11], v[100:103]
	v_mfma_f32_16x16x32_bf16 v[124:127], v[208:211], v[16:19], v[96:99]
	v_mfma_f32_16x16x32_bf16 v[116:119], v[188:191], v[12:15], v[64:67]
	v_mfma_f32_16x16x32_bf16 v[112:115], v[188:191], v[184:187], v[68:71]
	v_mfma_f32_16x16x32_bf16 v[100:103], v[196:199], v[12:15], v[80:83]
	v_mfma_f32_16x16x32_bf16 v[96:99], v[196:199], v[184:187], v[84:87]
	v_mfma_f32_16x16x32_bf16 v[84:87], v[204:207], v[12:15], v[108:111]
	v_mfma_f32_16x16x32_bf16 v[80:83], v[204:207], v[184:187], v[104:107]
	v_mfma_f32_16x16x32_bf16 v[68:71], v[212:215], v[12:15], v[120:123]
	v_mfma_f32_16x16x32_bf16 v[64:67], v[212:215], v[184:187], v[124:127]
	s_setprio 0
	s_barrier
	ds_read_b128 v[216:219], v154
	ds_read_b128 v[220:223], v154 offset:1024
	ds_read_b128 v[224:227], v154 offset:2048
	ds_read_b128 v[228:231], v154 offset:3072
	s_waitcnt vmcnt(0)
	s_barrier
	s_waitcnt lgkmcnt(0)
	s_setprio 1
	v_mfma_f32_16x16x32_bf16 v[92:95], v[20:23], v[216:219], v[92:95]
	v_mfma_f32_16x16x32_bf16 v[20:23], v[20:23], v[224:227], v[88:91]
	v_mfma_f32_16x16x32_bf16 v[88:91], v[192:195], v[216:219], v[168:171]
	v_mfma_f32_16x16x32_bf16 v[104:107], v[192:195], v[224:227], v[172:175]
	v_mfma_f32_16x16x32_bf16 v[76:79], v[200:203], v[216:219], v[76:79]
	v_mfma_f32_16x16x32_bf16 v[72:75], v[200:203], v[224:227], v[72:75]
	v_mfma_f32_16x16x32_bf16 v[168:171], v[208:211], v[216:219], v[176:179]
	v_mfma_f32_16x16x32_bf16 v[172:175], v[208:211], v[224:227], v[180:183]
	v_mfma_f32_16x16x32_bf16 v[124:127], v[188:191], v[220:223], v[92:95]
	v_mfma_f32_16x16x32_bf16 v[120:123], v[188:191], v[228:231], v[20:23]
	v_mfma_f32_16x16x32_bf16 v[108:111], v[196:199], v[220:223], v[88:91]
	v_mfma_f32_16x16x32_bf16 v[104:107], v[196:199], v[228:231], v[104:107]
	v_mfma_f32_16x16x32_bf16 v[92:95], v[204:207], v[220:223], v[76:79]
	v_mfma_f32_16x16x32_bf16 v[88:91], v[204:207], v[228:231], v[72:75]
	v_mfma_f32_16x16x32_bf16 v[76:79], v[212:215], v[220:223], v[168:171]
	v_mfma_f32_16x16x32_bf16 v[72:75], v[212:215], v[228:231], v[172:175]
	s_setprio 0
	s_barrier
	ds_read_b128 v[168:171], v148 offset:49152
	ds_read_b128 v[172:175], v148 offset:50176
	ds_read_b128 v[176:179], v149 offset:49152
	ds_read_b128 v[180:183], v149 offset:50176
	ds_read_b128 v[188:191], v150 offset:49152
	ds_read_b128 v[192:195], v150 offset:50176
	ds_read_b128 v[196:199], v151 offset:49152
	ds_read_b128 v[200:203], v151 offset:50176
	s_barrier
	s_waitcnt lgkmcnt(0)
	s_setprio 1
	v_mfma_f32_16x16x32_bf16 v[20:23], v[168:171], v[8:11], v[60:63]
	v_mfma_f32_16x16x32_bf16 v[56:59], v[168:171], v[16:19], v[56:59]
	v_mfma_f32_16x16x32_bf16 v[60:63], v[176:179], v[8:11], v[52:55]
	v_mfma_f32_16x16x32_bf16 v[204:207], v[176:179], v[16:19], v[48:51]
	v_mfma_f32_16x16x32_bf16 v[44:47], v[188:191], v[8:11], v[44:47]
	v_mfma_f32_16x16x32_bf16 v[40:43], v[188:191], v[16:19], v[40:43]
	v_mfma_f32_16x16x32_bf16 v[8:11], v[196:199], v[8:11], v[36:39]
	v_mfma_f32_16x16x32_bf16 v[208:211], v[196:199], v[16:19], v[32:35]
	v_mfma_f32_16x16x32_bf16 v[52:55], v[172:175], v[12:15], v[20:23]
	v_mfma_f32_16x16x32_bf16 v[48:51], v[172:175], v[184:187], v[56:59]
	v_mfma_f32_16x16x32_bf16 v[36:39], v[180:183], v[12:15], v[60:63]
	v_mfma_f32_16x16x32_bf16 v[32:35], v[180:183], v[184:187], v[204:207]
	v_mfma_f32_16x16x32_bf16 v[20:23], v[192:195], v[12:15], v[44:47]
	v_mfma_f32_16x16x32_bf16 v[16:19], v[192:195], v[184:187], v[40:43]
	v_mfma_f32_16x16x32_bf16 v[8:11], v[200:203], v[12:15], v[8:11]
	v_mfma_f32_16x16x32_bf16 v[12:15], v[200:203], v[184:187], v[208:211]
	s_setprio 0
	s_setprio 1
	v_mfma_f32_16x16x32_bf16 v[28:31], v[168:171], v[216:219], v[28:31]
	v_mfma_f32_16x16x32_bf16 v[24:27], v[168:171], v[224:227], v[24:27]
	v_mfma_f32_16x16x32_bf16 v[40:43], v[176:179], v[216:219], v[132:135]
	v_mfma_f32_16x16x32_bf16 v[132:135], v[176:179], v[224:227], v[156:159]
	v_mfma_f32_16x16x32_bf16 v[156:159], v[188:191], v[216:219], v[160:163]
	v_mfma_f32_16x16x32_bf16 v[160:163], v[188:191], v[224:227], v[164:167]
	v_mfma_f32_16x16x32_bf16 v[4:7], v[196:199], v[216:219], v[4:7]
	v_mfma_f32_16x16x32_bf16 v[0:3], v[196:199], v[224:227], v[0:3]
	v_mfma_f32_16x16x32_bf16 v[60:63], v[172:175], v[220:223], v[28:31]
	v_mfma_f32_16x16x32_bf16 v[56:59], v[172:175], v[228:231], v[24:27]
	v_mfma_f32_16x16x32_bf16 v[44:47], v[180:183], v[220:223], v[40:43]
	v_mfma_f32_16x16x32_bf16 v[40:43], v[180:183], v[228:231], v[132:135]
	v_mfma_f32_16x16x32_bf16 v[28:31], v[192:195], v[220:223], v[156:159]
	v_mfma_f32_16x16x32_bf16 v[24:27], v[192:195], v[228:231], v[160:163]
	v_mfma_f32_16x16x32_bf16 v[4:7], v[200:203], v[220:223], v[4:7]
	v_mfma_f32_16x16x32_bf16 v[0:3], v[200:203], v[228:231], v[0:3]
	s_setprio 0
	s_barrier
	s_and_saveexec_b64 s[2:3], s[6:7]
	s_cbranch_execz .LBB0_571
	s_barrier
